# RWKV scan step rewritten by hand (row-pair packed state, 5-op DPP reduction for two rows, 40 issue slots per step instead of 55) and the scan CUs take one gate-GEMM tile round after their item (X=10)
# speedup vs baseline: 1.0157x; 1.0057x over previous
; __device__ __forceinline__ unsigned char* arg_ws() { const char AS4* ka = (const char AS4*)__builtin_amdgcn_kernarg_segment_ptr(); asm volatile("" : "+s"(ka)); return *(unsigned char* const AS4*)(ka + 200); }
; #define WSP(off) ((bf16_t*)(arg_ws() + (off)))
;     __device__ bool next(int i, Unit& u) const {
;         const long L = (long)i * G + c; if (L >= nwg) return false;
;         int wgid = (int)L; { const int q = nwg / NXCD, r = nwg % NXCD, xcd = wgid % NXCD, off = wgid / NXCD; wgid = (xcd < r ? xcd * (q + 1) : r * (q + 1) + (xcd - r) * q) + off; }
;         const int nig = WGM * nN, gid = wgid / nig, fm = gid * WGM, gsz = (nM - fm) < WGM ? (nM - fm) : WGM;
;         u.pm = fm + ((wgid % nig) % gsz); u.pn = (wgid % nig) / gsz; return true;
; __global__ void __launch_bounds__(512, 2) mega_fwd(Params p) {
;     ...
;             const int ra = G >> 1, na = G - ra;
;     ...
;             if (bid < ra) for (int it = bid; it < 128; it += ra) rwkv::rwkv_item(lds, l, WSP(WS_BIG), WSP(WS_LO), WSP(WS_YR), (float*)WSP(WS_BON), it >> 5, (it >> 1) & 15, it & 1);
;     ...
;             if (bid >= ra) {
;     ...
;                 for (int it = bid - ra; it < 512; it += na) {
;                     if (it < 256) { const int qb = 15 - (it >> 4), bh = it & 15; att::attn_item<1>(lds, WSP(WS_BIG), WSP(WS_VT), (const float*)WSP(WS_C) + (size_t)bh * SEQ, __uint_as_float(((const unsigned*)arg_ws())[8192 + l * 16 + bh]), WSP(WS_YAB), bh >> 2, bh & 3, qb); }
;                     else { const int j = it - 256; const int qb = 15 - (j >> 4), bh = j & 15; att::attn_item<0>(lds, WSP(WS_BIG), WSP(WS_VT), nullptr, 0.f, WSP(WS_YAB), bh >> 2, bh & 3, qb); }
;                 }
;     ...
;                 { pg8::Gemm g{WSP(WS_U), WSP(WS_WIN) + (size_t)(C_GATE + GATE1) * DM, TT, GATE2, DM, DM, 0}; pg8::StaticOrder S; S.init(TT, GATE2, na, bid - ra);
;                   pg8::EpiStore<pg8::FProj> E{WSP(WS_BIG) + C_GATE + GATE1, NP, pg8::FProj{0}}; pg8::gemm_phase(lds, g, S, E); }
.LBB0_220:
	s_or_b64 exec, exec, s[4:5]
	s_cmpk_lt_i32 s84, 0x580
	s_cselect_b64 s[4:5], -1, 0
	s_ashr_i32 s11, s84, 31
	s_lshr_b32 s3, s11, 29
	v_writelane_b32 v253, s4, 4
	s_add_i32 s3, s84, s3
	s_ashr_i32 s16, s58, 31
	v_writelane_b32 v253, s5, 5
	s_ashr_i32 s5, s3, 3
	s_and_b32 s3, s3, -8
	s_sub_i32 s4, s84, s3
	s_cmpk_lt_i32 s84, 0x100
	s_cselect_b64 s[6:7], -1, 0
	v_writelane_b32 v253, s6, 6
	s_ashr_i32 s19, s58, 1
	s_add_i32 s3, s19, s84
	v_writelane_b32 v253, s7, 7
	s_lshl_b32 s6, s4, 5
	s_add_u32 s68, s60, 0x200
	s_addc_u32 s69, s61, 0
	s_add_u32 s70, s60, 0x1000
	s_addc_u32 s71, s61, 0
	s_add_u32 s72, s60, 0x1100
	s_addc_u32 s73, s61, 0
	s_add_u32 s74, s60, 0x1200
	s_addc_u32 s75, s61, 0
	s_add_u32 s76, s60, 0x1300
	s_addc_u32 s77, s61, 0
	s_cmp_eq_u32 s2, 15
	s_cselect_b64 s[8:9], -1, 0
	v_writelane_b32 v253, s8, 8
	s_cmp_eq_u32 s2, 14
	s_mul_i32 s10, s4, 33
	v_writelane_b32 v253, s9, 9
	s_cselect_b64 s[8:9], -1, 0
	v_writelane_b32 v253, s8, 10
	s_cmp_eq_u32 s2, 13
	s_movk_i32 s21, 0xb1
	v_writelane_b32 v253, s9, 11
	s_cselect_b64 s[8:9], -1, 0
	v_writelane_b32 v253, s8, 12
	s_cmp_eq_u32 s2, 12
	s_mul_i32 s59, s59, s58
	v_writelane_b32 v253, s9, 13
	s_cselect_b64 s[8:9], -1, 0
	v_writelane_b32 v253, s8, 14
	s_cmp_eq_u32 s2, 11
	s_mov_b32 s95, 0
	v_writelane_b32 v253, s9, 15
	s_cselect_b64 s[8:9], -1, 0
	v_writelane_b32 v253, s8, 16
	s_cmp_eq_u32 s2, 10
	v_mov_b32_e32 v211, 1
	v_writelane_b32 v253, s9, 17
	s_cselect_b64 s[8:9], -1, 0
	v_writelane_b32 v253, s8, 18
	s_cmp_eq_u32 s2, 9
	v_mov_b32_e32 v215, 0x260
	v_writelane_b32 v253, s9, 19
	s_cselect_b64 s[8:9], -1, 0
	v_writelane_b32 v253, s8, 20
	s_cmp_eq_u32 s2, 8
	v_mov_b32_e32 v250, 0x8000
	v_writelane_b32 v253, s9, 21
	s_cselect_b64 s[8:9], -1, 0
	v_writelane_b32 v253, s8, 22
	s_cmp_eq_u32 s2, 7
	v_mov_b32_e32 v214, 0x358637bd
	v_writelane_b32 v253, s9, 23
	s_cselect_b64 s[8:9], -1, 0
	v_writelane_b32 v253, s8, 24
	s_cmp_eq_u32 s2, 6
	v_mov_b64_e32 v[164:165], 0x580
	v_writelane_b32 v253, s9, 25
	s_cselect_b64 s[8:9], -1, 0
	v_writelane_b32 v253, s8, 26
	s_cmp_eq_u32 s2, 5
	v_mov_b64_e32 v[166:167], 0x57f
	v_writelane_b32 v253, s9, 27
	s_cselect_b64 s[8:9], -1, 0
	v_writelane_b32 v253, s8, 28
	s_cmp_eq_u32 s2, 4
	v_mov_b64_e32 v[168:169], 0x7f
	v_writelane_b32 v253, s9, 29
	s_cselect_b64 s[8:9], -1, 0
	v_writelane_b32 v253, s8, 30
	s_cmp_eq_u32 s2, 3
	v_mov_b32_e32 v217, 0x41b17218
	v_writelane_b32 v253, s9, 31
	s_cselect_b64 s[8:9], -1, 0
	v_writelane_b32 v253, s8, 32
	s_cmp_eq_u32 s2, 2
	v_mov_b64_e32 v[170:171], 0x300
	v_writelane_b32 v253, s9, 33
	s_cselect_b64 s[8:9], -1, 0
	v_writelane_b32 v253, s8, 34
	s_cmp_eq_u32 s2, 1
	v_mov_b64_e32 v[172:173], 0x2ff
	v_writelane_b32 v253, s9, 35
	s_cselect_b64 s[8:9], -1, 0
	v_writelane_b32 v253, s8, 36
	s_cmp_eq_u32 s2, 0
	v_mov_b32_e32 v218, 0xbf1b4598
	v_writelane_b32 v253, s9, 37
	s_cselect_b64 s[8:9], -1, 0
	s_lshl_b32 s2, s2, 8
	s_add_u32 s2, s60, s2
	v_writelane_b32 v253, s8, 38
	s_addc_u32 s7, s61, 0
	v_mov_b32_e32 v219, 0xff800000
	v_writelane_b32 v253, s9, 39
	s_add_u32 s8, s2, 0x1400
	s_addc_u32 s9, s7, 0
	v_writelane_b32 v253, s8, 40
	v_mov_b32_e32 v220, 0x170000
	v_mov_b32_e32 v221, 0x5c00
	v_writelane_b32 v253, s9, 41
	s_add_u32 s8, s2, 0x2400
	s_addc_u32 s9, s7, 0
	v_writelane_b32 v253, s8, 42
	v_mov_b32_e32 v174, -1.0
	v_mov_b32_e32 v176, 1.0
	v_writelane_b32 v253, s9, 43
	s_add_u32 s8, s60, 0x3400
	s_addc_u32 s9, s61, 0
	v_writelane_b32 v253, s8, 44
	v_mov_b32_e32 v251, 0x1800
	v_mov_b32_e32 v252, 2
	v_writelane_b32 v253, s9, 45
	s_add_u32 s8, s60, 0x3500
	s_addc_u32 s9, s61, 0
	v_writelane_b32 v253, s8, 46
	s_cmp_lt_i32 s84, 16
	v_mov_b64_e32 v[178:179], 0x200
	v_writelane_b32 v253, s9, 47
	s_cselect_b64 s[8:9], -1, 0
	v_writelane_b32 v253, s8, 48
	s_cmp_gt_u32 s62, 15
	v_mov_b64_e32 v[180:181], 0x1ff
	v_writelane_b32 v253, s9, 49
	s_cselect_b64 s[8:9], -1, 0
	s_lshl_b32 s2, s58, 1
	v_writelane_b32 v253, s8, 50
	s_and_b32 s2, s2, -4
	s_cmpk_lt_i32 s84, 0x300
	v_writelane_b32 v253, s9, 51
	v_writelane_b32 v253, s2, 52
	s_cselect_b64 s[8:9], -1, 0
	s_sub_i32 s7, s58, s19
	v_writelane_b32 v253, s8, 53
	s_cmp_ge_i32 s84, s19
	v_mov_b64_e32 v[182:183], 0x800
	v_writelane_b32 v253, s9, 54
	s_cselect_b64 s[8:9], -1, 0
	s_sub_i32 s20, s84, s19
	s_add_i32 s101, s84, 0x500
	s_cmp_lt_i32 s20, 0
	s_cselect_b32 s20, s101, s20
	v_writelane_b32 v253, s8, 55
	s_cmpk_lt_i32 s20, 0x200
	v_mov_b64_e32 v[184:185], 0x7ff
	v_writelane_b32 v253, s9, 56
	s_cselect_b64 s[8:9], -1, 0
	v_writelane_b32 v253, s8, 57
	s_cmpk_lt_i32 s20, 0x580
	s_movk_i32 s79, 0x2000
	v_writelane_b32 v253, s9, 58
	s_cselect_b64 s[8:9], -1, 0
	v_writelane_b32 v253, s8, 59
	s_ashr_i32 s2, s20, 31
	s_movk_i32 s88, 0x5c00
	v_writelane_b32 v253, s9, 60
	v_writelane_b32 v253, s2, 61
	s_lshr_b32 s2, s2, 29
	s_add_i32 s2, s20, s2
	s_ashr_i32 s8, s2, 3
	s_and_b32 s2, s2, -8
	s_sub_i32 s9, s20, s2
	s_ashr_i32 s2, s7, 31
	s_cmpk_lt_i32 s84, 0x80
	s_cselect_b64 s[12:13], -1, 0
	v_writelane_b32 v253, s7, 62
	v_writelane_b32 v254, s12, 0
	s_cmpk_lt_i32 s84, 0x200
	v_writelane_b32 v253, s2, 63
	v_writelane_b32 v254, s13, 1
	s_cselect_b64 s[12:13], -1, 0
	s_lshl_b32 s2, s4, 6
	v_writelane_b32 v254, s12, 2
	s_cmpk_lt_i32 s84, 0x800
	s_mov_b32 s89, 0xbfb8aa3b
	v_writelane_b32 v254, s13, 3
	s_cselect_b64 s[12:13], -1, 0
	s_lshl_b32 s7, s4, 8
	s_cmp_lt_i32 s4, 0
	s_cselect_b32 s6, s10, s6
	s_mul_i32 s10, s4, 0x41
	v_writelane_b32 v254, s12, 4
	s_cselect_b32 s10, s10, s2
	s_mul_i32 s2, s4, 0x101
	v_writelane_b32 v254, s13, 5
	s_cselect_b32 s12, s2, s7
	s_cselect_b32 s2, s21, 0xb0
	s_mul_i32 s2, s4, s2
	s_movk_i32 s7, 0x61
	s_cselect_b32 s7, s7, 0x60
	s_add_i32 s2, s2, s5
;     __device__ bool next(int i, Unit& u) const {
;         const long L = (long)i * G + c; if (L >= nwg) return false;
;         int wgid = (int)L; { const int q = nwg / NXCD, r = nwg % NXCD, xcd = wgid % NXCD, off = wgid / NXCD; wgid = (xcd < r ? xcd * (q + 1) : r * (q + 1) + (xcd - r) * q) + off; }
;         const int nig = WGM * nN, gid = wgid / nig, fm = gid * WGM, gsz = (nM - fm) < WGM ? (nM - fm) : WGM;
;         u.pm = fm + ((wgid % nig) % gsz); u.pn = (wgid % nig) / gsz; return true;
;     }
	s_mul_hi_i32 s13, s2, 0x2e8ba2e9
	s_lshr_b32 s14, s13, 31
	s_ashr_i32 s13, s13, 5
	s_add_i32 s13, s13, s14
	s_mul_i32 s14, s13, 0xb0
	s_sub_i32 s2, s2, s14
	s_bfe_u32 s14, s2, 0x3001c
	s_add_i32 s14, s2, s14
	s_and_b32 s15, s14, 0xfff8
	s_sub_i32 s15, s2, s15
	s_add_i32 s2, s6, s5
	s_ashr_i32 s6, s2, 31
	s_lshr_b32 s6, s6, 23
	s_mul_i32 s4, s4, s7
	s_add_i32 s6, s2, s6
	s_and_b32 s7, s6, 0xfffffe00
	s_add_i32 s4, s4, s5
	s_sub_i32 s2, s2, s7
	s_mul_hi_i32 s7, s4, 0x2aaaaaab
	s_lshr_b32 s17, s7, 31
	s_ashr_i32 s7, s7, 4
	s_add_i32 s7, s7, s17
	s_mul_i32 s17, s7, 0x60
	s_sub_i32 s4, s4, s17
	s_bfe_i32 s17, s4, 0x80000
	s_bfe_u32 s17, s17, 0x3000c
	s_add_i32 s17, s4, s17
	s_and_b32 s18, s17, 0xf8
	s_sub_i32 s4, s4, s18
	s_lshl_b32 s7, s7, 3
	s_sext_i32_i8 s4, s4
	s_add_i32 s4, s7, s4
	v_writelane_b32 v254, s4, 6
	s_lshl_b32 s4, s13, 3
	s_sext_i32_i16 s7, s15
	s_add_i32 s22, s4, s7
	s_ashr_i32 s4, s6, 9
	s_lshl_b32 s6, s4, 3
	s_sub_i32 s4, 4, s6
	s_min_u32 s7, s4, 8
	s_bfe_i32 s4, s17, 0x80000
	s_sext_i32_i16 s4, s4
	s_sext_i32_i16 s13, s14
	s_ashr_i32 s4, s4, 3
	v_writelane_b32 v254, s4, 7
	s_ashr_i32 s4, s13, 3
	v_writelane_b32 v254, s4, 8
	s_lshr_b32 s4, s13, 3
	s_cmp_lt_i32 s9, 0
	s_cselect_b32 s13, s21, 0xb0
	s_mul_i32 s9, s9, s13
	s_add_i32 s9, s9, s8
	s_mul_hi_i32 s8, s9, 0x2e8ba2e9
	s_lshr_b32 s13, s8, 31
	s_ashr_i32 s8, s8, 5
	s_add_i32 s8, s8, s13
	s_mul_i32 s13, s8, 0xb0
	s_sub_i32 s9, s9, s13
	s_bfe_u32 s13, s9, 0x3001c
	s_add_i32 s13, s9, s13
	s_and_b32 s14, s13, 0xfff8
	s_add_i32 s10, s10, s5
	s_sub_i32 s9, s9, s14
	s_ashr_i32 s14, s10, 31
	s_lshr_b32 s14, s14, 26
	s_add_i32 s14, s10, s14
	s_and_b32 s15, s14, 0xffc0
	s_sub_i32 s10, s10, s15
	s_bfe_i32 s15, s10, 0x80000
	s_add_i32 s5, s12, s5
	s_bfe_u32 s15, s15, 0x3000c
	s_ashr_i32 s12, s5, 31
	s_add_i32 s15, s10, s15
	s_lshr_b32 s12, s12, 24
	s_and_b32 s17, s15, 0xf8
	s_add_i32 s12, s5, s12
	s_sub_i32 s10, s10, s17
	s_and_b32 s17, s12, 0xff00
	s_sub_i32 s5, s5, s17
	s_sext_i32_i16 s17, s5
	s_bfe_u32 s17, s17, 0x3001c
	s_lshl_b32 s8, s8, 3
	s_sext_i32_i16 s9, s9
	s_add_i32 s17, s5, s17
	s_add_i32 s24, s8, s9
	s_ashr_i32 s8, s14, 6
	s_and_b32 s18, s17, 0xfff8
	s_lshl_b32 s8, s8, 3
	s_sext_i32_i8 s10, s10
	s_sub_i32 s5, s5, s18
	s_bfe_i32 s9, s15, 0x80000
	s_add_i32 s14, s8, s10
	s_ashr_i32 s10, s12, 8
	s_sext_i32_i16 s9, s9
	s_lshl_b32 s10, s10, 3
	s_sext_i32_i16 s12, s17
	s_sext_i32_i16 s5, s5
	s_ashr_i32 s8, s9, 3
	s_add_i32 s26, s10, s5
	s_lshr_b32 s10, s12, 3
	s_sext_i32_i16 s18, s13
	v_writelane_b32 v254, s8, 9
	s_ashr_i32 s5, s12, 3
	s_bfe_i64 s[12:13], s[10:11], 0x100000
	s_lshr_b32 s8, s9, 3
	v_writelane_b32 v254, s5, 10
	s_lshl_b64 s[12:13], s[12:13], 20
	s_bfe_i64 s[8:9], s[8:9], 0x100000
	v_writelane_b32 v254, s12, 11
	s_bfe_i64 s[4:5], s[4:5], 0x100000
	s_lshl_b64 s[4:5], s[4:5], 20
	v_writelane_b32 v254, s13, 12
	s_lshl_b64 s[12:13], s[8:9], 20
	v_writelane_b32 v254, s12, 13
	s_lshl_b64 s[8:9], s[8:9], 22
	s_ashr_i32 s15, s14, 31
	v_writelane_b32 v254, s13, 14
	v_writelane_b32 v254, s8, 15
	s_ashr_i32 s27, s26, 31
	v_cvt_f32_ubyte0_e32 v1, s7
	v_writelane_b32 v254, s9, 16
	v_writelane_b32 v254, s4, 17
	s_ashr_i32 s23, s22, 31
	v_cvt_f32_i32_e32 v0, s2
	v_writelane_b32 v254, s5, 18
	s_ashr_i32 s4, s18, 3
	v_writelane_b32 v254, s4, 19
	s_lshr_b32 s4, s18, 3
	s_bfe_i64 s[4:5], s[4:5], 0x100000
	s_lshl_b64 s[4:5], s[4:5], 20
	v_writelane_b32 v254, s4, 20
	v_rcp_iflag_f32_e32 v2, v1
	s_ashr_i32 s25, s24, 31
	v_writelane_b32 v254, s5, 21
	s_ashr_i32 s4, s2, 30
	s_or_b32 s8, s4, 1
	s_lshl_b64 s[4:5], s[14:15], 19
	v_writelane_b32 v254, s4, 22
	v_mul_f32_e32 v2, v0, v2
	v_trunc_f32_e32 v2, v2
	v_writelane_b32 v254, s5, 23
	s_lshl_b64 s[4:5], s[14:15], 20
	v_writelane_b32 v254, s4, 24
	v_fma_f32 v0, -v2, v1, v0
	s_mov_b32 s21, 0x3f317217
	v_writelane_b32 v254, s5, 25
	s_mov_b32 s4, s26
	v_writelane_b32 v254, s4, 26
	s_movk_i32 s78, 0x1800
	s_mov_b32 s53, 0x3db504f3
	v_writelane_b32 v254, s5, 27
	s_lshl_b64 s[4:5], s[26:27], 20
	v_writelane_b32 v254, s4, 28
	s_movk_i32 s17, 0x1000
	s_mov_b32 s10, 1.0
	v_writelane_b32 v254, s5, 29
	s_mov_b32 s4, s14
	v_writelane_b32 v254, s4, 30
	s_nop 1
	v_writelane_b32 v254, s5, 31
	s_lshl_b64 s[4:5], s[14:15], 22
	v_writelane_b32 v254, s4, 32
	s_mov_b32 s14, s95
	s_nop 0
	v_writelane_b32 v254, s5, 33
	s_mov_b32 s4, s22
	v_writelane_b32 v254, s4, 34
	s_nop 1
	v_writelane_b32 v254, s5, 35
	s_lshl_b64 s[4:5], s[22:23], 20
	v_writelane_b32 v254, s4, 36
	s_mov_b64 s[22:23], 0x189200
	s_nop 0
	v_writelane_b32 v254, s5, 37
	s_mov_b32 s4, s24
	v_writelane_b32 v254, s4, 38
	s_nop 1
	v_writelane_b32 v254, s5, 39
	s_lshl_b64 s[4:5], s[24:25], 20
	v_writelane_b32 v254, s4, 40
	s_nop 1
	v_writelane_b32 v254, s5, 41
	v_cmp_ge_f32_e64 s[4:5], |v0|, v1
	s_and_b64 s[4:5], s[4:5], exec
	s_load_dword s4, s[0:1], 0xd8
	v_cvt_i32_f32_e32 v0, v2
	v_mbcnt_lo_u32_b32 v1, -1, 0
	v_mbcnt_hi_u32_b32 v216, -1, v1
	s_barrier
; #define WSP(off) ((bf16_t*)(arg_ws() + (off)))
;     __device__ bool next(int i, Unit& u) const {
;         const long L = (long)i * G + c; if (L >= nwg) return false;
;         int wgid = (int)L; { const int q = nwg / NXCD, r = nwg % NXCD, xcd = wgid % NXCD, off = wgid / NXCD; wgid = (xcd < r ? xcd * (q + 1) : r * (q + 1) + (xcd - r) * q) + off; }
;         const int nig = WGM * nN, gid = wgid / nig, fm = gid * WGM, gsz = (nM - fm) < WGM ? (nM - fm) : WGM;
;         u.pm = fm + ((wgid % nig) % gsz); u.pn = (wgid % nig) / gsz; return true;
;     }
; __global__ void __launch_bounds__(512, 2) mega_fwd(Params p) {
;     ...
;         { pg8::Gemm g{WSP(WS_U), WSP(WS_WIN) + (size_t)C_GATE * DM, TT, GATE1, DM, DM, 0}; pg8::StaticOrder S; S.init(TT, GATE1, G, (bid + (G >> 1)) % G);
;           pg8::EpiStore<pg8::FProj> E{WSP(WS_BIG) + C_GATE, NP, pg8::FProj{0}}; pg8::gemm_phase(lds, g, S, E); }
	s_waitcnt lgkmcnt(0)
	s_mul_i32 s59, s59, s4
	s_cselect_b32 s4, s8, 0
	v_readfirstlane_b32 s5, v0
	s_add_i32 s4, s5, s4
	s_mul_i32 s5, s4, s7
	s_abs_i32 s7, s58
	v_cvt_f32_u32_e32 v0, s7
	s_sub_i32 s2, s2, s5
	s_sub_i32 s5, 0, s7
	s_sext_i32_i16 s2, s2
	v_rcp_iflag_f32_e32 v0, v0
	s_add_i32 s12, s6, s2
	s_sext_i32_i16 s2, s4
	v_writelane_b32 v254, s2, 42
	v_mul_f32_e32 v0, 0x4f7ffffe, v0
	v_cvt_u32_f32_e32 v0, v0
	s_ashr_i32 s13, s12, 31
	s_ashr_i32 s2, s3, 31
	v_readfirstlane_b32 s8, v0
	s_mul_i32 s5, s5, s8
	s_mul_hi_u32 s5, s8, s5
	s_add_i32 s8, s8, s5
	s_abs_i32 s5, s3
	s_mul_hi_u32 s8, s5, s8
	s_mul_i32 s8, s8, s7
	s_sub_i32 s8, s5, s8
	s_bfe_i64 s[4:5], s[4:5], 0x100000
	s_lshl_b64 s[4:5], s[4:5], 20
	v_writelane_b32 v254, s4, 43
	s_sub_i32 s3, s8, s7
	v_mov_b32_e32 v0, 0
	v_writelane_b32 v254, s5, 44
	s_mov_b32 s4, s12
	v_writelane_b32 v254, s4, 45
	s_nop 1
	v_writelane_b32 v254, s5, 46
	s_lshl_b64 s[4:5], s[12:13], 20
	s_cmp_ge_u32 s8, s7
	v_writelane_b32 v254, s4, 47
	s_cselect_b32 s3, s3, s8
	s_mov_b32 s8, 0x7f800000
	v_writelane_b32 v254, s5, 48
	s_sub_i32 s4, s3, s7
	s_cmp_ge_u32 s3, s7
	s_cselect_b32 s3, s4, s3
	s_xor_b32 s3, s3, s2
	s_sub_i32 s3, s3, s2
	s_cmpk_lt_i32 s3, 0x80
	s_cselect_b64 s[4:5], -1, 0
	v_writelane_b32 v254, s4, 49
	s_ashr_i32 s2, s3, 31
	s_mov_b64 s[6:7], 0x80
	v_writelane_b32 v254, s5, 50
	v_writelane_b32 v254, s2, 51
	s_lshr_b32 s2, s2, 29
	s_add_i32 s2, s3, s2
	s_ashr_i32 s4, s2, 3
	s_and_b32 s2, s2, -8
	s_sub_i32 s2, s3, s2
	v_writelane_b32 v254, s4, 52
	s_cmp_gt_i32 s2, -1
	v_writelane_b32 v254, s3, 53
	s_cselect_b64 s[4:5], -1, 0
	v_writelane_b32 v254, s4, 54
	s_lshl_b32 s3, s2, 4
	s_mul_i32 s2, s2, 17
	v_writelane_b32 v254, s5, 55
	v_writelane_b32 v254, s3, 56
	v_writelane_b32 v254, s2, 57
	s_add_i32 s2, s20, 0xffffff00
	v_writelane_b32 v254, s20, 58
	s_bitcmp1_b32 s84, 0
	v_writelane_b32 v254, s2, 59
	s_cselect_b64 s[2:3], -1, 0
	v_writelane_b32 v254, s2, 60
	s_bitcmp1_b32 s19, 0
	s_mov_b64 s[4:5], -1
	v_writelane_b32 v254, s3, 61
	v_writelane_b32 v254, s19, 62
	s_cselect_b64 s[2:3], -1, 0
	v_writelane_b32 v254, s2, 63
	s_ashr_i32 s63, s62, 31
	s_mov_b32 s20, 0x800000
	v_writelane_b32 v255, s3, 0
	v_readlane_b32 s2, v253, 2
	s_add_i32 s3, s2, s62
	v_writelane_b32 v255, s3, 1
	s_lshl_b32 s3, s84, 4
	v_writelane_b32 v255, s3, 2
	s_lshl_b32 s3, s58, 4
	v_writelane_b32 v255, s3, 3
	s_addk_i32 s2, 0xdf00
	v_writelane_b32 v255, s2, 4
	s_add_i32 s2, 0, 0x23fc0
	v_writelane_b32 v255, s2, 5
	s_add_i32 s2, 0, 0x23fc4
	v_writelane_b32 v255, s2, 6
	s_add_i32 s2, 0, 0x16400
	v_writelane_b32 v255, s2, 7
	s_add_i32 s2, 0, 0x15200
	v_writelane_b32 v255, s2, 8
	s_add_i32 s2, 0, 0x1a400
	v_writelane_b32 v255, s2, 9
	v_writelane_b32 v255, s4, 10
	s_mov_b32 s3, 0xc2200000
	s_lshl_b64 s[82:83], s[62:63], 12
	s_lshl_b64 s[64:65], s[62:63], 13
	v_writelane_b32 v255, s5, 11
	s_mov_b64 s[18:19], 0x40000
	s_branch .LBB0_224

; #define PG8_STAGE(bufoff, gbase, voff) do { _Pragma("unroll") for (int _i = 0; _i < 2; ++_i) \
;         __builtin_amdgcn_global_load_lds((const unsigned*)((const char*)(gbase) + (voff)[_i]), (LAS unsigned*)(lds + (bufoff) + ldsw + _i * 8192), 16, 0, 0); } while (0)
; #define PG8_WAIT_V(n) asm volatile("s_waitcnt vmcnt(" #n ")" ::: "memory")
; #define PG8_BAR __builtin_amdgcn_s_barrier()
; template <class Epi>
; __device__ __forceinline__ void gemm_phase(LAS unsigned char* lds, const Gemm g, const StaticOrder& S, const Epi& E) {
;     int tid_ = threadIdx.x; asm volatile("" : "+v"(tid_));
;     const int tid = tid_, wid = __builtin_amdgcn_readfirstlane(tid >> 6), lane = tid & 63, wr = wid >> 2, wc = wid & 3, fr = lane & 15, fq = lane >> 4;
;     const int K = g.K, nt = K / BK;
;     unsigned voffA[2], voffB[2];
; #pragma unroll
;     for (int i = 0; i < 2; ++i) { int R, C; stage_rc(tid * 16 + i * 8192, R, C); const int Rb = Epi::PERM ? ((R & ~31) + perm32(R & 31)) : R;
;         voffA[i] = (unsigned)(R * g.lda + C) * 2u; voffB[i] = (unsigned)(Rb * K + C) * 2u; }
;     const size_t kstep = (size_t)(BK * 2);
;     const size_t hstep = (size_t)HALF * K * 2;
;     const size_t tstep = 2 * hstep;
;     const size_t hstepA = (size_t)HALF * g.lda * 2, tstepA = 2 * hstepA;
;     const long aj = g.ajump;
;     ...
;     const unsigned ldsw = (unsigned)wid * 1024u;
;     const int aoff = lds_byte(wr * 64 + fr, fq * 8), boff = lds_byte(wc * 32 + fr, fq * 8);
;     ...
;     Unit cur, nxt; int ui = 0;
;     if (!S.next(0, cur)) return;
;     f32x4 acc[2][2][4][2];
; #pragma unroll
;     for (int a = 0; a < 2; ++a)
; #pragma unroll
;         for (int b = 0; b < 2; ++b)
; #pragma unroll
;             for (int m = 0; m < 4; ++m)
; #pragma unroll
;                 for (int n = 0; n < 2; ++n) acc[a][b][m][n] = (f32x4){0.f, 0.f, 0.f, 0.f};
;     bf16x8 At[4][2], B0[2][2], B1[2][2];
;     const char* cA = (const char*)g.A + (size_t)cur.pm * tstepA; const char* cB = (const char*)g.Bt + (size_t)cur.pn * tstep;
;     PG8_STAGE(PG8_SB(0, 0), cB, voffB); PG8_STAGE(PG8_SB(0, 1), cB + hstep, voffB); PG8_STAGE(PG8_SA(0, 0), cA, voffA); PG8_STAGE(PG8_SA(0, 1), cA + hstepA, voffA);
;     if (wr == 1) PG8_BAR;
;     PG8_WAIT_V(2); PG8_BAR;
;     PG8_STAGE(PG8_SB(1, 0), cB + kstep, voffB); PG8_STAGE(PG8_SA(1, 0), cA + kstep, voffA); PG8_STAGE(PG8_SB(1, 1), cB + hstep + kstep, voffB);
.Lp4_gate_entry:
	v_readlane_b32 s4, v253, 57
	v_readlane_b32 s5, v253, 58
	s_andn2_b64 vcc, exec, s[4:5]
	v_readlane_b32 s2, v254, 59
	v_readlane_b32 s28, v254, 58
	s_cbranch_vccz .LBB0_593
.LBB0_587:
	s_lshr_b32 s101, s58, 1
	s_movk_i32 s100, 0x580
	s_cmp_ge_u32 s84, s101
	s_cselect_b32 s100, 0x500, s100
	v_readlane_b32 s4, v253, 59
	s_mov_b64 s[36:37], s[0:1]
	s_mov_b64 s[34:35], s[0:1]
	s_mov_b64 s[30:31], s[0:1]
	v_mov_b32_e32 v1, v210
	v_readlane_b32 s5, v253, 60
	s_andn2_b64 vcc, exec, s[4:5]
	v_readfirstlane_b32 s38, v1
	s_cbranch_vccnz .LBB0_683
	v_lshlrev_b32_e32 v2, 4, v1
	v_add_u32_e32 v3, 0x2000, v2
	v_ashrrev_i32_e32 v4, 31, v3
	v_lshrrev_b32_e32 v4, 22, v4
	v_add_u32_e32 v4, v3, v4
	v_ashrrev_i32_e32 v10, 10, v4
	v_mul_i32_i24_e32 v4, 0x400, v10
	v_sub_u32_e32 v3, v3, v4
	v_lshrrev_b32_e32 v4, 4, v3
	v_bitop3_b32 v3, v4, v3, 32 bitop3:0x6c
	v_ashrrev_i32_e32 v4, 31, v3
	v_lshrrev_b32_e32 v4, 26, v4
	v_add_u32_e32 v4, v3, v4
	v_lshlrev_b32_e32 v5, 3, v10
	v_ashrrev_i32_e32 v11, 6, v4
	v_and_b32_e32 v5, -16, v5
	v_add_u32_e32 v5, v11, v5
	v_and_b32_e32 v6, 3, v11
	s_mov_b32 s12, 0xfffe0
	v_lshrrev_b32_e32 v7, 2, v5
	v_lshlrev_b32_e32 v8, 1, v5
	v_and_b32_e32 v4, 0xc0, v4
	v_and_or_b32 v6, v5, s12, v6
	v_and_b32_e32 v7, 4, v7
	v_and_b32_e32 v8, 24, v8
	v_sub_u32_e32 v3, v3, v4
	v_or3_b32 v6, v6, v7, v8
	v_lshlrev_b32_e32 v7, 5, v10
	v_ashrrev_i16_sdwa v3, v211, sext(v3) dst_sel:DWORD dst_unused:UNUSED_PAD src0_sel:DWORD src1_sel:BYTE_0
	v_and_b32_e32 v7, 32, v7
	v_bfe_i32 v12, v3, 0, 16
	v_add_lshl_u32 v3, v7, v12, 1
	v_lshl_add_u32 v130, v6, 12, v3
	v_lshl_add_u32 v132, v5, 12, v3
	v_bfe_i32 v3, v1, 27, 1
	v_lshrrev_b32_e32 v3, 22, v3
	v_add_u32_e32 v3, v2, v3
	v_and_b32_e32 v3, 0xfffffc00, v3
	v_sub_u32_e32 v2, v2, v3
	v_lshrrev_b32_e32 v3, 4, v2
	v_ashrrev_i32_e32 v4, 31, v1
	s_load_dwordx2 s[4:5], s[36:37], 0xc8
	s_load_dwordx2 s[24:25], s[34:35], 0xc8
	v_bitop3_b32 v2, v3, v2, 32 bitop3:0x6c
	v_lshrrev_b32_e32 v4, 26, v4
	v_ashrrev_i32_e32 v3, 31, v2
	v_add_u32_e32 v4, v1, v4
	v_lshrrev_b32_e32 v3, 26, v3
	v_ashrrev_i32_e32 v14, 6, v4
	v_add_u32_e32 v3, v2, v3
	v_lshlrev_b32_e32 v4, 3, v14
	s_waitcnt lgkmcnt(0)
	s_add_u32 s2, s4, 0x8700000
	v_ashrrev_i32_e32 v13, 6, v3
	v_and_b32_e32 v4, -16, v4
	s_addc_u32 s4, s5, 0
	v_add_u32_e32 v4, v13, v4
	s_add_u32 s5, s24, 0x1900000
	v_and_b32_e32 v5, 3, v13
	v_lshrrev_b32_e32 v6, 2, v4
	v_lshlrev_b32_e32 v7, 1, v4
	v_and_b32_e32 v3, 0xc0, v3
	s_addc_u32 s9, s25, 0
	s_ashr_i32 s29, s38, 6
	v_and_or_b32 v5, v4, s12, v5
	v_and_b32_e32 v6, 4, v6
	v_and_b32_e32 v7, 24, v7
	v_sub_u32_e32 v2, v2, v3
	s_mov_b32 s15, s33
	s_ashr_i32 s33, s38, 8
	s_lshl_b32 s24, s29, 10
	v_or3_b32 v5, v5, v6, v7
	v_lshlrev_b32_e32 v6, 5, v14
	v_ashrrev_i16_sdwa v2, v211, sext(v2) dst_sel:DWORD dst_unused:UNUSED_PAD src0_sel:DWORD src1_sel:BYTE_0
	v_readlane_b32 s12, v254, 20
	v_and_b32_e32 v6, 32, v6
	v_bfe_i32 v15, v2, 0, 16
	v_readlane_b32 s13, v254, 21
	s_add_u32 s54, s5, s12
	v_add_lshl_u32 v2, v6, v15, 1
	s_addc_u32 s55, s9, s13
	s_add_i32 s25, s24, 0
	v_lshl_add_u32 v134, v5, 12, v2
	s_add_i32 m0, s25, 0x10000
	v_readlane_b32 s12, v254, 40
	global_load_lds_dwordx4 v134, s[54:55]
	s_add_i32 m0, s25, 0x12000
	s_add_u32 s26, s54, 0x80000
	global_load_lds_dwordx4 v130, s[54:55]
	s_addc_u32 s27, s55, 0
	s_add_i32 m0, s25, 0x14000
	v_readlane_b32 s13, v254, 41
	global_load_lds_dwordx4 v134, s[26:27]
	s_add_i32 m0, s25, 0x16000
	s_add_u32 s40, s2, s12
	global_load_lds_dwordx4 v130, s[26:27]
	s_addc_u32 s41, s4, s13
	s_add_i32 s26, s25, 0x2000
	v_lshl_add_u32 v136, v4, 12, v2
	s_mov_b32 m0, s25
	s_add_u32 s34, s40, 0x80000
	global_load_lds_dwordx4 v136, s[40:41]
	s_mov_b32 m0, s26
	s_addc_u32 s35, s41, 0
	s_add_i32 s27, s25, 0x4000
	global_load_lds_dwordx4 v132, s[40:41]
	s_mov_b32 m0, s27
	s_add_i32 s28, s25, 0x6000
	global_load_lds_dwordx4 v136, s[34:35]
	s_mov_b32 m0, s28
	v_mov_b32_e32 v135, v0
	global_load_lds_dwordx4 v132, s[34:35]
	s_load_dwordx2 s[34:35], s[30:31], 0xc8
	v_mov_b32_e32 v131, v0
	v_mov_b32_e32 v137, v0
	v_mov_b32_e32 v133, v0
	s_cmp_eq_u32 s33, 1
	v_lshl_add_u64 v[8:9], s[54:55], 0, v[134:135]
	v_lshl_add_u64 v[6:7], s[54:55], 0, v[130:131]
	v_lshl_add_u64 v[2:3], s[40:41], 0, v[136:137]
	s_cselect_b64 s[30:31], -1, 0
	s_cmp_lg_u32 s33, 1
	v_lshl_add_u64 v[4:5], s[40:41], 0, v[132:133]
	s_cbranch_scc1 .LBB0_590
	s_barrier

;     __device__ bool next(int i, Unit& u) const {
;         const long L = (long)i * G + c; if (L >= nwg) return false;
;         int wgid = (int)L; { const int q = nwg / NXCD, r = nwg % NXCD, xcd = wgid % NXCD, off = wgid / NXCD; wgid = (xcd < r ? xcd * (q + 1) : r * (q + 1) + (xcd - r) * q) + off; }
;         const int nig = WGM * nN, gid = wgid / nig, fm = gid * WGM, gsz = (nM - fm) < WGM ? (nM - fm) : WGM;
;         u.pm = fm + ((wgid % nig) % gsz); u.pn = (wgid % nig) / gsz; return true;
;     }
; template <class Epi>
; __device__ __forceinline__ void gemm_phase(LAS unsigned char* lds, const Gemm g, const StaticOrder& S, const Epi& E) {
;     ...
;         const bool has_next = S.next(ui + 1, nxt);
;         const char* nA = has_next ? (const char*)g.A + (size_t)nxt.pm * tstepA : cA; const char* nB = has_next ? (const char*)g.Bt + (size_t)nxt.pn * tstep : cB;
.LBB0_641:
	s_add_i32 s52, s52, 1
	v_readlane_b32 s12, v253, 63
	v_readlane_b32 s14, v253, 62
	s_mul_i32 s12, s52, s12
	s_mul_hi_u32 s13, s52, s14
	s_add_i32 s13, s13, s12
	s_mul_i32 s12, s52, s14
	v_readlane_b32 s14, v254, 58
	s_add_u32 s48, s12, s14
	v_readlane_b32 s12, v253, 61
	s_addc_u32 s49, s13, s12
	s_cmp_lt_i32 s48, s100
	s_cselect_b64 s[38:39], exec, 0
	s_cselect_b64 vcc, 0, exec
	s_cbranch_vccnz .LBB0_643
	s_ashr_i32 s12, s48, 31
	s_lshr_b32 s12, s12, 29
	s_add_i32 s12, s48, s12
	s_ashr_i32 s13, s12, 3
	s_and_b32 s12, s12, -8
	s_sub_i32 s12, s48, s12
	s_cmp_lt_i32 s12, 0
	s_movk_i32 s14, 0xb1
	s_cselect_b32 s42, s14, 0xb0
	s_mul_i32 s12, s12, s42
	s_add_i32 s12, s12, s13
	s_mul_hi_i32 s13, s12, 0x2e8ba2e9
	s_lshr_b32 s42, s13, 31
	s_ashr_i32 s13, s13, 5
	s_add_i32 s13, s13, s42
	s_lshl_b32 s43, s13, 3
	s_sub_i32 s42, 64, s43
	s_min_i32 s44, s42, 8
	s_abs_i32 s42, s44
	v_cvt_f32_u32_e32 v2, s42
	s_sub_i32 s46, 0, s42
	s_mulk_i32 s13, 0xb0
	s_sub_i32 s12, s12, s13
	v_rcp_iflag_f32_e32 v2, v2
	s_abs_i32 s13, s12
	s_xor_b32 s45, s12, s44
	s_ashr_i32 s45, s45, 31
	v_mul_f32_e32 v2, 0x4f7ffffe, v2
	v_cvt_u32_f32_e32 v2, v2
	s_nop 0
	v_readfirstlane_b32 s47, v2
	s_mul_i32 s46, s46, s47
	s_mul_hi_u32 s46, s47, s46
	s_add_i32 s47, s47, s46
	s_mul_hi_u32 s46, s13, s47
	s_mul_i32 s47, s46, s42
	s_sub_i32 s13, s13, s47
	s_add_i32 s48, s46, 1
	s_sub_i32 s47, s13, s42
	s_cmp_ge_u32 s13, s42
	s_cselect_b32 s46, s48, s46
	s_cselect_b32 s13, s47, s13
	s_add_i32 s47, s46, 1
	s_cmp_ge_u32 s13, s42
	s_cselect_b32 s13, s47, s46
	s_xor_b32 s13, s13, s45
	s_sub_i32 s42, s13, s45
	s_mul_i32 s13, s42, s44
	s_sub_i32 s12, s12, s13
	s_add_i32 s46, s43, s12

; #define LAS __attribute__((address_space(3)))
; __device__ __forceinline__ void rwkv_item(LAS unsigned char* lds, int l, const bf16_t* PROJ, const bf16_t* LO, bf16_t* YR, float* BON, int b, int h, int qv) {
;     ...
;         const int rl = 8 * w + (lane >> 4), kq = lane & 15;
;         f32x2 S01[2], S23[2];
; #pragma unroll
;         for (int c = 0; c < 2; ++c) { S01[c] = (f32x2){0.f, 0.f}; S23[c] = (f32x2){0.f, 0.f}; }
;         __syncthreads();
;         for (int ci = 0; ci < NCH; ++ci) {
;             const LAS float* pk = base + (ci & 1) * BUFF + 4 * kq; const LAS float* pv = base + (ci & 1) * BUFF + 10240 + rl; const LAS float* ps = base + (ci & 1) * BUFF + 11264;
;             LAS float* py = yA + (ci & 1) * 4096 + rl * 4 + (kq >> 2);
;             f32x4 kk4 = *(const LAS f32x4*)(pk), wr4 = *(const LAS f32x4*)(pk + 2048), w4 = *(const LAS f32x4*)(pk + 4096), k4 = *(const LAS f32x4*)(pk + 6144), a4 = *(const LAS f32x4*)(pk + 8192);
;             float vv[2] = {pv[0], pv[4]}; f32x2 sc = *(const LAS f32x2*)(ps);
; #pragma unroll 32
;             for (int t = 0; t < CH; ++t) {
;                 const int tn = (t + 1) & (CH - 1);
;                 const LAS float* pn = pk + tn * 64;
;                 const f32x4 nkk = *(const LAS f32x4*)(pn), nwr = *(const LAS f32x4*)(pn + 2048), nw = *(const LAS f32x4*)(pn + 4096), nk = *(const LAS f32x4*)(pn + 6144), na = *(const LAS f32x4*)(pn + 8192);
;                 const float nv0 = pv[tn * 32], nv1 = pv[tn * 32 + 4]; const f32x2 nsc = *(const LAS f32x2*)(ps + 2 * tn);
;                 float sa[2], yp[2];
; #pragma unroll
;                 for (int c = 0; c < 2; ++c) { const f32x2 pa = S23[c] * kk4.hi + S01[c] * kk4.lo, pb = S23[c] * wr4.hi + S01[c] * wr4.lo; sa[c] = pa.x + pa.y; yp[c] = pb.x + pb.y; }
; #pragma unroll
;                 for (int c = 0; c < 2; ++c) { sa[c] = sum16(sa[c]); yp[c] += dppf<0xB1>(yp[c]); yp[c] += dppf<0x4E>(yp[c]); }
; #pragma unroll
;                 for (int c = 0; c < 2; ++c) {
;                     S01[c] = S01[c] * w4.lo + (k4.lo * vv[c] - a4.lo * sa[c]);
;                     S23[c] = S23[c] * w4.hi + (k4.hi * vv[c] - a4.hi * sa[c]);
;                     py[(t * 32 + 4 * c) * 4] = yp[c] + 0.25f * (vv[c] * sc.x - sa[c] * sc.y);
;                 }
;                 kk4 = nkk; wr4 = nwr; w4 = nw; k4 = nk; a4 = na; vv[0] = nv0; vv[1] = nv1; sc = nsc;
;             }
.LBB0_698:
	s_or_b64 exec, exec, s[30:31]
	global_load_dwordx2 v[4:5], v[4:5], off
	v_mov_b32_e32 v3, v0
	s_cmp_lt_i32 s4, 4
	s_mov_b64 s[30:31], -1
	s_waitcnt vmcnt(0)
	v_lshl_add_u64 v[2:3], v[2:3], 2, v[4:5]
	global_load_dword v2, v[2:3], off
	v_lshl_add_u32 v3, v1, 2, 0
	v_add_u32_e32 v3, 0x1e400, v3
	s_waitcnt vmcnt(0)
	ds_write_b32 v3, v2
	s_waitcnt lgkmcnt(0)
	s_barrier
	s_cbranch_scc0 .LBB0_702
	s_setprio 3
	v_and_b32_e32 v88, 15, v6
	v_lshlrev_b32_e32 v84, 4, v88
	v_lshrrev_b32_e32 v88, 4, v6
	v_lshl_or_b32 v88, s4, 3, v88
	v_and_b32_e32 v89, 3, v6
	v_lshrrev_b32_e32 v85, 1, v89
	v_xor_b32_e32 v89, v89, v85
	v_and_b32_e32 v89, 1, v89
	v_lshl_add_u32 v85, v89, 2, v88
	v_lshlrev_b32_e32 v89, 3, v89
	v_sub_u32_e32 v86, v85, v89
	v_add_u32_e32 v86, 4, v86
	v_readlane_b32 s31, v255, 7
	v_and_b32_e32 v89, 12, v6
	v_lshl_add_u32 v87, v85, 4, v89
	v_lshlrev_b32_e32 v85, 2, v85
	v_lshlrev_b32_e32 v86, 2, v86
	v_add_u32_e32 v87, s31, v87
	s_mov_b32 s30, 0
	v_mov_b32_e32 v2, 0
	v_mov_b32_e32 v3, 0
	v_mov_b32_e32 v4, 0
	v_mov_b32_e32 v5, 0
	v_mov_b32_e32 v6, 0
	v_mov_b32_e32 v7, 0
	v_mov_b32_e32 v8, 0
	v_mov_b32_e32 v9, 0
	s_barrier
.Lscan_chunk:
	s_and_b32 s24, s30, 1
	s_mul_i32 s4, s24, 0xb200
	s_lshl_b32 s31, s24, 14
	v_add_u32_e32 v10, s4, v84
	v_add_u32_e32 v11, s4, v85
	v_add_u32_e32 v12, s4, v86
	v_mov_b32_e32 v13, s4
	v_add_u32_e32 v14, s31, v87
	ds_read_b128 v[16:19], v10 offset:0
	ds_read_b128 v[20:23], v10 offset:8192
	ds_read_b128 v[24:27], v10 offset:16384
	ds_read_b128 v[28:31], v10 offset:24576
	ds_read_b128 v[32:35], v10 offset:32768
	ds_read_b32 v36, v11 offset:40960
	ds_read_b32 v37, v12 offset:40960
	ds_read_b64 v[38:39], v13 offset:45056
	s_waitcnt lgkmcnt(0)
	s_waitcnt lgkmcnt(1)
	v_pk_mul_f32 v[64:65], v[2:3], v[16:17] op_sel_hi:[1,0]
	v_pk_mul_f32 v[66:67], v[2:3], v[20:21] op_sel_hi:[1,0]
	v_pk_fma_f32 v[64:65], v[4:5], v[16:17], v[64:65] op_sel:[0,1,0] op_sel_hi:[1,1,1]
	v_pk_fma_f32 v[66:67], v[4:5], v[20:21], v[66:67] op_sel:[0,1,0] op_sel_hi:[1,1,1]
	v_pk_fma_f32 v[64:65], v[6:7], v[18:19], v[64:65] op_sel_hi:[1,0,1]
	v_pk_fma_f32 v[66:67], v[6:7], v[22:23], v[66:67] op_sel_hi:[1,0,1]
	v_pk_fma_f32 v[64:65], v[8:9], v[18:19], v[64:65] op_sel:[0,1,0] op_sel_hi:[1,1,1]
	v_pk_fma_f32 v[66:67], v[8:9], v[22:23], v[66:67] op_sel:[0,1,0] op_sel_hi:[1,1,1]
	ds_read_b128 v[40:43], v10 offset:256
	v_add_f32_dpp v78, v65, v64 quad_perm:[1,0,3,2] row_mask:0xf bank_mask:0xf bound_ctrl:1
	ds_read_b128 v[44:47], v10 offset:8448
	ds_read_b128 v[48:51], v10 offset:16640
	v_add_f32_dpp v79, v78, v78 quad_perm:[3,2,1,0] row_mask:0xf bank_mask:0xf bound_ctrl:1
	ds_read_b128 v[52:55], v10 offset:24832
	ds_read_b128 v[56:59], v10 offset:33024
	v_add_f32_dpp v80, v79, v79 row_half_mirror row_mask:0xf bank_mask:0xf bound_ctrl:1
	ds_read_b32 v60, v11 offset:41088
	ds_read_b32 v61, v12 offset:41088
	v_add_f32_dpp v76, v80, v80 row_mirror row_mask:0xf bank_mask:0xf bound_ctrl:1
	ds_read_b64 v[62:63], v13 offset:45064
	v_pk_mul_f32 v[68:69], v[36:37], v[28:29] op_sel_hi:[1,0]
	v_mov_b32_dpp v77, v76 quad_perm:[1,0,3,2] row_mask:0xf bank_mask:0xf bound_ctrl:1
	v_pk_mul_f32 v[70:71], v[36:37], v[28:29] op_sel:[0,1] op_sel_hi:[1,1]
	v_pk_mul_f32 v[72:73], v[36:37], v[30:31] op_sel_hi:[1,0]
	v_pk_mul_f32 v[74:75], v[36:37], v[30:31] op_sel:[0,1] op_sel_hi:[1,1]
	v_pk_fma_f32 v[68:69], v[2:3], v[24:25], v[68:69] op_sel_hi:[1,0,1]
	v_pk_fma_f32 v[70:71], v[4:5], v[24:25], v[70:71] op_sel:[0,1,0] op_sel_hi:[1,1,1]
	v_pk_fma_f32 v[72:73], v[6:7], v[26:27], v[72:73] op_sel_hi:[1,0,1]
	v_pk_fma_f32 v[74:75], v[8:9], v[26:27], v[74:75] op_sel:[0,1,0] op_sel_hi:[1,1,1]
	v_pk_fma_f32 v[2:3], v[32:33], v[76:77], v[68:69] op_sel_hi:[0,1,1] neg_lo:[1,0,0] neg_hi:[1,0,0]
	v_pk_fma_f32 v[4:5], v[32:33], v[76:77], v[70:71] op_sel:[1,0,0] op_sel_hi:[1,1,1] neg_lo:[1,0,0] neg_hi:[1,0,0]
	v_mul_f32_e32 v83, v36, v38
	v_add_f32_dpp v81, v67, v66 quad_perm:[1,0,3,2] row_mask:0xf bank_mask:0xf bound_ctrl:1
	v_pk_fma_f32 v[6:7], v[34:35], v[76:77], v[72:73] op_sel_hi:[0,1,1] neg_lo:[1,0,0] neg_hi:[1,0,0]
	v_pk_fma_f32 v[8:9], v[34:35], v[76:77], v[74:75] op_sel:[1,0,0] op_sel_hi:[1,1,1] neg_lo:[1,0,0] neg_hi:[1,0,0]
	v_add_f32_dpp v82, v81, v81 quad_perm:[3,2,1,0] row_mask:0xf bank_mask:0xf bound_ctrl:1
	v_fma_f32 v83, -v76, v39, v83
	v_fmac_f32_e32 v82, 0x3e800000, v83
	ds_write_b32 v14, v82 offset:0
	s_waitcnt lgkmcnt(1)
; #define LAS __attribute__((address_space(3)))
; template <int CTRL> __device__ __forceinline__ float dppf(float x) { return __builtin_bit_cast(float, __builtin_amdgcn_mov_dpp(__builtin_bit_cast(int, x), CTRL, 0xf, 0xf, true)); }
; __device__ __forceinline__ float sum16(float x) { x = sum8(x); x += dppf<0x140>(x); return x; }
; __device__ __forceinline__ void rwkv_item(LAS unsigned char* lds, int l, const bf16_t* PROJ, const bf16_t* LO, bf16_t* YR, float* BON, int b, int h, int qv) {
;     ...
;             for (int t = 0; t < CH; ++t) {
;                 const int tn = (t + 1) & (CH - 1);
;                 const LAS float* pn = pk + tn * 64;
;                 const f32x4 nkk = *(const LAS f32x4*)(pn), nwr = *(const LAS f32x4*)(pn + 2048), nw = *(const LAS f32x4*)(pn + 4096), nk = *(const LAS f32x4*)(pn + 6144), na = *(const LAS f32x4*)(pn + 8192);
;                 const float nv0 = pv[tn * 32], nv1 = pv[tn * 32 + 4]; const f32x2 nsc = *(const LAS f32x2*)(ps + 2 * tn);
;                 float sa[2], yp[2];
; #pragma unroll
;                 for (int c = 0; c < 2; ++c) { const f32x2 pa = S23[c] * kk4.hi + S01[c] * kk4.lo, pb = S23[c] * wr4.hi + S01[c] * wr4.lo; sa[c] = pa.x + pa.y; yp[c] = pb.x + pb.y; }
; #pragma unroll
;                 for (int c = 0; c < 2; ++c) { sa[c] = sum16(sa[c]); yp[c] += dppf<0xB1>(yp[c]); yp[c] += dppf<0x4E>(yp[c]); }
; #pragma unroll
;                 for (int c = 0; c < 2; ++c) {
;                     S01[c] = S01[c] * w4.lo + (k4.lo * vv[c] - a4.lo * sa[c]);
;                     S23[c] = S23[c] * w4.hi + (k4.hi * vv[c] - a4.hi * sa[c]);
;                     py[(t * 32 + 4 * c) * 4] = yp[c] + 0.25f * (vv[c] * sc.x - sa[c] * sc.y);
;                 }
;                 kk4 = nkk; wr4 = nwr; w4 = nw; k4 = nk; a4 = na; vv[0] = nv0; vv[1] = nv1; sc = nsc;
;             }
	v_pk_mul_f32 v[64:65], v[2:3], v[40:41] op_sel_hi:[1,0]
	v_pk_mul_f32 v[66:67], v[2:3], v[44:45] op_sel_hi:[1,0]
	v_pk_fma_f32 v[64:65], v[4:5], v[40:41], v[64:65] op_sel:[0,1,0] op_sel_hi:[1,1,1]
	v_pk_fma_f32 v[66:67], v[4:5], v[44:45], v[66:67] op_sel:[0,1,0] op_sel_hi:[1,1,1]
	v_pk_fma_f32 v[64:65], v[6:7], v[42:43], v[64:65] op_sel_hi:[1,0,1]
	v_pk_fma_f32 v[66:67], v[6:7], v[46:47], v[66:67] op_sel_hi:[1,0,1]
	v_pk_fma_f32 v[64:65], v[8:9], v[42:43], v[64:65] op_sel:[0,1,0] op_sel_hi:[1,1,1]
	v_pk_fma_f32 v[66:67], v[8:9], v[46:47], v[66:67] op_sel:[0,1,0] op_sel_hi:[1,1,1]
	ds_read_b128 v[16:19], v10 offset:512
	v_add_f32_dpp v78, v65, v64 quad_perm:[1,0,3,2] row_mask:0xf bank_mask:0xf bound_ctrl:1
	ds_read_b128 v[20:23], v10 offset:8704
	ds_read_b128 v[24:27], v10 offset:16896
	v_add_f32_dpp v79, v78, v78 quad_perm:[3,2,1,0] row_mask:0xf bank_mask:0xf bound_ctrl:1
	ds_read_b128 v[28:31], v10 offset:25088
	ds_read_b128 v[32:35], v10 offset:33280
	v_add_f32_dpp v80, v79, v79 row_half_mirror row_mask:0xf bank_mask:0xf bound_ctrl:1
	ds_read_b32 v36, v11 offset:41216
	ds_read_b32 v37, v12 offset:41216
	v_add_f32_dpp v76, v80, v80 row_mirror row_mask:0xf bank_mask:0xf bound_ctrl:1
	ds_read_b64 v[38:39], v13 offset:45072
	v_pk_mul_f32 v[68:69], v[60:61], v[52:53] op_sel_hi:[1,0]
	v_mov_b32_dpp v77, v76 quad_perm:[1,0,3,2] row_mask:0xf bank_mask:0xf bound_ctrl:1
	v_pk_mul_f32 v[70:71], v[60:61], v[52:53] op_sel:[0,1] op_sel_hi:[1,1]
	v_pk_mul_f32 v[72:73], v[60:61], v[54:55] op_sel_hi:[1,0]
	v_pk_mul_f32 v[74:75], v[60:61], v[54:55] op_sel:[0,1] op_sel_hi:[1,1]
	v_pk_fma_f32 v[68:69], v[2:3], v[48:49], v[68:69] op_sel_hi:[1,0,1]
	v_pk_fma_f32 v[70:71], v[4:5], v[48:49], v[70:71] op_sel:[0,1,0] op_sel_hi:[1,1,1]
	v_pk_fma_f32 v[72:73], v[6:7], v[50:51], v[72:73] op_sel_hi:[1,0,1]
	v_pk_fma_f32 v[74:75], v[8:9], v[50:51], v[74:75] op_sel:[0,1,0] op_sel_hi:[1,1,1]
	v_pk_fma_f32 v[2:3], v[56:57], v[76:77], v[68:69] op_sel_hi:[0,1,1] neg_lo:[1,0,0] neg_hi:[1,0,0]
	v_pk_fma_f32 v[4:5], v[56:57], v[76:77], v[70:71] op_sel:[1,0,0] op_sel_hi:[1,1,1] neg_lo:[1,0,0] neg_hi:[1,0,0]
	v_mul_f32_e32 v83, v60, v62
	v_add_f32_dpp v81, v67, v66 quad_perm:[1,0,3,2] row_mask:0xf bank_mask:0xf bound_ctrl:1
	v_pk_fma_f32 v[6:7], v[58:59], v[76:77], v[72:73] op_sel_hi:[0,1,1] neg_lo:[1,0,0] neg_hi:[1,0,0]
	v_pk_fma_f32 v[8:9], v[58:59], v[76:77], v[74:75] op_sel:[1,0,0] op_sel_hi:[1,1,1] neg_lo:[1,0,0] neg_hi:[1,0,0]
	v_add_f32_dpp v82, v81, v81 quad_perm:[3,2,1,0] row_mask:0xf bank_mask:0xf bound_ctrl:1
	v_fma_f32 v83, -v76, v63, v83
	v_fmac_f32_e32 v82, 0x3e800000, v83
	ds_write_b32 v14, v82 offset:512
	s_waitcnt lgkmcnt(1)
	v_pk_mul_f32 v[64:65], v[2:3], v[16:17] op_sel_hi:[1,0]
	v_pk_mul_f32 v[66:67], v[2:3], v[20:21] op_sel_hi:[1,0]
	v_pk_fma_f32 v[64:65], v[4:5], v[16:17], v[64:65] op_sel:[0,1,0] op_sel_hi:[1,1,1]
	v_pk_fma_f32 v[66:67], v[4:5], v[20:21], v[66:67] op_sel:[0,1,0] op_sel_hi:[1,1,1]
	v_pk_fma_f32 v[64:65], v[6:7], v[18:19], v[64:65] op_sel_hi:[1,0,1]
	v_pk_fma_f32 v[66:67], v[6:7], v[22:23], v[66:67] op_sel_hi:[1,0,1]
	v_pk_fma_f32 v[64:65], v[8:9], v[18:19], v[64:65] op_sel:[0,1,0] op_sel_hi:[1,1,1]
	v_pk_fma_f32 v[66:67], v[8:9], v[22:23], v[66:67] op_sel:[0,1,0] op_sel_hi:[1,1,1]
	ds_read_b128 v[40:43], v10 offset:768
	v_add_f32_dpp v78, v65, v64 quad_perm:[1,0,3,2] row_mask:0xf bank_mask:0xf bound_ctrl:1
	ds_read_b128 v[44:47], v10 offset:8960
	ds_read_b128 v[48:51], v10 offset:17152
	v_add_f32_dpp v79, v78, v78 quad_perm:[3,2,1,0] row_mask:0xf bank_mask:0xf bound_ctrl:1
	ds_read_b128 v[52:55], v10 offset:25344
	ds_read_b128 v[56:59], v10 offset:33536
	v_add_f32_dpp v80, v79, v79 row_half_mirror row_mask:0xf bank_mask:0xf bound_ctrl:1
	ds_read_b32 v60, v11 offset:41344
	ds_read_b32 v61, v12 offset:41344
	v_add_f32_dpp v76, v80, v80 row_mirror row_mask:0xf bank_mask:0xf bound_ctrl:1
	ds_read_b64 v[62:63], v13 offset:45080
	v_pk_mul_f32 v[68:69], v[36:37], v[28:29] op_sel_hi:[1,0]
	v_mov_b32_dpp v77, v76 quad_perm:[1,0,3,2] row_mask:0xf bank_mask:0xf bound_ctrl:1
	v_pk_mul_f32 v[70:71], v[36:37], v[28:29] op_sel:[0,1] op_sel_hi:[1,1]
	v_pk_mul_f32 v[72:73], v[36:37], v[30:31] op_sel_hi:[1,0]
	v_pk_mul_f32 v[74:75], v[36:37], v[30:31] op_sel:[0,1] op_sel_hi:[1,1]
	v_pk_fma_f32 v[68:69], v[2:3], v[24:25], v[68:69] op_sel_hi:[1,0,1]
	v_pk_fma_f32 v[70:71], v[4:5], v[24:25], v[70:71] op_sel:[0,1,0] op_sel_hi:[1,1,1]
	v_pk_fma_f32 v[72:73], v[6:7], v[26:27], v[72:73] op_sel_hi:[1,0,1]
	v_pk_fma_f32 v[74:75], v[8:9], v[26:27], v[74:75] op_sel:[0,1,0] op_sel_hi:[1,1,1]
	v_pk_fma_f32 v[2:3], v[32:33], v[76:77], v[68:69] op_sel_hi:[0,1,1] neg_lo:[1,0,0] neg_hi:[1,0,0]
	v_pk_fma_f32 v[4:5], v[32:33], v[76:77], v[70:71] op_sel:[1,0,0] op_sel_hi:[1,1,1] neg_lo:[1,0,0] neg_hi:[1,0,0]
	v_mul_f32_e32 v83, v36, v38
	v_add_f32_dpp v81, v67, v66 quad_perm:[1,0,3,2] row_mask:0xf bank_mask:0xf bound_ctrl:1
	v_pk_fma_f32 v[6:7], v[34:35], v[76:77], v[72:73] op_sel_hi:[0,1,1] neg_lo:[1,0,0] neg_hi:[1,0,0]
	v_pk_fma_f32 v[8:9], v[34:35], v[76:77], v[74:75] op_sel:[1,0,0] op_sel_hi:[1,1,1] neg_lo:[1,0,0] neg_hi:[1,0,0]
	v_add_f32_dpp v82, v81, v81 quad_perm:[3,2,1,0] row_mask:0xf bank_mask:0xf bound_ctrl:1
	v_fma_f32 v83, -v76, v39, v83
	v_fmac_f32_e32 v82, 0x3e800000, v83
	ds_write_b32 v14, v82 offset:1024
	s_waitcnt lgkmcnt(1)
; #define LAS __attribute__((address_space(3)))
; template <int CTRL> __device__ __forceinline__ float dppf(float x) { return __builtin_bit_cast(float, __builtin_amdgcn_mov_dpp(__builtin_bit_cast(int, x), CTRL, 0xf, 0xf, true)); }
; __device__ __forceinline__ float sum16(float x) { x = sum8(x); x += dppf<0x140>(x); return x; }
; __device__ __forceinline__ void rwkv_item(LAS unsigned char* lds, int l, const bf16_t* PROJ, const bf16_t* LO, bf16_t* YR, float* BON, int b, int h, int qv) {
;     ...
;             for (int t = 0; t < CH; ++t) {
;                 const int tn = (t + 1) & (CH - 1);
;                 const LAS float* pn = pk + tn * 64;
;                 const f32x4 nkk = *(const LAS f32x4*)(pn), nwr = *(const LAS f32x4*)(pn + 2048), nw = *(const LAS f32x4*)(pn + 4096), nk = *(const LAS f32x4*)(pn + 6144), na = *(const LAS f32x4*)(pn + 8192);
;                 const float nv0 = pv[tn * 32], nv1 = pv[tn * 32 + 4]; const f32x2 nsc = *(const LAS f32x2*)(ps + 2 * tn);
;                 float sa[2], yp[2];
; #pragma unroll
;                 for (int c = 0; c < 2; ++c) { const f32x2 pa = S23[c] * kk4.hi + S01[c] * kk4.lo, pb = S23[c] * wr4.hi + S01[c] * wr4.lo; sa[c] = pa.x + pa.y; yp[c] = pb.x + pb.y; }
; #pragma unroll
;                 for (int c = 0; c < 2; ++c) { sa[c] = sum16(sa[c]); yp[c] += dppf<0xB1>(yp[c]); yp[c] += dppf<0x4E>(yp[c]); }
; #pragma unroll
;                 for (int c = 0; c < 2; ++c) {
;                     S01[c] = S01[c] * w4.lo + (k4.lo * vv[c] - a4.lo * sa[c]);
;                     S23[c] = S23[c] * w4.hi + (k4.hi * vv[c] - a4.hi * sa[c]);
;                     py[(t * 32 + 4 * c) * 4] = yp[c] + 0.25f * (vv[c] * sc.x - sa[c] * sc.y);
;                 }
;                 kk4 = nkk; wr4 = nwr; w4 = nw; k4 = nk; a4 = na; vv[0] = nv0; vv[1] = nv1; sc = nsc;
;             }
	v_pk_mul_f32 v[64:65], v[2:3], v[40:41] op_sel_hi:[1,0]
	v_pk_mul_f32 v[66:67], v[2:3], v[44:45] op_sel_hi:[1,0]
	v_pk_fma_f32 v[64:65], v[4:5], v[40:41], v[64:65] op_sel:[0,1,0] op_sel_hi:[1,1,1]
	v_pk_fma_f32 v[66:67], v[4:5], v[44:45], v[66:67] op_sel:[0,1,0] op_sel_hi:[1,1,1]
	v_pk_fma_f32 v[64:65], v[6:7], v[42:43], v[64:65] op_sel_hi:[1,0,1]
	v_pk_fma_f32 v[66:67], v[6:7], v[46:47], v[66:67] op_sel_hi:[1,0,1]
	v_pk_fma_f32 v[64:65], v[8:9], v[42:43], v[64:65] op_sel:[0,1,0] op_sel_hi:[1,1,1]
	v_pk_fma_f32 v[66:67], v[8:9], v[46:47], v[66:67] op_sel:[0,1,0] op_sel_hi:[1,1,1]
	ds_read_b128 v[16:19], v10 offset:1024
	v_add_f32_dpp v78, v65, v64 quad_perm:[1,0,3,2] row_mask:0xf bank_mask:0xf bound_ctrl:1
	ds_read_b128 v[20:23], v10 offset:9216
	ds_read_b128 v[24:27], v10 offset:17408
	v_add_f32_dpp v79, v78, v78 quad_perm:[3,2,1,0] row_mask:0xf bank_mask:0xf bound_ctrl:1
	ds_read_b128 v[28:31], v10 offset:25600
	ds_read_b128 v[32:35], v10 offset:33792
	v_add_f32_dpp v80, v79, v79 row_half_mirror row_mask:0xf bank_mask:0xf bound_ctrl:1
	ds_read_b32 v36, v11 offset:41472
	ds_read_b32 v37, v12 offset:41472
	v_add_f32_dpp v76, v80, v80 row_mirror row_mask:0xf bank_mask:0xf bound_ctrl:1
	ds_read_b64 v[38:39], v13 offset:45088
	v_pk_mul_f32 v[68:69], v[60:61], v[52:53] op_sel_hi:[1,0]
	v_mov_b32_dpp v77, v76 quad_perm:[1,0,3,2] row_mask:0xf bank_mask:0xf bound_ctrl:1
	v_pk_mul_f32 v[70:71], v[60:61], v[52:53] op_sel:[0,1] op_sel_hi:[1,1]
	v_pk_mul_f32 v[72:73], v[60:61], v[54:55] op_sel_hi:[1,0]
	v_pk_mul_f32 v[74:75], v[60:61], v[54:55] op_sel:[0,1] op_sel_hi:[1,1]
	v_pk_fma_f32 v[68:69], v[2:3], v[48:49], v[68:69] op_sel_hi:[1,0,1]
	v_pk_fma_f32 v[70:71], v[4:5], v[48:49], v[70:71] op_sel:[0,1,0] op_sel_hi:[1,1,1]
	v_pk_fma_f32 v[72:73], v[6:7], v[50:51], v[72:73] op_sel_hi:[1,0,1]
	v_pk_fma_f32 v[74:75], v[8:9], v[50:51], v[74:75] op_sel:[0,1,0] op_sel_hi:[1,1,1]
	v_pk_fma_f32 v[2:3], v[56:57], v[76:77], v[68:69] op_sel_hi:[0,1,1] neg_lo:[1,0,0] neg_hi:[1,0,0]
	v_pk_fma_f32 v[4:5], v[56:57], v[76:77], v[70:71] op_sel:[1,0,0] op_sel_hi:[1,1,1] neg_lo:[1,0,0] neg_hi:[1,0,0]
	v_mul_f32_e32 v83, v60, v62
	v_add_f32_dpp v81, v67, v66 quad_perm:[1,0,3,2] row_mask:0xf bank_mask:0xf bound_ctrl:1
	v_pk_fma_f32 v[6:7], v[58:59], v[76:77], v[72:73] op_sel_hi:[0,1,1] neg_lo:[1,0,0] neg_hi:[1,0,0]
	v_pk_fma_f32 v[8:9], v[58:59], v[76:77], v[74:75] op_sel:[1,0,0] op_sel_hi:[1,1,1] neg_lo:[1,0,0] neg_hi:[1,0,0]
	v_add_f32_dpp v82, v81, v81 quad_perm:[3,2,1,0] row_mask:0xf bank_mask:0xf bound_ctrl:1
	v_fma_f32 v83, -v76, v63, v83
	v_fmac_f32_e32 v82, 0x3e800000, v83
	ds_write_b32 v14, v82 offset:1536
	s_waitcnt lgkmcnt(1)
	v_pk_mul_f32 v[64:65], v[2:3], v[16:17] op_sel_hi:[1,0]
	v_pk_mul_f32 v[66:67], v[2:3], v[20:21] op_sel_hi:[1,0]
	v_pk_fma_f32 v[64:65], v[4:5], v[16:17], v[64:65] op_sel:[0,1,0] op_sel_hi:[1,1,1]
	v_pk_fma_f32 v[66:67], v[4:5], v[20:21], v[66:67] op_sel:[0,1,0] op_sel_hi:[1,1,1]
	v_pk_fma_f32 v[64:65], v[6:7], v[18:19], v[64:65] op_sel_hi:[1,0,1]
	v_pk_fma_f32 v[66:67], v[6:7], v[22:23], v[66:67] op_sel_hi:[1,0,1]
	v_pk_fma_f32 v[64:65], v[8:9], v[18:19], v[64:65] op_sel:[0,1,0] op_sel_hi:[1,1,1]
	v_pk_fma_f32 v[66:67], v[8:9], v[22:23], v[66:67] op_sel:[0,1,0] op_sel_hi:[1,1,1]
	ds_read_b128 v[40:43], v10 offset:1280
	v_add_f32_dpp v78, v65, v64 quad_perm:[1,0,3,2] row_mask:0xf bank_mask:0xf bound_ctrl:1
	ds_read_b128 v[44:47], v10 offset:9472
	ds_read_b128 v[48:51], v10 offset:17664
	v_add_f32_dpp v79, v78, v78 quad_perm:[3,2,1,0] row_mask:0xf bank_mask:0xf bound_ctrl:1
	ds_read_b128 v[52:55], v10 offset:25856
	ds_read_b128 v[56:59], v10 offset:34048
	v_add_f32_dpp v80, v79, v79 row_half_mirror row_mask:0xf bank_mask:0xf bound_ctrl:1
	ds_read_b32 v60, v11 offset:41600
	ds_read_b32 v61, v12 offset:41600
	v_add_f32_dpp v76, v80, v80 row_mirror row_mask:0xf bank_mask:0xf bound_ctrl:1
	ds_read_b64 v[62:63], v13 offset:45096
	v_pk_mul_f32 v[68:69], v[36:37], v[28:29] op_sel_hi:[1,0]
	v_mov_b32_dpp v77, v76 quad_perm:[1,0,3,2] row_mask:0xf bank_mask:0xf bound_ctrl:1
	v_pk_mul_f32 v[70:71], v[36:37], v[28:29] op_sel:[0,1] op_sel_hi:[1,1]
	v_pk_mul_f32 v[72:73], v[36:37], v[30:31] op_sel_hi:[1,0]
	v_pk_mul_f32 v[74:75], v[36:37], v[30:31] op_sel:[0,1] op_sel_hi:[1,1]
	v_pk_fma_f32 v[68:69], v[2:3], v[24:25], v[68:69] op_sel_hi:[1,0,1]
	v_pk_fma_f32 v[70:71], v[4:5], v[24:25], v[70:71] op_sel:[0,1,0] op_sel_hi:[1,1,1]
	v_pk_fma_f32 v[72:73], v[6:7], v[26:27], v[72:73] op_sel_hi:[1,0,1]
	v_pk_fma_f32 v[74:75], v[8:9], v[26:27], v[74:75] op_sel:[0,1,0] op_sel_hi:[1,1,1]
	v_pk_fma_f32 v[2:3], v[32:33], v[76:77], v[68:69] op_sel_hi:[0,1,1] neg_lo:[1,0,0] neg_hi:[1,0,0]
	v_pk_fma_f32 v[4:5], v[32:33], v[76:77], v[70:71] op_sel:[1,0,0] op_sel_hi:[1,1,1] neg_lo:[1,0,0] neg_hi:[1,0,0]
	v_mul_f32_e32 v83, v36, v38
	v_add_f32_dpp v81, v67, v66 quad_perm:[1,0,3,2] row_mask:0xf bank_mask:0xf bound_ctrl:1
	v_pk_fma_f32 v[6:7], v[34:35], v[76:77], v[72:73] op_sel_hi:[0,1,1] neg_lo:[1,0,0] neg_hi:[1,0,0]
	v_pk_fma_f32 v[8:9], v[34:35], v[76:77], v[74:75] op_sel:[1,0,0] op_sel_hi:[1,1,1] neg_lo:[1,0,0] neg_hi:[1,0,0]
	v_add_f32_dpp v82, v81, v81 quad_perm:[3,2,1,0] row_mask:0xf bank_mask:0xf bound_ctrl:1
	v_fma_f32 v83, -v76, v39, v83
	v_fmac_f32_e32 v82, 0x3e800000, v83
	ds_write_b32 v14, v82 offset:2048
	s_waitcnt lgkmcnt(1)
; #define LAS __attribute__((address_space(3)))
; template <int CTRL> __device__ __forceinline__ float dppf(float x) { return __builtin_bit_cast(float, __builtin_amdgcn_mov_dpp(__builtin_bit_cast(int, x), CTRL, 0xf, 0xf, true)); }
; __device__ __forceinline__ float sum16(float x) { x = sum8(x); x += dppf<0x140>(x); return x; }
; __device__ __forceinline__ void rwkv_item(LAS unsigned char* lds, int l, const bf16_t* PROJ, const bf16_t* LO, bf16_t* YR, float* BON, int b, int h, int qv) {
;     ...
;             for (int t = 0; t < CH; ++t) {
;                 const int tn = (t + 1) & (CH - 1);
;                 const LAS float* pn = pk + tn * 64;
;                 const f32x4 nkk = *(const LAS f32x4*)(pn), nwr = *(const LAS f32x4*)(pn + 2048), nw = *(const LAS f32x4*)(pn + 4096), nk = *(const LAS f32x4*)(pn + 6144), na = *(const LAS f32x4*)(pn + 8192);
;                 const float nv0 = pv[tn * 32], nv1 = pv[tn * 32 + 4]; const f32x2 nsc = *(const LAS f32x2*)(ps + 2 * tn);
;                 float sa[2], yp[2];
; #pragma unroll
;                 for (int c = 0; c < 2; ++c) { const f32x2 pa = S23[c] * kk4.hi + S01[c] * kk4.lo, pb = S23[c] * wr4.hi + S01[c] * wr4.lo; sa[c] = pa.x + pa.y; yp[c] = pb.x + pb.y; }
; #pragma unroll
;                 for (int c = 0; c < 2; ++c) { sa[c] = sum16(sa[c]); yp[c] += dppf<0xB1>(yp[c]); yp[c] += dppf<0x4E>(yp[c]); }
; #pragma unroll
;                 for (int c = 0; c < 2; ++c) {
;                     S01[c] = S01[c] * w4.lo + (k4.lo * vv[c] - a4.lo * sa[c]);
;                     S23[c] = S23[c] * w4.hi + (k4.hi * vv[c] - a4.hi * sa[c]);
;                     py[(t * 32 + 4 * c) * 4] = yp[c] + 0.25f * (vv[c] * sc.x - sa[c] * sc.y);
;                 }
;                 kk4 = nkk; wr4 = nwr; w4 = nw; k4 = nk; a4 = na; vv[0] = nv0; vv[1] = nv1; sc = nsc;
;             }
	v_pk_mul_f32 v[64:65], v[2:3], v[40:41] op_sel_hi:[1,0]
	v_pk_mul_f32 v[66:67], v[2:3], v[44:45] op_sel_hi:[1,0]
	v_pk_fma_f32 v[64:65], v[4:5], v[40:41], v[64:65] op_sel:[0,1,0] op_sel_hi:[1,1,1]
	v_pk_fma_f32 v[66:67], v[4:5], v[44:45], v[66:67] op_sel:[0,1,0] op_sel_hi:[1,1,1]
	v_pk_fma_f32 v[64:65], v[6:7], v[42:43], v[64:65] op_sel_hi:[1,0,1]
	v_pk_fma_f32 v[66:67], v[6:7], v[46:47], v[66:67] op_sel_hi:[1,0,1]
	v_pk_fma_f32 v[64:65], v[8:9], v[42:43], v[64:65] op_sel:[0,1,0] op_sel_hi:[1,1,1]
	v_pk_fma_f32 v[66:67], v[8:9], v[46:47], v[66:67] op_sel:[0,1,0] op_sel_hi:[1,1,1]
	ds_read_b128 v[16:19], v10 offset:1536
	v_add_f32_dpp v78, v65, v64 quad_perm:[1,0,3,2] row_mask:0xf bank_mask:0xf bound_ctrl:1
	ds_read_b128 v[20:23], v10 offset:9728
	ds_read_b128 v[24:27], v10 offset:17920
	v_add_f32_dpp v79, v78, v78 quad_perm:[3,2,1,0] row_mask:0xf bank_mask:0xf bound_ctrl:1
	ds_read_b128 v[28:31], v10 offset:26112
	ds_read_b128 v[32:35], v10 offset:34304
	v_add_f32_dpp v80, v79, v79 row_half_mirror row_mask:0xf bank_mask:0xf bound_ctrl:1
	ds_read_b32 v36, v11 offset:41728
	ds_read_b32 v37, v12 offset:41728
	v_add_f32_dpp v76, v80, v80 row_mirror row_mask:0xf bank_mask:0xf bound_ctrl:1
	ds_read_b64 v[38:39], v13 offset:45104
	v_pk_mul_f32 v[68:69], v[60:61], v[52:53] op_sel_hi:[1,0]
	v_mov_b32_dpp v77, v76 quad_perm:[1,0,3,2] row_mask:0xf bank_mask:0xf bound_ctrl:1
	v_pk_mul_f32 v[70:71], v[60:61], v[52:53] op_sel:[0,1] op_sel_hi:[1,1]
	v_pk_mul_f32 v[72:73], v[60:61], v[54:55] op_sel_hi:[1,0]
	v_pk_mul_f32 v[74:75], v[60:61], v[54:55] op_sel:[0,1] op_sel_hi:[1,1]
	v_pk_fma_f32 v[68:69], v[2:3], v[48:49], v[68:69] op_sel_hi:[1,0,1]
	v_pk_fma_f32 v[70:71], v[4:5], v[48:49], v[70:71] op_sel:[0,1,0] op_sel_hi:[1,1,1]
	v_pk_fma_f32 v[72:73], v[6:7], v[50:51], v[72:73] op_sel_hi:[1,0,1]
	v_pk_fma_f32 v[74:75], v[8:9], v[50:51], v[74:75] op_sel:[0,1,0] op_sel_hi:[1,1,1]
	v_pk_fma_f32 v[2:3], v[56:57], v[76:77], v[68:69] op_sel_hi:[0,1,1] neg_lo:[1,0,0] neg_hi:[1,0,0]
	v_pk_fma_f32 v[4:5], v[56:57], v[76:77], v[70:71] op_sel:[1,0,0] op_sel_hi:[1,1,1] neg_lo:[1,0,0] neg_hi:[1,0,0]
	v_mul_f32_e32 v83, v60, v62
	v_add_f32_dpp v81, v67, v66 quad_perm:[1,0,3,2] row_mask:0xf bank_mask:0xf bound_ctrl:1
	v_pk_fma_f32 v[6:7], v[58:59], v[76:77], v[72:73] op_sel_hi:[0,1,1] neg_lo:[1,0,0] neg_hi:[1,0,0]
	v_pk_fma_f32 v[8:9], v[58:59], v[76:77], v[74:75] op_sel:[1,0,0] op_sel_hi:[1,1,1] neg_lo:[1,0,0] neg_hi:[1,0,0]
	v_add_f32_dpp v82, v81, v81 quad_perm:[3,2,1,0] row_mask:0xf bank_mask:0xf bound_ctrl:1
	v_fma_f32 v83, -v76, v63, v83
	v_fmac_f32_e32 v82, 0x3e800000, v83
	ds_write_b32 v14, v82 offset:2560
	s_waitcnt lgkmcnt(1)
	v_pk_mul_f32 v[64:65], v[2:3], v[16:17] op_sel_hi:[1,0]
	v_pk_mul_f32 v[66:67], v[2:3], v[20:21] op_sel_hi:[1,0]
	v_pk_fma_f32 v[64:65], v[4:5], v[16:17], v[64:65] op_sel:[0,1,0] op_sel_hi:[1,1,1]
	v_pk_fma_f32 v[66:67], v[4:5], v[20:21], v[66:67] op_sel:[0,1,0] op_sel_hi:[1,1,1]
	v_pk_fma_f32 v[64:65], v[6:7], v[18:19], v[64:65] op_sel_hi:[1,0,1]
	v_pk_fma_f32 v[66:67], v[6:7], v[22:23], v[66:67] op_sel_hi:[1,0,1]
	v_pk_fma_f32 v[64:65], v[8:9], v[18:19], v[64:65] op_sel:[0,1,0] op_sel_hi:[1,1,1]
	v_pk_fma_f32 v[66:67], v[8:9], v[22:23], v[66:67] op_sel:[0,1,0] op_sel_hi:[1,1,1]
	ds_read_b128 v[40:43], v10 offset:1792
	v_add_f32_dpp v78, v65, v64 quad_perm:[1,0,3,2] row_mask:0xf bank_mask:0xf bound_ctrl:1
	ds_read_b128 v[44:47], v10 offset:9984
	ds_read_b128 v[48:51], v10 offset:18176
	v_add_f32_dpp v79, v78, v78 quad_perm:[3,2,1,0] row_mask:0xf bank_mask:0xf bound_ctrl:1
	ds_read_b128 v[52:55], v10 offset:26368
	ds_read_b128 v[56:59], v10 offset:34560
	v_add_f32_dpp v80, v79, v79 row_half_mirror row_mask:0xf bank_mask:0xf bound_ctrl:1
	ds_read_b32 v60, v11 offset:41856
	ds_read_b32 v61, v12 offset:41856
	v_add_f32_dpp v76, v80, v80 row_mirror row_mask:0xf bank_mask:0xf bound_ctrl:1
	ds_read_b64 v[62:63], v13 offset:45112
	v_pk_mul_f32 v[68:69], v[36:37], v[28:29] op_sel_hi:[1,0]
	v_mov_b32_dpp v77, v76 quad_perm:[1,0,3,2] row_mask:0xf bank_mask:0xf bound_ctrl:1
	v_pk_mul_f32 v[70:71], v[36:37], v[28:29] op_sel:[0,1] op_sel_hi:[1,1]
	v_pk_mul_f32 v[72:73], v[36:37], v[30:31] op_sel_hi:[1,0]
	v_pk_mul_f32 v[74:75], v[36:37], v[30:31] op_sel:[0,1] op_sel_hi:[1,1]
	v_pk_fma_f32 v[68:69], v[2:3], v[24:25], v[68:69] op_sel_hi:[1,0,1]
	v_pk_fma_f32 v[70:71], v[4:5], v[24:25], v[70:71] op_sel:[0,1,0] op_sel_hi:[1,1,1]
	v_pk_fma_f32 v[72:73], v[6:7], v[26:27], v[72:73] op_sel_hi:[1,0,1]
	v_pk_fma_f32 v[74:75], v[8:9], v[26:27], v[74:75] op_sel:[0,1,0] op_sel_hi:[1,1,1]
	v_pk_fma_f32 v[2:3], v[32:33], v[76:77], v[68:69] op_sel_hi:[0,1,1] neg_lo:[1,0,0] neg_hi:[1,0,0]
	v_pk_fma_f32 v[4:5], v[32:33], v[76:77], v[70:71] op_sel:[1,0,0] op_sel_hi:[1,1,1] neg_lo:[1,0,0] neg_hi:[1,0,0]
	v_mul_f32_e32 v83, v36, v38
	v_add_f32_dpp v81, v67, v66 quad_perm:[1,0,3,2] row_mask:0xf bank_mask:0xf bound_ctrl:1
	v_pk_fma_f32 v[6:7], v[34:35], v[76:77], v[72:73] op_sel_hi:[0,1,1] neg_lo:[1,0,0] neg_hi:[1,0,0]
	v_pk_fma_f32 v[8:9], v[34:35], v[76:77], v[74:75] op_sel:[1,0,0] op_sel_hi:[1,1,1] neg_lo:[1,0,0] neg_hi:[1,0,0]
	v_add_f32_dpp v82, v81, v81 quad_perm:[3,2,1,0] row_mask:0xf bank_mask:0xf bound_ctrl:1
	v_fma_f32 v83, -v76, v39, v83
	v_fmac_f32_e32 v82, 0x3e800000, v83
	ds_write_b32 v14, v82 offset:3072
	s_waitcnt lgkmcnt(1)
; #define LAS __attribute__((address_space(3)))
; template <int CTRL> __device__ __forceinline__ float dppf(float x) { return __builtin_bit_cast(float, __builtin_amdgcn_mov_dpp(__builtin_bit_cast(int, x), CTRL, 0xf, 0xf, true)); }
; __device__ __forceinline__ float sum16(float x) { x = sum8(x); x += dppf<0x140>(x); return x; }
; __device__ __forceinline__ void rwkv_item(LAS unsigned char* lds, int l, const bf16_t* PROJ, const bf16_t* LO, bf16_t* YR, float* BON, int b, int h, int qv) {
;     ...
;             for (int t = 0; t < CH; ++t) {
;                 const int tn = (t + 1) & (CH - 1);
;                 const LAS float* pn = pk + tn * 64;
;                 const f32x4 nkk = *(const LAS f32x4*)(pn), nwr = *(const LAS f32x4*)(pn + 2048), nw = *(const LAS f32x4*)(pn + 4096), nk = *(const LAS f32x4*)(pn + 6144), na = *(const LAS f32x4*)(pn + 8192);
;                 const float nv0 = pv[tn * 32], nv1 = pv[tn * 32 + 4]; const f32x2 nsc = *(const LAS f32x2*)(ps + 2 * tn);
;                 float sa[2], yp[2];
; #pragma unroll
;                 for (int c = 0; c < 2; ++c) { const f32x2 pa = S23[c] * kk4.hi + S01[c] * kk4.lo, pb = S23[c] * wr4.hi + S01[c] * wr4.lo; sa[c] = pa.x + pa.y; yp[c] = pb.x + pb.y; }
; #pragma unroll
;                 for (int c = 0; c < 2; ++c) { sa[c] = sum16(sa[c]); yp[c] += dppf<0xB1>(yp[c]); yp[c] += dppf<0x4E>(yp[c]); }
; #pragma unroll
;                 for (int c = 0; c < 2; ++c) {
;                     S01[c] = S01[c] * w4.lo + (k4.lo * vv[c] - a4.lo * sa[c]);
;                     S23[c] = S23[c] * w4.hi + (k4.hi * vv[c] - a4.hi * sa[c]);
;                     py[(t * 32 + 4 * c) * 4] = yp[c] + 0.25f * (vv[c] * sc.x - sa[c] * sc.y);
;                 }
;                 kk4 = nkk; wr4 = nwr; w4 = nw; k4 = nk; a4 = na; vv[0] = nv0; vv[1] = nv1; sc = nsc;
;             }
	v_pk_mul_f32 v[64:65], v[2:3], v[40:41] op_sel_hi:[1,0]
	v_pk_mul_f32 v[66:67], v[2:3], v[44:45] op_sel_hi:[1,0]
	v_pk_fma_f32 v[64:65], v[4:5], v[40:41], v[64:65] op_sel:[0,1,0] op_sel_hi:[1,1,1]
	v_pk_fma_f32 v[66:67], v[4:5], v[44:45], v[66:67] op_sel:[0,1,0] op_sel_hi:[1,1,1]
	v_pk_fma_f32 v[64:65], v[6:7], v[42:43], v[64:65] op_sel_hi:[1,0,1]
	v_pk_fma_f32 v[66:67], v[6:7], v[46:47], v[66:67] op_sel_hi:[1,0,1]
	v_pk_fma_f32 v[64:65], v[8:9], v[42:43], v[64:65] op_sel:[0,1,0] op_sel_hi:[1,1,1]
	v_pk_fma_f32 v[66:67], v[8:9], v[46:47], v[66:67] op_sel:[0,1,0] op_sel_hi:[1,1,1]
	ds_read_b128 v[16:19], v10 offset:2048
	v_add_f32_dpp v78, v65, v64 quad_perm:[1,0,3,2] row_mask:0xf bank_mask:0xf bound_ctrl:1
	ds_read_b128 v[20:23], v10 offset:10240
	ds_read_b128 v[24:27], v10 offset:18432
	v_add_f32_dpp v79, v78, v78 quad_perm:[3,2,1,0] row_mask:0xf bank_mask:0xf bound_ctrl:1
	ds_read_b128 v[28:31], v10 offset:26624
	ds_read_b128 v[32:35], v10 offset:34816
	v_add_f32_dpp v80, v79, v79 row_half_mirror row_mask:0xf bank_mask:0xf bound_ctrl:1
	ds_read_b32 v36, v11 offset:41984
	ds_read_b32 v37, v12 offset:41984
	v_add_f32_dpp v76, v80, v80 row_mirror row_mask:0xf bank_mask:0xf bound_ctrl:1
	ds_read_b64 v[38:39], v13 offset:45120
	v_pk_mul_f32 v[68:69], v[60:61], v[52:53] op_sel_hi:[1,0]
	v_mov_b32_dpp v77, v76 quad_perm:[1,0,3,2] row_mask:0xf bank_mask:0xf bound_ctrl:1
	v_pk_mul_f32 v[70:71], v[60:61], v[52:53] op_sel:[0,1] op_sel_hi:[1,1]
	v_pk_mul_f32 v[72:73], v[60:61], v[54:55] op_sel_hi:[1,0]
	v_pk_mul_f32 v[74:75], v[60:61], v[54:55] op_sel:[0,1] op_sel_hi:[1,1]
	v_pk_fma_f32 v[68:69], v[2:3], v[48:49], v[68:69] op_sel_hi:[1,0,1]
	v_pk_fma_f32 v[70:71], v[4:5], v[48:49], v[70:71] op_sel:[0,1,0] op_sel_hi:[1,1,1]
	v_pk_fma_f32 v[72:73], v[6:7], v[50:51], v[72:73] op_sel_hi:[1,0,1]
	v_pk_fma_f32 v[74:75], v[8:9], v[50:51], v[74:75] op_sel:[0,1,0] op_sel_hi:[1,1,1]
	v_pk_fma_f32 v[2:3], v[56:57], v[76:77], v[68:69] op_sel_hi:[0,1,1] neg_lo:[1,0,0] neg_hi:[1,0,0]
	v_pk_fma_f32 v[4:5], v[56:57], v[76:77], v[70:71] op_sel:[1,0,0] op_sel_hi:[1,1,1] neg_lo:[1,0,0] neg_hi:[1,0,0]
	v_mul_f32_e32 v83, v60, v62
	v_add_f32_dpp v81, v67, v66 quad_perm:[1,0,3,2] row_mask:0xf bank_mask:0xf bound_ctrl:1
	v_pk_fma_f32 v[6:7], v[58:59], v[76:77], v[72:73] op_sel_hi:[0,1,1] neg_lo:[1,0,0] neg_hi:[1,0,0]
	v_pk_fma_f32 v[8:9], v[58:59], v[76:77], v[74:75] op_sel:[1,0,0] op_sel_hi:[1,1,1] neg_lo:[1,0,0] neg_hi:[1,0,0]
	v_add_f32_dpp v82, v81, v81 quad_perm:[3,2,1,0] row_mask:0xf bank_mask:0xf bound_ctrl:1
	v_fma_f32 v83, -v76, v63, v83
	v_fmac_f32_e32 v82, 0x3e800000, v83
	ds_write_b32 v14, v82 offset:3584
	s_waitcnt lgkmcnt(1)
	v_pk_mul_f32 v[64:65], v[2:3], v[16:17] op_sel_hi:[1,0]
	v_pk_mul_f32 v[66:67], v[2:3], v[20:21] op_sel_hi:[1,0]
	v_pk_fma_f32 v[64:65], v[4:5], v[16:17], v[64:65] op_sel:[0,1,0] op_sel_hi:[1,1,1]
	v_pk_fma_f32 v[66:67], v[4:5], v[20:21], v[66:67] op_sel:[0,1,0] op_sel_hi:[1,1,1]
	v_pk_fma_f32 v[64:65], v[6:7], v[18:19], v[64:65] op_sel_hi:[1,0,1]
	v_pk_fma_f32 v[66:67], v[6:7], v[22:23], v[66:67] op_sel_hi:[1,0,1]
	v_pk_fma_f32 v[64:65], v[8:9], v[18:19], v[64:65] op_sel:[0,1,0] op_sel_hi:[1,1,1]
	v_pk_fma_f32 v[66:67], v[8:9], v[22:23], v[66:67] op_sel:[0,1,0] op_sel_hi:[1,1,1]
	ds_read_b128 v[40:43], v10 offset:2304
	v_add_f32_dpp v78, v65, v64 quad_perm:[1,0,3,2] row_mask:0xf bank_mask:0xf bound_ctrl:1
	ds_read_b128 v[44:47], v10 offset:10496
	ds_read_b128 v[48:51], v10 offset:18688
	v_add_f32_dpp v79, v78, v78 quad_perm:[3,2,1,0] row_mask:0xf bank_mask:0xf bound_ctrl:1
	ds_read_b128 v[52:55], v10 offset:26880
	ds_read_b128 v[56:59], v10 offset:35072
	v_add_f32_dpp v80, v79, v79 row_half_mirror row_mask:0xf bank_mask:0xf bound_ctrl:1
	ds_read_b32 v60, v11 offset:42112
	ds_read_b32 v61, v12 offset:42112
	v_add_f32_dpp v76, v80, v80 row_mirror row_mask:0xf bank_mask:0xf bound_ctrl:1
	ds_read_b64 v[62:63], v13 offset:45128
	v_pk_mul_f32 v[68:69], v[36:37], v[28:29] op_sel_hi:[1,0]
	v_mov_b32_dpp v77, v76 quad_perm:[1,0,3,2] row_mask:0xf bank_mask:0xf bound_ctrl:1
	v_pk_mul_f32 v[70:71], v[36:37], v[28:29] op_sel:[0,1] op_sel_hi:[1,1]
	v_pk_mul_f32 v[72:73], v[36:37], v[30:31] op_sel_hi:[1,0]
	v_pk_mul_f32 v[74:75], v[36:37], v[30:31] op_sel:[0,1] op_sel_hi:[1,1]
	v_pk_fma_f32 v[68:69], v[2:3], v[24:25], v[68:69] op_sel_hi:[1,0,1]
	v_pk_fma_f32 v[70:71], v[4:5], v[24:25], v[70:71] op_sel:[0,1,0] op_sel_hi:[1,1,1]
	v_pk_fma_f32 v[72:73], v[6:7], v[26:27], v[72:73] op_sel_hi:[1,0,1]
	v_pk_fma_f32 v[74:75], v[8:9], v[26:27], v[74:75] op_sel:[0,1,0] op_sel_hi:[1,1,1]
	v_pk_fma_f32 v[2:3], v[32:33], v[76:77], v[68:69] op_sel_hi:[0,1,1] neg_lo:[1,0,0] neg_hi:[1,0,0]
	v_pk_fma_f32 v[4:5], v[32:33], v[76:77], v[70:71] op_sel:[1,0,0] op_sel_hi:[1,1,1] neg_lo:[1,0,0] neg_hi:[1,0,0]
	v_mul_f32_e32 v83, v36, v38
	v_add_f32_dpp v81, v67, v66 quad_perm:[1,0,3,2] row_mask:0xf bank_mask:0xf bound_ctrl:1
	v_pk_fma_f32 v[6:7], v[34:35], v[76:77], v[72:73] op_sel_hi:[0,1,1] neg_lo:[1,0,0] neg_hi:[1,0,0]
	v_pk_fma_f32 v[8:9], v[34:35], v[76:77], v[74:75] op_sel:[1,0,0] op_sel_hi:[1,1,1] neg_lo:[1,0,0] neg_hi:[1,0,0]
	v_add_f32_dpp v82, v81, v81 quad_perm:[3,2,1,0] row_mask:0xf bank_mask:0xf bound_ctrl:1
	v_fma_f32 v83, -v76, v39, v83
	v_fmac_f32_e32 v82, 0x3e800000, v83
	ds_write_b32 v14, v82 offset:4096
	s_waitcnt lgkmcnt(1)
; #define LAS __attribute__((address_space(3)))
; template <int CTRL> __device__ __forceinline__ float dppf(float x) { return __builtin_bit_cast(float, __builtin_amdgcn_mov_dpp(__builtin_bit_cast(int, x), CTRL, 0xf, 0xf, true)); }
; __device__ __forceinline__ float sum16(float x) { x = sum8(x); x += dppf<0x140>(x); return x; }
; __device__ __forceinline__ void rwkv_item(LAS unsigned char* lds, int l, const bf16_t* PROJ, const bf16_t* LO, bf16_t* YR, float* BON, int b, int h, int qv) {
;     ...
;             for (int t = 0; t < CH; ++t) {
;                 const int tn = (t + 1) & (CH - 1);
;                 const LAS float* pn = pk + tn * 64;
;                 const f32x4 nkk = *(const LAS f32x4*)(pn), nwr = *(const LAS f32x4*)(pn + 2048), nw = *(const LAS f32x4*)(pn + 4096), nk = *(const LAS f32x4*)(pn + 6144), na = *(const LAS f32x4*)(pn + 8192);
;                 const float nv0 = pv[tn * 32], nv1 = pv[tn * 32 + 4]; const f32x2 nsc = *(const LAS f32x2*)(ps + 2 * tn);
;                 float sa[2], yp[2];
; #pragma unroll
;                 for (int c = 0; c < 2; ++c) { const f32x2 pa = S23[c] * kk4.hi + S01[c] * kk4.lo, pb = S23[c] * wr4.hi + S01[c] * wr4.lo; sa[c] = pa.x + pa.y; yp[c] = pb.x + pb.y; }
; #pragma unroll
;                 for (int c = 0; c < 2; ++c) { sa[c] = sum16(sa[c]); yp[c] += dppf<0xB1>(yp[c]); yp[c] += dppf<0x4E>(yp[c]); }
; #pragma unroll
;                 for (int c = 0; c < 2; ++c) {
;                     S01[c] = S01[c] * w4.lo + (k4.lo * vv[c] - a4.lo * sa[c]);
;                     S23[c] = S23[c] * w4.hi + (k4.hi * vv[c] - a4.hi * sa[c]);
;                     py[(t * 32 + 4 * c) * 4] = yp[c] + 0.25f * (vv[c] * sc.x - sa[c] * sc.y);
;                 }
;                 kk4 = nkk; wr4 = nwr; w4 = nw; k4 = nk; a4 = na; vv[0] = nv0; vv[1] = nv1; sc = nsc;
;             }
	v_pk_mul_f32 v[64:65], v[2:3], v[40:41] op_sel_hi:[1,0]
	v_pk_mul_f32 v[66:67], v[2:3], v[44:45] op_sel_hi:[1,0]
	v_pk_fma_f32 v[64:65], v[4:5], v[40:41], v[64:65] op_sel:[0,1,0] op_sel_hi:[1,1,1]
	v_pk_fma_f32 v[66:67], v[4:5], v[44:45], v[66:67] op_sel:[0,1,0] op_sel_hi:[1,1,1]
	v_pk_fma_f32 v[64:65], v[6:7], v[42:43], v[64:65] op_sel_hi:[1,0,1]
	v_pk_fma_f32 v[66:67], v[6:7], v[46:47], v[66:67] op_sel_hi:[1,0,1]
	v_pk_fma_f32 v[64:65], v[8:9], v[42:43], v[64:65] op_sel:[0,1,0] op_sel_hi:[1,1,1]
	v_pk_fma_f32 v[66:67], v[8:9], v[46:47], v[66:67] op_sel:[0,1,0] op_sel_hi:[1,1,1]
	ds_read_b128 v[16:19], v10 offset:2560
	v_add_f32_dpp v78, v65, v64 quad_perm:[1,0,3,2] row_mask:0xf bank_mask:0xf bound_ctrl:1
	ds_read_b128 v[20:23], v10 offset:10752
	ds_read_b128 v[24:27], v10 offset:18944
	v_add_f32_dpp v79, v78, v78 quad_perm:[3,2,1,0] row_mask:0xf bank_mask:0xf bound_ctrl:1
	ds_read_b128 v[28:31], v10 offset:27136
	ds_read_b128 v[32:35], v10 offset:35328
	v_add_f32_dpp v80, v79, v79 row_half_mirror row_mask:0xf bank_mask:0xf bound_ctrl:1
	ds_read_b32 v36, v11 offset:42240
	ds_read_b32 v37, v12 offset:42240
	v_add_f32_dpp v76, v80, v80 row_mirror row_mask:0xf bank_mask:0xf bound_ctrl:1
	ds_read_b64 v[38:39], v13 offset:45136
	v_pk_mul_f32 v[68:69], v[60:61], v[52:53] op_sel_hi:[1,0]
	v_mov_b32_dpp v77, v76 quad_perm:[1,0,3,2] row_mask:0xf bank_mask:0xf bound_ctrl:1
	v_pk_mul_f32 v[70:71], v[60:61], v[52:53] op_sel:[0,1] op_sel_hi:[1,1]
	v_pk_mul_f32 v[72:73], v[60:61], v[54:55] op_sel_hi:[1,0]
	v_pk_mul_f32 v[74:75], v[60:61], v[54:55] op_sel:[0,1] op_sel_hi:[1,1]
	v_pk_fma_f32 v[68:69], v[2:3], v[48:49], v[68:69] op_sel_hi:[1,0,1]
	v_pk_fma_f32 v[70:71], v[4:5], v[48:49], v[70:71] op_sel:[0,1,0] op_sel_hi:[1,1,1]
	v_pk_fma_f32 v[72:73], v[6:7], v[50:51], v[72:73] op_sel_hi:[1,0,1]
	v_pk_fma_f32 v[74:75], v[8:9], v[50:51], v[74:75] op_sel:[0,1,0] op_sel_hi:[1,1,1]
	v_pk_fma_f32 v[2:3], v[56:57], v[76:77], v[68:69] op_sel_hi:[0,1,1] neg_lo:[1,0,0] neg_hi:[1,0,0]
	v_pk_fma_f32 v[4:5], v[56:57], v[76:77], v[70:71] op_sel:[1,0,0] op_sel_hi:[1,1,1] neg_lo:[1,0,0] neg_hi:[1,0,0]
	v_mul_f32_e32 v83, v60, v62
	v_add_f32_dpp v81, v67, v66 quad_perm:[1,0,3,2] row_mask:0xf bank_mask:0xf bound_ctrl:1
	v_pk_fma_f32 v[6:7], v[58:59], v[76:77], v[72:73] op_sel_hi:[0,1,1] neg_lo:[1,0,0] neg_hi:[1,0,0]
	v_pk_fma_f32 v[8:9], v[58:59], v[76:77], v[74:75] op_sel:[1,0,0] op_sel_hi:[1,1,1] neg_lo:[1,0,0] neg_hi:[1,0,0]
	v_add_f32_dpp v82, v81, v81 quad_perm:[3,2,1,0] row_mask:0xf bank_mask:0xf bound_ctrl:1
	v_fma_f32 v83, -v76, v63, v83
	v_fmac_f32_e32 v82, 0x3e800000, v83
	ds_write_b32 v14, v82 offset:4608
	s_waitcnt lgkmcnt(1)
	v_pk_mul_f32 v[64:65], v[2:3], v[16:17] op_sel_hi:[1,0]
	v_pk_mul_f32 v[66:67], v[2:3], v[20:21] op_sel_hi:[1,0]
	v_pk_fma_f32 v[64:65], v[4:5], v[16:17], v[64:65] op_sel:[0,1,0] op_sel_hi:[1,1,1]
	v_pk_fma_f32 v[66:67], v[4:5], v[20:21], v[66:67] op_sel:[0,1,0] op_sel_hi:[1,1,1]
	v_pk_fma_f32 v[64:65], v[6:7], v[18:19], v[64:65] op_sel_hi:[1,0,1]
	v_pk_fma_f32 v[66:67], v[6:7], v[22:23], v[66:67] op_sel_hi:[1,0,1]
	v_pk_fma_f32 v[64:65], v[8:9], v[18:19], v[64:65] op_sel:[0,1,0] op_sel_hi:[1,1,1]
	v_pk_fma_f32 v[66:67], v[8:9], v[22:23], v[66:67] op_sel:[0,1,0] op_sel_hi:[1,1,1]
	ds_read_b128 v[40:43], v10 offset:2816
	v_add_f32_dpp v78, v65, v64 quad_perm:[1,0,3,2] row_mask:0xf bank_mask:0xf bound_ctrl:1
	ds_read_b128 v[44:47], v10 offset:11008
	ds_read_b128 v[48:51], v10 offset:19200
	v_add_f32_dpp v79, v78, v78 quad_perm:[3,2,1,0] row_mask:0xf bank_mask:0xf bound_ctrl:1
	ds_read_b128 v[52:55], v10 offset:27392
	ds_read_b128 v[56:59], v10 offset:35584
	v_add_f32_dpp v80, v79, v79 row_half_mirror row_mask:0xf bank_mask:0xf bound_ctrl:1
	ds_read_b32 v60, v11 offset:42368
	ds_read_b32 v61, v12 offset:42368
	v_add_f32_dpp v76, v80, v80 row_mirror row_mask:0xf bank_mask:0xf bound_ctrl:1
	ds_read_b64 v[62:63], v13 offset:45144
	v_pk_mul_f32 v[68:69], v[36:37], v[28:29] op_sel_hi:[1,0]
	v_mov_b32_dpp v77, v76 quad_perm:[1,0,3,2] row_mask:0xf bank_mask:0xf bound_ctrl:1
	v_pk_mul_f32 v[70:71], v[36:37], v[28:29] op_sel:[0,1] op_sel_hi:[1,1]
	v_pk_mul_f32 v[72:73], v[36:37], v[30:31] op_sel_hi:[1,0]
	v_pk_mul_f32 v[74:75], v[36:37], v[30:31] op_sel:[0,1] op_sel_hi:[1,1]
	v_pk_fma_f32 v[68:69], v[2:3], v[24:25], v[68:69] op_sel_hi:[1,0,1]
	v_pk_fma_f32 v[70:71], v[4:5], v[24:25], v[70:71] op_sel:[0,1,0] op_sel_hi:[1,1,1]
	v_pk_fma_f32 v[72:73], v[6:7], v[26:27], v[72:73] op_sel_hi:[1,0,1]
	v_pk_fma_f32 v[74:75], v[8:9], v[26:27], v[74:75] op_sel:[0,1,0] op_sel_hi:[1,1,1]
	v_pk_fma_f32 v[2:3], v[32:33], v[76:77], v[68:69] op_sel_hi:[0,1,1] neg_lo:[1,0,0] neg_hi:[1,0,0]
	v_pk_fma_f32 v[4:5], v[32:33], v[76:77], v[70:71] op_sel:[1,0,0] op_sel_hi:[1,1,1] neg_lo:[1,0,0] neg_hi:[1,0,0]
	v_mul_f32_e32 v83, v36, v38
	v_add_f32_dpp v81, v67, v66 quad_perm:[1,0,3,2] row_mask:0xf bank_mask:0xf bound_ctrl:1
	v_pk_fma_f32 v[6:7], v[34:35], v[76:77], v[72:73] op_sel_hi:[0,1,1] neg_lo:[1,0,0] neg_hi:[1,0,0]
	v_pk_fma_f32 v[8:9], v[34:35], v[76:77], v[74:75] op_sel:[1,0,0] op_sel_hi:[1,1,1] neg_lo:[1,0,0] neg_hi:[1,0,0]
	v_add_f32_dpp v82, v81, v81 quad_perm:[3,2,1,0] row_mask:0xf bank_mask:0xf bound_ctrl:1
	v_fma_f32 v83, -v76, v39, v83
	v_fmac_f32_e32 v82, 0x3e800000, v83
	ds_write_b32 v14, v82 offset:5120
	s_waitcnt lgkmcnt(1)
; #define LAS __attribute__((address_space(3)))
; template <int CTRL> __device__ __forceinline__ float dppf(float x) { return __builtin_bit_cast(float, __builtin_amdgcn_mov_dpp(__builtin_bit_cast(int, x), CTRL, 0xf, 0xf, true)); }
; __device__ __forceinline__ float sum16(float x) { x = sum8(x); x += dppf<0x140>(x); return x; }
; __device__ __forceinline__ void rwkv_item(LAS unsigned char* lds, int l, const bf16_t* PROJ, const bf16_t* LO, bf16_t* YR, float* BON, int b, int h, int qv) {
;     ...
;             for (int t = 0; t < CH; ++t) {
;                 const int tn = (t + 1) & (CH - 1);
;                 const LAS float* pn = pk + tn * 64;
;                 const f32x4 nkk = *(const LAS f32x4*)(pn), nwr = *(const LAS f32x4*)(pn + 2048), nw = *(const LAS f32x4*)(pn + 4096), nk = *(const LAS f32x4*)(pn + 6144), na = *(const LAS f32x4*)(pn + 8192);
;                 const float nv0 = pv[tn * 32], nv1 = pv[tn * 32 + 4]; const f32x2 nsc = *(const LAS f32x2*)(ps + 2 * tn);
;                 float sa[2], yp[2];
; #pragma unroll
;                 for (int c = 0; c < 2; ++c) { const f32x2 pa = S23[c] * kk4.hi + S01[c] * kk4.lo, pb = S23[c] * wr4.hi + S01[c] * wr4.lo; sa[c] = pa.x + pa.y; yp[c] = pb.x + pb.y; }
; #pragma unroll
;                 for (int c = 0; c < 2; ++c) { sa[c] = sum16(sa[c]); yp[c] += dppf<0xB1>(yp[c]); yp[c] += dppf<0x4E>(yp[c]); }
; #pragma unroll
;                 for (int c = 0; c < 2; ++c) {
;                     S01[c] = S01[c] * w4.lo + (k4.lo * vv[c] - a4.lo * sa[c]);
;                     S23[c] = S23[c] * w4.hi + (k4.hi * vv[c] - a4.hi * sa[c]);
;                     py[(t * 32 + 4 * c) * 4] = yp[c] + 0.25f * (vv[c] * sc.x - sa[c] * sc.y);
;                 }
;                 kk4 = nkk; wr4 = nwr; w4 = nw; k4 = nk; a4 = na; vv[0] = nv0; vv[1] = nv1; sc = nsc;
;             }
	v_pk_mul_f32 v[64:65], v[2:3], v[40:41] op_sel_hi:[1,0]
	v_pk_mul_f32 v[66:67], v[2:3], v[44:45] op_sel_hi:[1,0]
	v_pk_fma_f32 v[64:65], v[4:5], v[40:41], v[64:65] op_sel:[0,1,0] op_sel_hi:[1,1,1]
	v_pk_fma_f32 v[66:67], v[4:5], v[44:45], v[66:67] op_sel:[0,1,0] op_sel_hi:[1,1,1]
	v_pk_fma_f32 v[64:65], v[6:7], v[42:43], v[64:65] op_sel_hi:[1,0,1]
	v_pk_fma_f32 v[66:67], v[6:7], v[46:47], v[66:67] op_sel_hi:[1,0,1]
	v_pk_fma_f32 v[64:65], v[8:9], v[42:43], v[64:65] op_sel:[0,1,0] op_sel_hi:[1,1,1]
	v_pk_fma_f32 v[66:67], v[8:9], v[46:47], v[66:67] op_sel:[0,1,0] op_sel_hi:[1,1,1]
	ds_read_b128 v[16:19], v10 offset:3072
	v_add_f32_dpp v78, v65, v64 quad_perm:[1,0,3,2] row_mask:0xf bank_mask:0xf bound_ctrl:1
	ds_read_b128 v[20:23], v10 offset:11264
	ds_read_b128 v[24:27], v10 offset:19456
	v_add_f32_dpp v79, v78, v78 quad_perm:[3,2,1,0] row_mask:0xf bank_mask:0xf bound_ctrl:1
	ds_read_b128 v[28:31], v10 offset:27648
	ds_read_b128 v[32:35], v10 offset:35840
	v_add_f32_dpp v80, v79, v79 row_half_mirror row_mask:0xf bank_mask:0xf bound_ctrl:1
	ds_read_b32 v36, v11 offset:42496
	ds_read_b32 v37, v12 offset:42496
	v_add_f32_dpp v76, v80, v80 row_mirror row_mask:0xf bank_mask:0xf bound_ctrl:1
	ds_read_b64 v[38:39], v13 offset:45152
	v_pk_mul_f32 v[68:69], v[60:61], v[52:53] op_sel_hi:[1,0]
	v_mov_b32_dpp v77, v76 quad_perm:[1,0,3,2] row_mask:0xf bank_mask:0xf bound_ctrl:1
	v_pk_mul_f32 v[70:71], v[60:61], v[52:53] op_sel:[0,1] op_sel_hi:[1,1]
	v_pk_mul_f32 v[72:73], v[60:61], v[54:55] op_sel_hi:[1,0]
	v_pk_mul_f32 v[74:75], v[60:61], v[54:55] op_sel:[0,1] op_sel_hi:[1,1]
	v_pk_fma_f32 v[68:69], v[2:3], v[48:49], v[68:69] op_sel_hi:[1,0,1]
	v_pk_fma_f32 v[70:71], v[4:5], v[48:49], v[70:71] op_sel:[0,1,0] op_sel_hi:[1,1,1]
	v_pk_fma_f32 v[72:73], v[6:7], v[50:51], v[72:73] op_sel_hi:[1,0,1]
	v_pk_fma_f32 v[74:75], v[8:9], v[50:51], v[74:75] op_sel:[0,1,0] op_sel_hi:[1,1,1]
	v_pk_fma_f32 v[2:3], v[56:57], v[76:77], v[68:69] op_sel_hi:[0,1,1] neg_lo:[1,0,0] neg_hi:[1,0,0]
	v_pk_fma_f32 v[4:5], v[56:57], v[76:77], v[70:71] op_sel:[1,0,0] op_sel_hi:[1,1,1] neg_lo:[1,0,0] neg_hi:[1,0,0]
	v_mul_f32_e32 v83, v60, v62
	v_add_f32_dpp v81, v67, v66 quad_perm:[1,0,3,2] row_mask:0xf bank_mask:0xf bound_ctrl:1
	v_pk_fma_f32 v[6:7], v[58:59], v[76:77], v[72:73] op_sel_hi:[0,1,1] neg_lo:[1,0,0] neg_hi:[1,0,0]
	v_pk_fma_f32 v[8:9], v[58:59], v[76:77], v[74:75] op_sel:[1,0,0] op_sel_hi:[1,1,1] neg_lo:[1,0,0] neg_hi:[1,0,0]
	v_add_f32_dpp v82, v81, v81 quad_perm:[3,2,1,0] row_mask:0xf bank_mask:0xf bound_ctrl:1
	v_fma_f32 v83, -v76, v63, v83
	v_fmac_f32_e32 v82, 0x3e800000, v83
	ds_write_b32 v14, v82 offset:5632
	s_waitcnt lgkmcnt(1)
	v_pk_mul_f32 v[64:65], v[2:3], v[16:17] op_sel_hi:[1,0]
	v_pk_mul_f32 v[66:67], v[2:3], v[20:21] op_sel_hi:[1,0]
	v_pk_fma_f32 v[64:65], v[4:5], v[16:17], v[64:65] op_sel:[0,1,0] op_sel_hi:[1,1,1]
	v_pk_fma_f32 v[66:67], v[4:5], v[20:21], v[66:67] op_sel:[0,1,0] op_sel_hi:[1,1,1]
	v_pk_fma_f32 v[64:65], v[6:7], v[18:19], v[64:65] op_sel_hi:[1,0,1]
	v_pk_fma_f32 v[66:67], v[6:7], v[22:23], v[66:67] op_sel_hi:[1,0,1]
	v_pk_fma_f32 v[64:65], v[8:9], v[18:19], v[64:65] op_sel:[0,1,0] op_sel_hi:[1,1,1]
	v_pk_fma_f32 v[66:67], v[8:9], v[22:23], v[66:67] op_sel:[0,1,0] op_sel_hi:[1,1,1]
	ds_read_b128 v[40:43], v10 offset:3328
	v_add_f32_dpp v78, v65, v64 quad_perm:[1,0,3,2] row_mask:0xf bank_mask:0xf bound_ctrl:1
	ds_read_b128 v[44:47], v10 offset:11520
	ds_read_b128 v[48:51], v10 offset:19712
	v_add_f32_dpp v79, v78, v78 quad_perm:[3,2,1,0] row_mask:0xf bank_mask:0xf bound_ctrl:1
	ds_read_b128 v[52:55], v10 offset:27904
	ds_read_b128 v[56:59], v10 offset:36096
	v_add_f32_dpp v80, v79, v79 row_half_mirror row_mask:0xf bank_mask:0xf bound_ctrl:1
	ds_read_b32 v60, v11 offset:42624
	ds_read_b32 v61, v12 offset:42624
	v_add_f32_dpp v76, v80, v80 row_mirror row_mask:0xf bank_mask:0xf bound_ctrl:1
	ds_read_b64 v[62:63], v13 offset:45160
	v_pk_mul_f32 v[68:69], v[36:37], v[28:29] op_sel_hi:[1,0]
	v_mov_b32_dpp v77, v76 quad_perm:[1,0,3,2] row_mask:0xf bank_mask:0xf bound_ctrl:1
	v_pk_mul_f32 v[70:71], v[36:37], v[28:29] op_sel:[0,1] op_sel_hi:[1,1]
	v_pk_mul_f32 v[72:73], v[36:37], v[30:31] op_sel_hi:[1,0]
	v_pk_mul_f32 v[74:75], v[36:37], v[30:31] op_sel:[0,1] op_sel_hi:[1,1]
	v_pk_fma_f32 v[68:69], v[2:3], v[24:25], v[68:69] op_sel_hi:[1,0,1]
	v_pk_fma_f32 v[70:71], v[4:5], v[24:25], v[70:71] op_sel:[0,1,0] op_sel_hi:[1,1,1]
	v_pk_fma_f32 v[72:73], v[6:7], v[26:27], v[72:73] op_sel_hi:[1,0,1]
	v_pk_fma_f32 v[74:75], v[8:9], v[26:27], v[74:75] op_sel:[0,1,0] op_sel_hi:[1,1,1]
	v_pk_fma_f32 v[2:3], v[32:33], v[76:77], v[68:69] op_sel_hi:[0,1,1] neg_lo:[1,0,0] neg_hi:[1,0,0]
	v_pk_fma_f32 v[4:5], v[32:33], v[76:77], v[70:71] op_sel:[1,0,0] op_sel_hi:[1,1,1] neg_lo:[1,0,0] neg_hi:[1,0,0]
	v_mul_f32_e32 v83, v36, v38
	v_add_f32_dpp v81, v67, v66 quad_perm:[1,0,3,2] row_mask:0xf bank_mask:0xf bound_ctrl:1
	v_pk_fma_f32 v[6:7], v[34:35], v[76:77], v[72:73] op_sel_hi:[0,1,1] neg_lo:[1,0,0] neg_hi:[1,0,0]
	v_pk_fma_f32 v[8:9], v[34:35], v[76:77], v[74:75] op_sel:[1,0,0] op_sel_hi:[1,1,1] neg_lo:[1,0,0] neg_hi:[1,0,0]
	v_add_f32_dpp v82, v81, v81 quad_perm:[3,2,1,0] row_mask:0xf bank_mask:0xf bound_ctrl:1
	v_fma_f32 v83, -v76, v39, v83
	v_fmac_f32_e32 v82, 0x3e800000, v83
	ds_write_b32 v14, v82 offset:6144
	s_waitcnt lgkmcnt(1)
; #define LAS __attribute__((address_space(3)))
; template <int CTRL> __device__ __forceinline__ float dppf(float x) { return __builtin_bit_cast(float, __builtin_amdgcn_mov_dpp(__builtin_bit_cast(int, x), CTRL, 0xf, 0xf, true)); }
; __device__ __forceinline__ float sum16(float x) { x = sum8(x); x += dppf<0x140>(x); return x; }
; __device__ __forceinline__ void rwkv_item(LAS unsigned char* lds, int l, const bf16_t* PROJ, const bf16_t* LO, bf16_t* YR, float* BON, int b, int h, int qv) {
;     ...
;             for (int t = 0; t < CH; ++t) {
;                 const int tn = (t + 1) & (CH - 1);
;                 const LAS float* pn = pk + tn * 64;
;                 const f32x4 nkk = *(const LAS f32x4*)(pn), nwr = *(const LAS f32x4*)(pn + 2048), nw = *(const LAS f32x4*)(pn + 4096), nk = *(const LAS f32x4*)(pn + 6144), na = *(const LAS f32x4*)(pn + 8192);
;                 const float nv0 = pv[tn * 32], nv1 = pv[tn * 32 + 4]; const f32x2 nsc = *(const LAS f32x2*)(ps + 2 * tn);
;                 float sa[2], yp[2];
; #pragma unroll
;                 for (int c = 0; c < 2; ++c) { const f32x2 pa = S23[c] * kk4.hi + S01[c] * kk4.lo, pb = S23[c] * wr4.hi + S01[c] * wr4.lo; sa[c] = pa.x + pa.y; yp[c] = pb.x + pb.y; }
; #pragma unroll
;                 for (int c = 0; c < 2; ++c) { sa[c] = sum16(sa[c]); yp[c] += dppf<0xB1>(yp[c]); yp[c] += dppf<0x4E>(yp[c]); }
; #pragma unroll
;                 for (int c = 0; c < 2; ++c) {
;                     S01[c] = S01[c] * w4.lo + (k4.lo * vv[c] - a4.lo * sa[c]);
;                     S23[c] = S23[c] * w4.hi + (k4.hi * vv[c] - a4.hi * sa[c]);
;                     py[(t * 32 + 4 * c) * 4] = yp[c] + 0.25f * (vv[c] * sc.x - sa[c] * sc.y);
;                 }
;                 kk4 = nkk; wr4 = nwr; w4 = nw; k4 = nk; a4 = na; vv[0] = nv0; vv[1] = nv1; sc = nsc;
;             }
	v_pk_mul_f32 v[64:65], v[2:3], v[40:41] op_sel_hi:[1,0]
	v_pk_mul_f32 v[66:67], v[2:3], v[44:45] op_sel_hi:[1,0]
	v_pk_fma_f32 v[64:65], v[4:5], v[40:41], v[64:65] op_sel:[0,1,0] op_sel_hi:[1,1,1]
	v_pk_fma_f32 v[66:67], v[4:5], v[44:45], v[66:67] op_sel:[0,1,0] op_sel_hi:[1,1,1]
	v_pk_fma_f32 v[64:65], v[6:7], v[42:43], v[64:65] op_sel_hi:[1,0,1]
	v_pk_fma_f32 v[66:67], v[6:7], v[46:47], v[66:67] op_sel_hi:[1,0,1]
	v_pk_fma_f32 v[64:65], v[8:9], v[42:43], v[64:65] op_sel:[0,1,0] op_sel_hi:[1,1,1]
	v_pk_fma_f32 v[66:67], v[8:9], v[46:47], v[66:67] op_sel:[0,1,0] op_sel_hi:[1,1,1]
	ds_read_b128 v[16:19], v10 offset:3584
	v_add_f32_dpp v78, v65, v64 quad_perm:[1,0,3,2] row_mask:0xf bank_mask:0xf bound_ctrl:1
	ds_read_b128 v[20:23], v10 offset:11776
	ds_read_b128 v[24:27], v10 offset:19968
	v_add_f32_dpp v79, v78, v78 quad_perm:[3,2,1,0] row_mask:0xf bank_mask:0xf bound_ctrl:1
	ds_read_b128 v[28:31], v10 offset:28160
	ds_read_b128 v[32:35], v10 offset:36352
	v_add_f32_dpp v80, v79, v79 row_half_mirror row_mask:0xf bank_mask:0xf bound_ctrl:1
	ds_read_b32 v36, v11 offset:42752
	ds_read_b32 v37, v12 offset:42752
	v_add_f32_dpp v76, v80, v80 row_mirror row_mask:0xf bank_mask:0xf bound_ctrl:1
	ds_read_b64 v[38:39], v13 offset:45168
	v_pk_mul_f32 v[68:69], v[60:61], v[52:53] op_sel_hi:[1,0]
	v_mov_b32_dpp v77, v76 quad_perm:[1,0,3,2] row_mask:0xf bank_mask:0xf bound_ctrl:1
	v_pk_mul_f32 v[70:71], v[60:61], v[52:53] op_sel:[0,1] op_sel_hi:[1,1]
	v_pk_mul_f32 v[72:73], v[60:61], v[54:55] op_sel_hi:[1,0]
	v_pk_mul_f32 v[74:75], v[60:61], v[54:55] op_sel:[0,1] op_sel_hi:[1,1]
	v_pk_fma_f32 v[68:69], v[2:3], v[48:49], v[68:69] op_sel_hi:[1,0,1]
	v_pk_fma_f32 v[70:71], v[4:5], v[48:49], v[70:71] op_sel:[0,1,0] op_sel_hi:[1,1,1]
	v_pk_fma_f32 v[72:73], v[6:7], v[50:51], v[72:73] op_sel_hi:[1,0,1]
	v_pk_fma_f32 v[74:75], v[8:9], v[50:51], v[74:75] op_sel:[0,1,0] op_sel_hi:[1,1,1]
	v_pk_fma_f32 v[2:3], v[56:57], v[76:77], v[68:69] op_sel_hi:[0,1,1] neg_lo:[1,0,0] neg_hi:[1,0,0]
	v_pk_fma_f32 v[4:5], v[56:57], v[76:77], v[70:71] op_sel:[1,0,0] op_sel_hi:[1,1,1] neg_lo:[1,0,0] neg_hi:[1,0,0]
	v_mul_f32_e32 v83, v60, v62
	v_add_f32_dpp v81, v67, v66 quad_perm:[1,0,3,2] row_mask:0xf bank_mask:0xf bound_ctrl:1
	v_pk_fma_f32 v[6:7], v[58:59], v[76:77], v[72:73] op_sel_hi:[0,1,1] neg_lo:[1,0,0] neg_hi:[1,0,0]
	v_pk_fma_f32 v[8:9], v[58:59], v[76:77], v[74:75] op_sel:[1,0,0] op_sel_hi:[1,1,1] neg_lo:[1,0,0] neg_hi:[1,0,0]
	v_add_f32_dpp v82, v81, v81 quad_perm:[3,2,1,0] row_mask:0xf bank_mask:0xf bound_ctrl:1
	v_fma_f32 v83, -v76, v63, v83
	v_fmac_f32_e32 v82, 0x3e800000, v83
	ds_write_b32 v14, v82 offset:6656
	s_waitcnt lgkmcnt(1)
	v_pk_mul_f32 v[64:65], v[2:3], v[16:17] op_sel_hi:[1,0]
	v_pk_mul_f32 v[66:67], v[2:3], v[20:21] op_sel_hi:[1,0]
	v_pk_fma_f32 v[64:65], v[4:5], v[16:17], v[64:65] op_sel:[0,1,0] op_sel_hi:[1,1,1]
	v_pk_fma_f32 v[66:67], v[4:5], v[20:21], v[66:67] op_sel:[0,1,0] op_sel_hi:[1,1,1]
	v_pk_fma_f32 v[64:65], v[6:7], v[18:19], v[64:65] op_sel_hi:[1,0,1]
	v_pk_fma_f32 v[66:67], v[6:7], v[22:23], v[66:67] op_sel_hi:[1,0,1]
	v_pk_fma_f32 v[64:65], v[8:9], v[18:19], v[64:65] op_sel:[0,1,0] op_sel_hi:[1,1,1]
	v_pk_fma_f32 v[66:67], v[8:9], v[22:23], v[66:67] op_sel:[0,1,0] op_sel_hi:[1,1,1]
	ds_read_b128 v[40:43], v10 offset:3840
	v_add_f32_dpp v78, v65, v64 quad_perm:[1,0,3,2] row_mask:0xf bank_mask:0xf bound_ctrl:1
	ds_read_b128 v[44:47], v10 offset:12032
	ds_read_b128 v[48:51], v10 offset:20224
	v_add_f32_dpp v79, v78, v78 quad_perm:[3,2,1,0] row_mask:0xf bank_mask:0xf bound_ctrl:1
	ds_read_b128 v[52:55], v10 offset:28416
	ds_read_b128 v[56:59], v10 offset:36608
	v_add_f32_dpp v80, v79, v79 row_half_mirror row_mask:0xf bank_mask:0xf bound_ctrl:1
	ds_read_b32 v60, v11 offset:42880
	ds_read_b32 v61, v12 offset:42880
	v_add_f32_dpp v76, v80, v80 row_mirror row_mask:0xf bank_mask:0xf bound_ctrl:1
	ds_read_b64 v[62:63], v13 offset:45176
	v_pk_mul_f32 v[68:69], v[36:37], v[28:29] op_sel_hi:[1,0]
	v_mov_b32_dpp v77, v76 quad_perm:[1,0,3,2] row_mask:0xf bank_mask:0xf bound_ctrl:1
	v_pk_mul_f32 v[70:71], v[36:37], v[28:29] op_sel:[0,1] op_sel_hi:[1,1]
	v_pk_mul_f32 v[72:73], v[36:37], v[30:31] op_sel_hi:[1,0]
	v_pk_mul_f32 v[74:75], v[36:37], v[30:31] op_sel:[0,1] op_sel_hi:[1,1]
	v_pk_fma_f32 v[68:69], v[2:3], v[24:25], v[68:69] op_sel_hi:[1,0,1]
	v_pk_fma_f32 v[70:71], v[4:5], v[24:25], v[70:71] op_sel:[0,1,0] op_sel_hi:[1,1,1]
	v_pk_fma_f32 v[72:73], v[6:7], v[26:27], v[72:73] op_sel_hi:[1,0,1]
	v_pk_fma_f32 v[74:75], v[8:9], v[26:27], v[74:75] op_sel:[0,1,0] op_sel_hi:[1,1,1]
	v_pk_fma_f32 v[2:3], v[32:33], v[76:77], v[68:69] op_sel_hi:[0,1,1] neg_lo:[1,0,0] neg_hi:[1,0,0]
	v_pk_fma_f32 v[4:5], v[32:33], v[76:77], v[70:71] op_sel:[1,0,0] op_sel_hi:[1,1,1] neg_lo:[1,0,0] neg_hi:[1,0,0]
	v_mul_f32_e32 v83, v36, v38
	v_add_f32_dpp v81, v67, v66 quad_perm:[1,0,3,2] row_mask:0xf bank_mask:0xf bound_ctrl:1
	v_pk_fma_f32 v[6:7], v[34:35], v[76:77], v[72:73] op_sel_hi:[0,1,1] neg_lo:[1,0,0] neg_hi:[1,0,0]
	v_pk_fma_f32 v[8:9], v[34:35], v[76:77], v[74:75] op_sel:[1,0,0] op_sel_hi:[1,1,1] neg_lo:[1,0,0] neg_hi:[1,0,0]
	v_add_f32_dpp v82, v81, v81 quad_perm:[3,2,1,0] row_mask:0xf bank_mask:0xf bound_ctrl:1
	v_fma_f32 v83, -v76, v39, v83
	v_fmac_f32_e32 v82, 0x3e800000, v83
	ds_write_b32 v14, v82 offset:7168
	s_waitcnt lgkmcnt(1)
; #define LAS __attribute__((address_space(3)))
; template <int CTRL> __device__ __forceinline__ float dppf(float x) { return __builtin_bit_cast(float, __builtin_amdgcn_mov_dpp(__builtin_bit_cast(int, x), CTRL, 0xf, 0xf, true)); }
; __device__ __forceinline__ float sum16(float x) { x = sum8(x); x += dppf<0x140>(x); return x; }
; __device__ __forceinline__ void rwkv_item(LAS unsigned char* lds, int l, const bf16_t* PROJ, const bf16_t* LO, bf16_t* YR, float* BON, int b, int h, int qv) {
;     ...
;             for (int t = 0; t < CH; ++t) {
;                 const int tn = (t + 1) & (CH - 1);
;                 const LAS float* pn = pk + tn * 64;
;                 const f32x4 nkk = *(const LAS f32x4*)(pn), nwr = *(const LAS f32x4*)(pn + 2048), nw = *(const LAS f32x4*)(pn + 4096), nk = *(const LAS f32x4*)(pn + 6144), na = *(const LAS f32x4*)(pn + 8192);
;                 const float nv0 = pv[tn * 32], nv1 = pv[tn * 32 + 4]; const f32x2 nsc = *(const LAS f32x2*)(ps + 2 * tn);
;                 float sa[2], yp[2];
; #pragma unroll
;                 for (int c = 0; c < 2; ++c) { const f32x2 pa = S23[c] * kk4.hi + S01[c] * kk4.lo, pb = S23[c] * wr4.hi + S01[c] * wr4.lo; sa[c] = pa.x + pa.y; yp[c] = pb.x + pb.y; }
; #pragma unroll
;                 for (int c = 0; c < 2; ++c) { sa[c] = sum16(sa[c]); yp[c] += dppf<0xB1>(yp[c]); yp[c] += dppf<0x4E>(yp[c]); }
; #pragma unroll
;                 for (int c = 0; c < 2; ++c) {
;                     S01[c] = S01[c] * w4.lo + (k4.lo * vv[c] - a4.lo * sa[c]);
;                     S23[c] = S23[c] * w4.hi + (k4.hi * vv[c] - a4.hi * sa[c]);
;                     py[(t * 32 + 4 * c) * 4] = yp[c] + 0.25f * (vv[c] * sc.x - sa[c] * sc.y);
;                 }
;                 kk4 = nkk; wr4 = nwr; w4 = nw; k4 = nk; a4 = na; vv[0] = nv0; vv[1] = nv1; sc = nsc;
;             }
	v_pk_mul_f32 v[64:65], v[2:3], v[40:41] op_sel_hi:[1,0]
	v_pk_mul_f32 v[66:67], v[2:3], v[44:45] op_sel_hi:[1,0]
	v_pk_fma_f32 v[64:65], v[4:5], v[40:41], v[64:65] op_sel:[0,1,0] op_sel_hi:[1,1,1]
	v_pk_fma_f32 v[66:67], v[4:5], v[44:45], v[66:67] op_sel:[0,1,0] op_sel_hi:[1,1,1]
	v_pk_fma_f32 v[64:65], v[6:7], v[42:43], v[64:65] op_sel_hi:[1,0,1]
	v_pk_fma_f32 v[66:67], v[6:7], v[46:47], v[66:67] op_sel_hi:[1,0,1]
	v_pk_fma_f32 v[64:65], v[8:9], v[42:43], v[64:65] op_sel:[0,1,0] op_sel_hi:[1,1,1]
	v_pk_fma_f32 v[66:67], v[8:9], v[46:47], v[66:67] op_sel:[0,1,0] op_sel_hi:[1,1,1]
	ds_read_b128 v[16:19], v10 offset:4096
	v_add_f32_dpp v78, v65, v64 quad_perm:[1,0,3,2] row_mask:0xf bank_mask:0xf bound_ctrl:1
	ds_read_b128 v[20:23], v10 offset:12288
	ds_read_b128 v[24:27], v10 offset:20480
	v_add_f32_dpp v79, v78, v78 quad_perm:[3,2,1,0] row_mask:0xf bank_mask:0xf bound_ctrl:1
	ds_read_b128 v[28:31], v10 offset:28672
	ds_read_b128 v[32:35], v10 offset:36864
	v_add_f32_dpp v80, v79, v79 row_half_mirror row_mask:0xf bank_mask:0xf bound_ctrl:1
	ds_read_b32 v36, v11 offset:43008
	ds_read_b32 v37, v12 offset:43008
	v_add_f32_dpp v76, v80, v80 row_mirror row_mask:0xf bank_mask:0xf bound_ctrl:1
	ds_read_b64 v[38:39], v13 offset:45184
	v_pk_mul_f32 v[68:69], v[60:61], v[52:53] op_sel_hi:[1,0]
	v_mov_b32_dpp v77, v76 quad_perm:[1,0,3,2] row_mask:0xf bank_mask:0xf bound_ctrl:1
	v_pk_mul_f32 v[70:71], v[60:61], v[52:53] op_sel:[0,1] op_sel_hi:[1,1]
	v_pk_mul_f32 v[72:73], v[60:61], v[54:55] op_sel_hi:[1,0]
	v_pk_mul_f32 v[74:75], v[60:61], v[54:55] op_sel:[0,1] op_sel_hi:[1,1]
	v_pk_fma_f32 v[68:69], v[2:3], v[48:49], v[68:69] op_sel_hi:[1,0,1]
	v_pk_fma_f32 v[70:71], v[4:5], v[48:49], v[70:71] op_sel:[0,1,0] op_sel_hi:[1,1,1]
	v_pk_fma_f32 v[72:73], v[6:7], v[50:51], v[72:73] op_sel_hi:[1,0,1]
	v_pk_fma_f32 v[74:75], v[8:9], v[50:51], v[74:75] op_sel:[0,1,0] op_sel_hi:[1,1,1]
	v_pk_fma_f32 v[2:3], v[56:57], v[76:77], v[68:69] op_sel_hi:[0,1,1] neg_lo:[1,0,0] neg_hi:[1,0,0]
	v_pk_fma_f32 v[4:5], v[56:57], v[76:77], v[70:71] op_sel:[1,0,0] op_sel_hi:[1,1,1] neg_lo:[1,0,0] neg_hi:[1,0,0]
	v_mul_f32_e32 v83, v60, v62
	v_add_f32_dpp v81, v67, v66 quad_perm:[1,0,3,2] row_mask:0xf bank_mask:0xf bound_ctrl:1
	v_pk_fma_f32 v[6:7], v[58:59], v[76:77], v[72:73] op_sel_hi:[0,1,1] neg_lo:[1,0,0] neg_hi:[1,0,0]
	v_pk_fma_f32 v[8:9], v[58:59], v[76:77], v[74:75] op_sel:[1,0,0] op_sel_hi:[1,1,1] neg_lo:[1,0,0] neg_hi:[1,0,0]
	v_add_f32_dpp v82, v81, v81 quad_perm:[3,2,1,0] row_mask:0xf bank_mask:0xf bound_ctrl:1
	v_fma_f32 v83, -v76, v63, v83
	v_fmac_f32_e32 v82, 0x3e800000, v83
	ds_write_b32 v14, v82 offset:7680
	s_waitcnt lgkmcnt(1)
	v_pk_mul_f32 v[64:65], v[2:3], v[16:17] op_sel_hi:[1,0]
	v_pk_mul_f32 v[66:67], v[2:3], v[20:21] op_sel_hi:[1,0]
	v_pk_fma_f32 v[64:65], v[4:5], v[16:17], v[64:65] op_sel:[0,1,0] op_sel_hi:[1,1,1]
	v_pk_fma_f32 v[66:67], v[4:5], v[20:21], v[66:67] op_sel:[0,1,0] op_sel_hi:[1,1,1]
	v_pk_fma_f32 v[64:65], v[6:7], v[18:19], v[64:65] op_sel_hi:[1,0,1]
	v_pk_fma_f32 v[66:67], v[6:7], v[22:23], v[66:67] op_sel_hi:[1,0,1]
	v_pk_fma_f32 v[64:65], v[8:9], v[18:19], v[64:65] op_sel:[0,1,0] op_sel_hi:[1,1,1]
	v_pk_fma_f32 v[66:67], v[8:9], v[22:23], v[66:67] op_sel:[0,1,0] op_sel_hi:[1,1,1]
	ds_read_b128 v[40:43], v10 offset:4352
	v_add_f32_dpp v78, v65, v64 quad_perm:[1,0,3,2] row_mask:0xf bank_mask:0xf bound_ctrl:1
	ds_read_b128 v[44:47], v10 offset:12544
	ds_read_b128 v[48:51], v10 offset:20736
	v_add_f32_dpp v79, v78, v78 quad_perm:[3,2,1,0] row_mask:0xf bank_mask:0xf bound_ctrl:1
	ds_read_b128 v[52:55], v10 offset:28928
	ds_read_b128 v[56:59], v10 offset:37120
	v_add_f32_dpp v80, v79, v79 row_half_mirror row_mask:0xf bank_mask:0xf bound_ctrl:1
	ds_read_b32 v60, v11 offset:43136
	ds_read_b32 v61, v12 offset:43136
	v_add_f32_dpp v76, v80, v80 row_mirror row_mask:0xf bank_mask:0xf bound_ctrl:1
	ds_read_b64 v[62:63], v13 offset:45192
	v_pk_mul_f32 v[68:69], v[36:37], v[28:29] op_sel_hi:[1,0]
	v_mov_b32_dpp v77, v76 quad_perm:[1,0,3,2] row_mask:0xf bank_mask:0xf bound_ctrl:1
	v_pk_mul_f32 v[70:71], v[36:37], v[28:29] op_sel:[0,1] op_sel_hi:[1,1]
	v_pk_mul_f32 v[72:73], v[36:37], v[30:31] op_sel_hi:[1,0]
	v_pk_mul_f32 v[74:75], v[36:37], v[30:31] op_sel:[0,1] op_sel_hi:[1,1]
	v_pk_fma_f32 v[68:69], v[2:3], v[24:25], v[68:69] op_sel_hi:[1,0,1]
	v_pk_fma_f32 v[70:71], v[4:5], v[24:25], v[70:71] op_sel:[0,1,0] op_sel_hi:[1,1,1]
	v_pk_fma_f32 v[72:73], v[6:7], v[26:27], v[72:73] op_sel_hi:[1,0,1]
	v_pk_fma_f32 v[74:75], v[8:9], v[26:27], v[74:75] op_sel:[0,1,0] op_sel_hi:[1,1,1]
	v_pk_fma_f32 v[2:3], v[32:33], v[76:77], v[68:69] op_sel_hi:[0,1,1] neg_lo:[1,0,0] neg_hi:[1,0,0]
	v_pk_fma_f32 v[4:5], v[32:33], v[76:77], v[70:71] op_sel:[1,0,0] op_sel_hi:[1,1,1] neg_lo:[1,0,0] neg_hi:[1,0,0]
	v_mul_f32_e32 v83, v36, v38
	v_add_f32_dpp v81, v67, v66 quad_perm:[1,0,3,2] row_mask:0xf bank_mask:0xf bound_ctrl:1
	v_pk_fma_f32 v[6:7], v[34:35], v[76:77], v[72:73] op_sel_hi:[0,1,1] neg_lo:[1,0,0] neg_hi:[1,0,0]
	v_pk_fma_f32 v[8:9], v[34:35], v[76:77], v[74:75] op_sel:[1,0,0] op_sel_hi:[1,1,1] neg_lo:[1,0,0] neg_hi:[1,0,0]
	v_add_f32_dpp v82, v81, v81 quad_perm:[3,2,1,0] row_mask:0xf bank_mask:0xf bound_ctrl:1
	v_fma_f32 v83, -v76, v39, v83
	v_fmac_f32_e32 v82, 0x3e800000, v83
	ds_write_b32 v14, v82 offset:8192
	s_waitcnt lgkmcnt(1)
; #define LAS __attribute__((address_space(3)))
; template <int CTRL> __device__ __forceinline__ float dppf(float x) { return __builtin_bit_cast(float, __builtin_amdgcn_mov_dpp(__builtin_bit_cast(int, x), CTRL, 0xf, 0xf, true)); }
; __device__ __forceinline__ float sum16(float x) { x = sum8(x); x += dppf<0x140>(x); return x; }
; __device__ __forceinline__ void rwkv_item(LAS unsigned char* lds, int l, const bf16_t* PROJ, const bf16_t* LO, bf16_t* YR, float* BON, int b, int h, int qv) {
;     ...
;             for (int t = 0; t < CH; ++t) {
;                 const int tn = (t + 1) & (CH - 1);
;                 const LAS float* pn = pk + tn * 64;
;                 const f32x4 nkk = *(const LAS f32x4*)(pn), nwr = *(const LAS f32x4*)(pn + 2048), nw = *(const LAS f32x4*)(pn + 4096), nk = *(const LAS f32x4*)(pn + 6144), na = *(const LAS f32x4*)(pn + 8192);
;                 const float nv0 = pv[tn * 32], nv1 = pv[tn * 32 + 4]; const f32x2 nsc = *(const LAS f32x2*)(ps + 2 * tn);
;                 float sa[2], yp[2];
; #pragma unroll
;                 for (int c = 0; c < 2; ++c) { const f32x2 pa = S23[c] * kk4.hi + S01[c] * kk4.lo, pb = S23[c] * wr4.hi + S01[c] * wr4.lo; sa[c] = pa.x + pa.y; yp[c] = pb.x + pb.y; }
; #pragma unroll
;                 for (int c = 0; c < 2; ++c) { sa[c] = sum16(sa[c]); yp[c] += dppf<0xB1>(yp[c]); yp[c] += dppf<0x4E>(yp[c]); }
; #pragma unroll
;                 for (int c = 0; c < 2; ++c) {
;                     S01[c] = S01[c] * w4.lo + (k4.lo * vv[c] - a4.lo * sa[c]);
;                     S23[c] = S23[c] * w4.hi + (k4.hi * vv[c] - a4.hi * sa[c]);
;                     py[(t * 32 + 4 * c) * 4] = yp[c] + 0.25f * (vv[c] * sc.x - sa[c] * sc.y);
;                 }
;                 kk4 = nkk; wr4 = nwr; w4 = nw; k4 = nk; a4 = na; vv[0] = nv0; vv[1] = nv1; sc = nsc;
;             }
	v_pk_mul_f32 v[64:65], v[2:3], v[40:41] op_sel_hi:[1,0]
	v_pk_mul_f32 v[66:67], v[2:3], v[44:45] op_sel_hi:[1,0]
	v_pk_fma_f32 v[64:65], v[4:5], v[40:41], v[64:65] op_sel:[0,1,0] op_sel_hi:[1,1,1]
	v_pk_fma_f32 v[66:67], v[4:5], v[44:45], v[66:67] op_sel:[0,1,0] op_sel_hi:[1,1,1]
	v_pk_fma_f32 v[64:65], v[6:7], v[42:43], v[64:65] op_sel_hi:[1,0,1]
	v_pk_fma_f32 v[66:67], v[6:7], v[46:47], v[66:67] op_sel_hi:[1,0,1]
	v_pk_fma_f32 v[64:65], v[8:9], v[42:43], v[64:65] op_sel:[0,1,0] op_sel_hi:[1,1,1]
	v_pk_fma_f32 v[66:67], v[8:9], v[46:47], v[66:67] op_sel:[0,1,0] op_sel_hi:[1,1,1]
	ds_read_b128 v[16:19], v10 offset:4608
	v_add_f32_dpp v78, v65, v64 quad_perm:[1,0,3,2] row_mask:0xf bank_mask:0xf bound_ctrl:1
	ds_read_b128 v[20:23], v10 offset:12800
	ds_read_b128 v[24:27], v10 offset:20992
	v_add_f32_dpp v79, v78, v78 quad_perm:[3,2,1,0] row_mask:0xf bank_mask:0xf bound_ctrl:1
	ds_read_b128 v[28:31], v10 offset:29184
	ds_read_b128 v[32:35], v10 offset:37376
	v_add_f32_dpp v80, v79, v79 row_half_mirror row_mask:0xf bank_mask:0xf bound_ctrl:1
	ds_read_b32 v36, v11 offset:43264
	ds_read_b32 v37, v12 offset:43264
	v_add_f32_dpp v76, v80, v80 row_mirror row_mask:0xf bank_mask:0xf bound_ctrl:1
	ds_read_b64 v[38:39], v13 offset:45200
	v_pk_mul_f32 v[68:69], v[60:61], v[52:53] op_sel_hi:[1,0]
	v_mov_b32_dpp v77, v76 quad_perm:[1,0,3,2] row_mask:0xf bank_mask:0xf bound_ctrl:1
	v_pk_mul_f32 v[70:71], v[60:61], v[52:53] op_sel:[0,1] op_sel_hi:[1,1]
	v_pk_mul_f32 v[72:73], v[60:61], v[54:55] op_sel_hi:[1,0]
	v_pk_mul_f32 v[74:75], v[60:61], v[54:55] op_sel:[0,1] op_sel_hi:[1,1]
	v_pk_fma_f32 v[68:69], v[2:3], v[48:49], v[68:69] op_sel_hi:[1,0,1]
	v_pk_fma_f32 v[70:71], v[4:5], v[48:49], v[70:71] op_sel:[0,1,0] op_sel_hi:[1,1,1]
	v_pk_fma_f32 v[72:73], v[6:7], v[50:51], v[72:73] op_sel_hi:[1,0,1]
	v_pk_fma_f32 v[74:75], v[8:9], v[50:51], v[74:75] op_sel:[0,1,0] op_sel_hi:[1,1,1]
	v_pk_fma_f32 v[2:3], v[56:57], v[76:77], v[68:69] op_sel_hi:[0,1,1] neg_lo:[1,0,0] neg_hi:[1,0,0]
	v_pk_fma_f32 v[4:5], v[56:57], v[76:77], v[70:71] op_sel:[1,0,0] op_sel_hi:[1,1,1] neg_lo:[1,0,0] neg_hi:[1,0,0]
	v_mul_f32_e32 v83, v60, v62
	v_add_f32_dpp v81, v67, v66 quad_perm:[1,0,3,2] row_mask:0xf bank_mask:0xf bound_ctrl:1
	v_pk_fma_f32 v[6:7], v[58:59], v[76:77], v[72:73] op_sel_hi:[0,1,1] neg_lo:[1,0,0] neg_hi:[1,0,0]
	v_pk_fma_f32 v[8:9], v[58:59], v[76:77], v[74:75] op_sel:[1,0,0] op_sel_hi:[1,1,1] neg_lo:[1,0,0] neg_hi:[1,0,0]
	v_add_f32_dpp v82, v81, v81 quad_perm:[3,2,1,0] row_mask:0xf bank_mask:0xf bound_ctrl:1
	v_fma_f32 v83, -v76, v63, v83
	v_fmac_f32_e32 v82, 0x3e800000, v83
	ds_write_b32 v14, v82 offset:8704
	s_waitcnt lgkmcnt(1)
	v_pk_mul_f32 v[64:65], v[2:3], v[16:17] op_sel_hi:[1,0]
	v_pk_mul_f32 v[66:67], v[2:3], v[20:21] op_sel_hi:[1,0]
	v_pk_fma_f32 v[64:65], v[4:5], v[16:17], v[64:65] op_sel:[0,1,0] op_sel_hi:[1,1,1]
	v_pk_fma_f32 v[66:67], v[4:5], v[20:21], v[66:67] op_sel:[0,1,0] op_sel_hi:[1,1,1]
	v_pk_fma_f32 v[64:65], v[6:7], v[18:19], v[64:65] op_sel_hi:[1,0,1]
	v_pk_fma_f32 v[66:67], v[6:7], v[22:23], v[66:67] op_sel_hi:[1,0,1]
	v_pk_fma_f32 v[64:65], v[8:9], v[18:19], v[64:65] op_sel:[0,1,0] op_sel_hi:[1,1,1]
	v_pk_fma_f32 v[66:67], v[8:9], v[22:23], v[66:67] op_sel:[0,1,0] op_sel_hi:[1,1,1]
	ds_read_b128 v[40:43], v10 offset:4864
	v_add_f32_dpp v78, v65, v64 quad_perm:[1,0,3,2] row_mask:0xf bank_mask:0xf bound_ctrl:1
	ds_read_b128 v[44:47], v10 offset:13056
	ds_read_b128 v[48:51], v10 offset:21248
	v_add_f32_dpp v79, v78, v78 quad_perm:[3,2,1,0] row_mask:0xf bank_mask:0xf bound_ctrl:1
	ds_read_b128 v[52:55], v10 offset:29440
	ds_read_b128 v[56:59], v10 offset:37632
	v_add_f32_dpp v80, v79, v79 row_half_mirror row_mask:0xf bank_mask:0xf bound_ctrl:1
	ds_read_b32 v60, v11 offset:43392
	ds_read_b32 v61, v12 offset:43392
	v_add_f32_dpp v76, v80, v80 row_mirror row_mask:0xf bank_mask:0xf bound_ctrl:1
	ds_read_b64 v[62:63], v13 offset:45208
	v_pk_mul_f32 v[68:69], v[36:37], v[28:29] op_sel_hi:[1,0]
	v_mov_b32_dpp v77, v76 quad_perm:[1,0,3,2] row_mask:0xf bank_mask:0xf bound_ctrl:1
	v_pk_mul_f32 v[70:71], v[36:37], v[28:29] op_sel:[0,1] op_sel_hi:[1,1]
	v_pk_mul_f32 v[72:73], v[36:37], v[30:31] op_sel_hi:[1,0]
	v_pk_mul_f32 v[74:75], v[36:37], v[30:31] op_sel:[0,1] op_sel_hi:[1,1]
	v_pk_fma_f32 v[68:69], v[2:3], v[24:25], v[68:69] op_sel_hi:[1,0,1]
	v_pk_fma_f32 v[70:71], v[4:5], v[24:25], v[70:71] op_sel:[0,1,0] op_sel_hi:[1,1,1]
	v_pk_fma_f32 v[72:73], v[6:7], v[26:27], v[72:73] op_sel_hi:[1,0,1]
	v_pk_fma_f32 v[74:75], v[8:9], v[26:27], v[74:75] op_sel:[0,1,0] op_sel_hi:[1,1,1]
	v_pk_fma_f32 v[2:3], v[32:33], v[76:77], v[68:69] op_sel_hi:[0,1,1] neg_lo:[1,0,0] neg_hi:[1,0,0]
	v_pk_fma_f32 v[4:5], v[32:33], v[76:77], v[70:71] op_sel:[1,0,0] op_sel_hi:[1,1,1] neg_lo:[1,0,0] neg_hi:[1,0,0]
	v_mul_f32_e32 v83, v36, v38
	v_add_f32_dpp v81, v67, v66 quad_perm:[1,0,3,2] row_mask:0xf bank_mask:0xf bound_ctrl:1
	v_pk_fma_f32 v[6:7], v[34:35], v[76:77], v[72:73] op_sel_hi:[0,1,1] neg_lo:[1,0,0] neg_hi:[1,0,0]
	v_pk_fma_f32 v[8:9], v[34:35], v[76:77], v[74:75] op_sel:[1,0,0] op_sel_hi:[1,1,1] neg_lo:[1,0,0] neg_hi:[1,0,0]
	v_add_f32_dpp v82, v81, v81 quad_perm:[3,2,1,0] row_mask:0xf bank_mask:0xf bound_ctrl:1
	v_fma_f32 v83, -v76, v39, v83
	v_fmac_f32_e32 v82, 0x3e800000, v83
	ds_write_b32 v14, v82 offset:9216
	s_waitcnt lgkmcnt(1)
; #define LAS __attribute__((address_space(3)))
; template <int CTRL> __device__ __forceinline__ float dppf(float x) { return __builtin_bit_cast(float, __builtin_amdgcn_mov_dpp(__builtin_bit_cast(int, x), CTRL, 0xf, 0xf, true)); }
; __device__ __forceinline__ float sum16(float x) { x = sum8(x); x += dppf<0x140>(x); return x; }
; __device__ __forceinline__ void rwkv_item(LAS unsigned char* lds, int l, const bf16_t* PROJ, const bf16_t* LO, bf16_t* YR, float* BON, int b, int h, int qv) {
;     ...
;             for (int t = 0; t < CH; ++t) {
;                 const int tn = (t + 1) & (CH - 1);
;                 const LAS float* pn = pk + tn * 64;
;                 const f32x4 nkk = *(const LAS f32x4*)(pn), nwr = *(const LAS f32x4*)(pn + 2048), nw = *(const LAS f32x4*)(pn + 4096), nk = *(const LAS f32x4*)(pn + 6144), na = *(const LAS f32x4*)(pn + 8192);
;                 const float nv0 = pv[tn * 32], nv1 = pv[tn * 32 + 4]; const f32x2 nsc = *(const LAS f32x2*)(ps + 2 * tn);
;                 float sa[2], yp[2];
; #pragma unroll
;                 for (int c = 0; c < 2; ++c) { const f32x2 pa = S23[c] * kk4.hi + S01[c] * kk4.lo, pb = S23[c] * wr4.hi + S01[c] * wr4.lo; sa[c] = pa.x + pa.y; yp[c] = pb.x + pb.y; }
; #pragma unroll
;                 for (int c = 0; c < 2; ++c) { sa[c] = sum16(sa[c]); yp[c] += dppf<0xB1>(yp[c]); yp[c] += dppf<0x4E>(yp[c]); }
; #pragma unroll
;                 for (int c = 0; c < 2; ++c) {
;                     S01[c] = S01[c] * w4.lo + (k4.lo * vv[c] - a4.lo * sa[c]);
;                     S23[c] = S23[c] * w4.hi + (k4.hi * vv[c] - a4.hi * sa[c]);
;                     py[(t * 32 + 4 * c) * 4] = yp[c] + 0.25f * (vv[c] * sc.x - sa[c] * sc.y);
;                 }
;                 kk4 = nkk; wr4 = nwr; w4 = nw; k4 = nk; a4 = na; vv[0] = nv0; vv[1] = nv1; sc = nsc;
;             }
	v_pk_mul_f32 v[64:65], v[2:3], v[40:41] op_sel_hi:[1,0]
	v_pk_mul_f32 v[66:67], v[2:3], v[44:45] op_sel_hi:[1,0]
	v_pk_fma_f32 v[64:65], v[4:5], v[40:41], v[64:65] op_sel:[0,1,0] op_sel_hi:[1,1,1]
	v_pk_fma_f32 v[66:67], v[4:5], v[44:45], v[66:67] op_sel:[0,1,0] op_sel_hi:[1,1,1]
	v_pk_fma_f32 v[64:65], v[6:7], v[42:43], v[64:65] op_sel_hi:[1,0,1]
	v_pk_fma_f32 v[66:67], v[6:7], v[46:47], v[66:67] op_sel_hi:[1,0,1]
	v_pk_fma_f32 v[64:65], v[8:9], v[42:43], v[64:65] op_sel:[0,1,0] op_sel_hi:[1,1,1]
	v_pk_fma_f32 v[66:67], v[8:9], v[46:47], v[66:67] op_sel:[0,1,0] op_sel_hi:[1,1,1]
	ds_read_b128 v[16:19], v10 offset:5120
	v_add_f32_dpp v78, v65, v64 quad_perm:[1,0,3,2] row_mask:0xf bank_mask:0xf bound_ctrl:1
	ds_read_b128 v[20:23], v10 offset:13312
	ds_read_b128 v[24:27], v10 offset:21504
	v_add_f32_dpp v79, v78, v78 quad_perm:[3,2,1,0] row_mask:0xf bank_mask:0xf bound_ctrl:1
	ds_read_b128 v[28:31], v10 offset:29696
	ds_read_b128 v[32:35], v10 offset:37888
	v_add_f32_dpp v80, v79, v79 row_half_mirror row_mask:0xf bank_mask:0xf bound_ctrl:1
	ds_read_b32 v36, v11 offset:43520
	ds_read_b32 v37, v12 offset:43520
	v_add_f32_dpp v76, v80, v80 row_mirror row_mask:0xf bank_mask:0xf bound_ctrl:1
	ds_read_b64 v[38:39], v13 offset:45216
	v_pk_mul_f32 v[68:69], v[60:61], v[52:53] op_sel_hi:[1,0]
	v_mov_b32_dpp v77, v76 quad_perm:[1,0,3,2] row_mask:0xf bank_mask:0xf bound_ctrl:1
	v_pk_mul_f32 v[70:71], v[60:61], v[52:53] op_sel:[0,1] op_sel_hi:[1,1]
	v_pk_mul_f32 v[72:73], v[60:61], v[54:55] op_sel_hi:[1,0]
	v_pk_mul_f32 v[74:75], v[60:61], v[54:55] op_sel:[0,1] op_sel_hi:[1,1]
	v_pk_fma_f32 v[68:69], v[2:3], v[48:49], v[68:69] op_sel_hi:[1,0,1]
	v_pk_fma_f32 v[70:71], v[4:5], v[48:49], v[70:71] op_sel:[0,1,0] op_sel_hi:[1,1,1]
	v_pk_fma_f32 v[72:73], v[6:7], v[50:51], v[72:73] op_sel_hi:[1,0,1]
	v_pk_fma_f32 v[74:75], v[8:9], v[50:51], v[74:75] op_sel:[0,1,0] op_sel_hi:[1,1,1]
	v_pk_fma_f32 v[2:3], v[56:57], v[76:77], v[68:69] op_sel_hi:[0,1,1] neg_lo:[1,0,0] neg_hi:[1,0,0]
	v_pk_fma_f32 v[4:5], v[56:57], v[76:77], v[70:71] op_sel:[1,0,0] op_sel_hi:[1,1,1] neg_lo:[1,0,0] neg_hi:[1,0,0]
	v_mul_f32_e32 v83, v60, v62
	v_add_f32_dpp v81, v67, v66 quad_perm:[1,0,3,2] row_mask:0xf bank_mask:0xf bound_ctrl:1
	v_pk_fma_f32 v[6:7], v[58:59], v[76:77], v[72:73] op_sel_hi:[0,1,1] neg_lo:[1,0,0] neg_hi:[1,0,0]
	v_pk_fma_f32 v[8:9], v[58:59], v[76:77], v[74:75] op_sel:[1,0,0] op_sel_hi:[1,1,1] neg_lo:[1,0,0] neg_hi:[1,0,0]
	v_add_f32_dpp v82, v81, v81 quad_perm:[3,2,1,0] row_mask:0xf bank_mask:0xf bound_ctrl:1
	v_fma_f32 v83, -v76, v63, v83
	v_fmac_f32_e32 v82, 0x3e800000, v83
	ds_write_b32 v14, v82 offset:9728
	s_waitcnt lgkmcnt(1)
	v_pk_mul_f32 v[64:65], v[2:3], v[16:17] op_sel_hi:[1,0]
	v_pk_mul_f32 v[66:67], v[2:3], v[20:21] op_sel_hi:[1,0]
	v_pk_fma_f32 v[64:65], v[4:5], v[16:17], v[64:65] op_sel:[0,1,0] op_sel_hi:[1,1,1]
	v_pk_fma_f32 v[66:67], v[4:5], v[20:21], v[66:67] op_sel:[0,1,0] op_sel_hi:[1,1,1]
	v_pk_fma_f32 v[64:65], v[6:7], v[18:19], v[64:65] op_sel_hi:[1,0,1]
	v_pk_fma_f32 v[66:67], v[6:7], v[22:23], v[66:67] op_sel_hi:[1,0,1]
	v_pk_fma_f32 v[64:65], v[8:9], v[18:19], v[64:65] op_sel:[0,1,0] op_sel_hi:[1,1,1]
	v_pk_fma_f32 v[66:67], v[8:9], v[22:23], v[66:67] op_sel:[0,1,0] op_sel_hi:[1,1,1]
	ds_read_b128 v[40:43], v10 offset:5376
	v_add_f32_dpp v78, v65, v64 quad_perm:[1,0,3,2] row_mask:0xf bank_mask:0xf bound_ctrl:1
	ds_read_b128 v[44:47], v10 offset:13568
	ds_read_b128 v[48:51], v10 offset:21760
	v_add_f32_dpp v79, v78, v78 quad_perm:[3,2,1,0] row_mask:0xf bank_mask:0xf bound_ctrl:1
	ds_read_b128 v[52:55], v10 offset:29952
	ds_read_b128 v[56:59], v10 offset:38144
	v_add_f32_dpp v80, v79, v79 row_half_mirror row_mask:0xf bank_mask:0xf bound_ctrl:1
	ds_read_b32 v60, v11 offset:43648
	ds_read_b32 v61, v12 offset:43648
	v_add_f32_dpp v76, v80, v80 row_mirror row_mask:0xf bank_mask:0xf bound_ctrl:1
	ds_read_b64 v[62:63], v13 offset:45224
	v_pk_mul_f32 v[68:69], v[36:37], v[28:29] op_sel_hi:[1,0]
	v_mov_b32_dpp v77, v76 quad_perm:[1,0,3,2] row_mask:0xf bank_mask:0xf bound_ctrl:1
	v_pk_mul_f32 v[70:71], v[36:37], v[28:29] op_sel:[0,1] op_sel_hi:[1,1]
	v_pk_mul_f32 v[72:73], v[36:37], v[30:31] op_sel_hi:[1,0]
	v_pk_mul_f32 v[74:75], v[36:37], v[30:31] op_sel:[0,1] op_sel_hi:[1,1]
	v_pk_fma_f32 v[68:69], v[2:3], v[24:25], v[68:69] op_sel_hi:[1,0,1]
	v_pk_fma_f32 v[70:71], v[4:5], v[24:25], v[70:71] op_sel:[0,1,0] op_sel_hi:[1,1,1]
	v_pk_fma_f32 v[72:73], v[6:7], v[26:27], v[72:73] op_sel_hi:[1,0,1]
	v_pk_fma_f32 v[74:75], v[8:9], v[26:27], v[74:75] op_sel:[0,1,0] op_sel_hi:[1,1,1]
	v_pk_fma_f32 v[2:3], v[32:33], v[76:77], v[68:69] op_sel_hi:[0,1,1] neg_lo:[1,0,0] neg_hi:[1,0,0]
	v_pk_fma_f32 v[4:5], v[32:33], v[76:77], v[70:71] op_sel:[1,0,0] op_sel_hi:[1,1,1] neg_lo:[1,0,0] neg_hi:[1,0,0]
	v_mul_f32_e32 v83, v36, v38
	v_add_f32_dpp v81, v67, v66 quad_perm:[1,0,3,2] row_mask:0xf bank_mask:0xf bound_ctrl:1
	v_pk_fma_f32 v[6:7], v[34:35], v[76:77], v[72:73] op_sel_hi:[0,1,1] neg_lo:[1,0,0] neg_hi:[1,0,0]
	v_pk_fma_f32 v[8:9], v[34:35], v[76:77], v[74:75] op_sel:[1,0,0] op_sel_hi:[1,1,1] neg_lo:[1,0,0] neg_hi:[1,0,0]
	v_add_f32_dpp v82, v81, v81 quad_perm:[3,2,1,0] row_mask:0xf bank_mask:0xf bound_ctrl:1
	v_fma_f32 v83, -v76, v39, v83
	v_fmac_f32_e32 v82, 0x3e800000, v83
	ds_write_b32 v14, v82 offset:10240
	s_waitcnt lgkmcnt(1)
; #define LAS __attribute__((address_space(3)))
; template <int CTRL> __device__ __forceinline__ float dppf(float x) { return __builtin_bit_cast(float, __builtin_amdgcn_mov_dpp(__builtin_bit_cast(int, x), CTRL, 0xf, 0xf, true)); }
; __device__ __forceinline__ float sum16(float x) { x = sum8(x); x += dppf<0x140>(x); return x; }
; __device__ __forceinline__ void rwkv_item(LAS unsigned char* lds, int l, const bf16_t* PROJ, const bf16_t* LO, bf16_t* YR, float* BON, int b, int h, int qv) {
;     ...
;             for (int t = 0; t < CH; ++t) {
;                 const int tn = (t + 1) & (CH - 1);
;                 const LAS float* pn = pk + tn * 64;
;                 const f32x4 nkk = *(const LAS f32x4*)(pn), nwr = *(const LAS f32x4*)(pn + 2048), nw = *(const LAS f32x4*)(pn + 4096), nk = *(const LAS f32x4*)(pn + 6144), na = *(const LAS f32x4*)(pn + 8192);
;                 const float nv0 = pv[tn * 32], nv1 = pv[tn * 32 + 4]; const f32x2 nsc = *(const LAS f32x2*)(ps + 2 * tn);
;                 float sa[2], yp[2];
; #pragma unroll
;                 for (int c = 0; c < 2; ++c) { const f32x2 pa = S23[c] * kk4.hi + S01[c] * kk4.lo, pb = S23[c] * wr4.hi + S01[c] * wr4.lo; sa[c] = pa.x + pa.y; yp[c] = pb.x + pb.y; }
; #pragma unroll
;                 for (int c = 0; c < 2; ++c) { sa[c] = sum16(sa[c]); yp[c] += dppf<0xB1>(yp[c]); yp[c] += dppf<0x4E>(yp[c]); }
; #pragma unroll
;                 for (int c = 0; c < 2; ++c) {
;                     S01[c] = S01[c] * w4.lo + (k4.lo * vv[c] - a4.lo * sa[c]);
;                     S23[c] = S23[c] * w4.hi + (k4.hi * vv[c] - a4.hi * sa[c]);
;                     py[(t * 32 + 4 * c) * 4] = yp[c] + 0.25f * (vv[c] * sc.x - sa[c] * sc.y);
;                 }
;                 kk4 = nkk; wr4 = nwr; w4 = nw; k4 = nk; a4 = na; vv[0] = nv0; vv[1] = nv1; sc = nsc;
	v_pk_mul_f32 v[64:65], v[2:3], v[40:41] op_sel_hi:[1,0]
	v_pk_mul_f32 v[66:67], v[2:3], v[44:45] op_sel_hi:[1,0]
	v_pk_fma_f32 v[64:65], v[4:5], v[40:41], v[64:65] op_sel:[0,1,0] op_sel_hi:[1,1,1]
	v_pk_fma_f32 v[66:67], v[4:5], v[44:45], v[66:67] op_sel:[0,1,0] op_sel_hi:[1,1,1]
	v_pk_fma_f32 v[64:65], v[6:7], v[42:43], v[64:65] op_sel_hi:[1,0,1]
	v_pk_fma_f32 v[66:67], v[6:7], v[46:47], v[66:67] op_sel_hi:[1,0,1]
	v_pk_fma_f32 v[64:65], v[8:9], v[42:43], v[64:65] op_sel:[0,1,0] op_sel_hi:[1,1,1]
	v_pk_fma_f32 v[66:67], v[8:9], v[46:47], v[66:67] op_sel:[0,1,0] op_sel_hi:[1,1,1]
	ds_read_b128 v[16:19], v10 offset:5632
	v_add_f32_dpp v78, v65, v64 quad_perm:[1,0,3,2] row_mask:0xf bank_mask:0xf bound_ctrl:1
	ds_read_b128 v[20:23], v10 offset:13824
	ds_read_b128 v[24:27], v10 offset:22016
	v_add_f32_dpp v79, v78, v78 quad_perm:[3,2,1,0] row_mask:0xf bank_mask:0xf bound_ctrl:1
	ds_read_b128 v[28:31], v10 offset:30208
	ds_read_b128 v[32:35], v10 offset:38400
	v_add_f32_dpp v80, v79, v79 row_half_mirror row_mask:0xf bank_mask:0xf bound_ctrl:1
	ds_read_b32 v36, v11 offset:43776
	ds_read_b32 v37, v12 offset:43776
	v_add_f32_dpp v76, v80, v80 row_mirror row_mask:0xf bank_mask:0xf bound_ctrl:1
	ds_read_b64 v[38:39], v13 offset:45232
	v_pk_mul_f32 v[68:69], v[60:61], v[52:53] op_sel_hi:[1,0]
	v_mov_b32_dpp v77, v76 quad_perm:[1,0,3,2] row_mask:0xf bank_mask:0xf bound_ctrl:1
	v_pk_mul_f32 v[70:71], v[60:61], v[52:53] op_sel:[0,1] op_sel_hi:[1,1]
	v_pk_mul_f32 v[72:73], v[60:61], v[54:55] op_sel_hi:[1,0]
	v_pk_mul_f32 v[74:75], v[60:61], v[54:55] op_sel:[0,1] op_sel_hi:[1,1]
	v_pk_fma_f32 v[68:69], v[2:3], v[48:49], v[68:69] op_sel_hi:[1,0,1]
	v_pk_fma_f32 v[70:71], v[4:5], v[48:49], v[70:71] op_sel:[0,1,0] op_sel_hi:[1,1,1]
	v_pk_fma_f32 v[72:73], v[6:7], v[50:51], v[72:73] op_sel_hi:[1,0,1]
	v_pk_fma_f32 v[74:75], v[8:9], v[50:51], v[74:75] op_sel:[0,1,0] op_sel_hi:[1,1,1]
	v_pk_fma_f32 v[2:3], v[56:57], v[76:77], v[68:69] op_sel_hi:[0,1,1] neg_lo:[1,0,0] neg_hi:[1,0,0]
	v_pk_fma_f32 v[4:5], v[56:57], v[76:77], v[70:71] op_sel:[1,0,0] op_sel_hi:[1,1,1] neg_lo:[1,0,0] neg_hi:[1,0,0]
	v_mul_f32_e32 v83, v60, v62
	v_add_f32_dpp v81, v67, v66 quad_perm:[1,0,3,2] row_mask:0xf bank_mask:0xf bound_ctrl:1
	v_pk_fma_f32 v[6:7], v[58:59], v[76:77], v[72:73] op_sel_hi:[0,1,1] neg_lo:[1,0,0] neg_hi:[1,0,0]
	v_pk_fma_f32 v[8:9], v[58:59], v[76:77], v[74:75] op_sel:[1,0,0] op_sel_hi:[1,1,1] neg_lo:[1,0,0] neg_hi:[1,0,0]
	v_add_f32_dpp v82, v81, v81 quad_perm:[3,2,1,0] row_mask:0xf bank_mask:0xf bound_ctrl:1
	v_fma_f32 v83, -v76, v63, v83
	v_fmac_f32_e32 v82, 0x3e800000, v83
	ds_write_b32 v14, v82 offset:10752
	s_waitcnt lgkmcnt(1)
	v_pk_mul_f32 v[64:65], v[2:3], v[16:17] op_sel_hi:[1,0]
	v_pk_mul_f32 v[66:67], v[2:3], v[20:21] op_sel_hi:[1,0]
	v_pk_fma_f32 v[64:65], v[4:5], v[16:17], v[64:65] op_sel:[0,1,0] op_sel_hi:[1,1,1]
	v_pk_fma_f32 v[66:67], v[4:5], v[20:21], v[66:67] op_sel:[0,1,0] op_sel_hi:[1,1,1]
	v_pk_fma_f32 v[64:65], v[6:7], v[18:19], v[64:65] op_sel_hi:[1,0,1]
	v_pk_fma_f32 v[66:67], v[6:7], v[22:23], v[66:67] op_sel_hi:[1,0,1]
	v_pk_fma_f32 v[64:65], v[8:9], v[18:19], v[64:65] op_sel:[0,1,0] op_sel_hi:[1,1,1]
	v_pk_fma_f32 v[66:67], v[8:9], v[22:23], v[66:67] op_sel:[0,1,0] op_sel_hi:[1,1,1]
	ds_read_b128 v[40:43], v10 offset:5888
	v_add_f32_dpp v78, v65, v64 quad_perm:[1,0,3,2] row_mask:0xf bank_mask:0xf bound_ctrl:1
	ds_read_b128 v[44:47], v10 offset:14080
	ds_read_b128 v[48:51], v10 offset:22272
	v_add_f32_dpp v79, v78, v78 quad_perm:[3,2,1,0] row_mask:0xf bank_mask:0xf bound_ctrl:1
	ds_read_b128 v[52:55], v10 offset:30464
	ds_read_b128 v[56:59], v10 offset:38656
	v_add_f32_dpp v80, v79, v79 row_half_mirror row_mask:0xf bank_mask:0xf bound_ctrl:1
	ds_read_b32 v60, v11 offset:43904
	ds_read_b32 v61, v12 offset:43904
	v_add_f32_dpp v76, v80, v80 row_mirror row_mask:0xf bank_mask:0xf bound_ctrl:1
	ds_read_b64 v[62:63], v13 offset:45240
	v_pk_mul_f32 v[68:69], v[36:37], v[28:29] op_sel_hi:[1,0]
	v_mov_b32_dpp v77, v76 quad_perm:[1,0,3,2] row_mask:0xf bank_mask:0xf bound_ctrl:1
	v_pk_mul_f32 v[70:71], v[36:37], v[28:29] op_sel:[0,1] op_sel_hi:[1,1]
	v_pk_mul_f32 v[72:73], v[36:37], v[30:31] op_sel_hi:[1,0]
	v_pk_mul_f32 v[74:75], v[36:37], v[30:31] op_sel:[0,1] op_sel_hi:[1,1]
	v_pk_fma_f32 v[68:69], v[2:3], v[24:25], v[68:69] op_sel_hi:[1,0,1]
	v_pk_fma_f32 v[70:71], v[4:5], v[24:25], v[70:71] op_sel:[0,1,0] op_sel_hi:[1,1,1]
	v_pk_fma_f32 v[72:73], v[6:7], v[26:27], v[72:73] op_sel_hi:[1,0,1]
	v_pk_fma_f32 v[74:75], v[8:9], v[26:27], v[74:75] op_sel:[0,1,0] op_sel_hi:[1,1,1]
	v_pk_fma_f32 v[2:3], v[32:33], v[76:77], v[68:69] op_sel_hi:[0,1,1] neg_lo:[1,0,0] neg_hi:[1,0,0]
	v_pk_fma_f32 v[4:5], v[32:33], v[76:77], v[70:71] op_sel:[1,0,0] op_sel_hi:[1,1,1] neg_lo:[1,0,0] neg_hi:[1,0,0]
	v_mul_f32_e32 v83, v36, v38
	v_add_f32_dpp v81, v67, v66 quad_perm:[1,0,3,2] row_mask:0xf bank_mask:0xf bound_ctrl:1
	v_pk_fma_f32 v[6:7], v[34:35], v[76:77], v[72:73] op_sel_hi:[0,1,1] neg_lo:[1,0,0] neg_hi:[1,0,0]
	v_pk_fma_f32 v[8:9], v[34:35], v[76:77], v[74:75] op_sel:[1,0,0] op_sel_hi:[1,1,1] neg_lo:[1,0,0] neg_hi:[1,0,0]
	v_add_f32_dpp v82, v81, v81 quad_perm:[3,2,1,0] row_mask:0xf bank_mask:0xf bound_ctrl:1
	v_fma_f32 v83, -v76, v39, v83
	v_fmac_f32_e32 v82, 0x3e800000, v83
	ds_write_b32 v14, v82 offset:11264
	s_waitcnt lgkmcnt(1)
; #define LAS __attribute__((address_space(3)))
; template <int CTRL> __device__ __forceinline__ float dppf(float x) { return __builtin_bit_cast(float, __builtin_amdgcn_mov_dpp(__builtin_bit_cast(int, x), CTRL, 0xf, 0xf, true)); }
; __device__ __forceinline__ float sum16(float x) { x = sum8(x); x += dppf<0x140>(x); return x; }
; __device__ __forceinline__ void rwkv_item(LAS unsigned char* lds, int l, const bf16_t* PROJ, const bf16_t* LO, bf16_t* YR, float* BON, int b, int h, int qv) {
;     ...
;             for (int t = 0; t < CH; ++t) {
;                 const int tn = (t + 1) & (CH - 1);
;                 const LAS float* pn = pk + tn * 64;
;                 const f32x4 nkk = *(const LAS f32x4*)(pn), nwr = *(const LAS f32x4*)(pn + 2048), nw = *(const LAS f32x4*)(pn + 4096), nk = *(const LAS f32x4*)(pn + 6144), na = *(const LAS f32x4*)(pn + 8192);
;                 const float nv0 = pv[tn * 32], nv1 = pv[tn * 32 + 4]; const f32x2 nsc = *(const LAS f32x2*)(ps + 2 * tn);
;                 float sa[2], yp[2];
; #pragma unroll
;                 for (int c = 0; c < 2; ++c) { const f32x2 pa = S23[c] * kk4.hi + S01[c] * kk4.lo, pb = S23[c] * wr4.hi + S01[c] * wr4.lo; sa[c] = pa.x + pa.y; yp[c] = pb.x + pb.y; }
; #pragma unroll
;                 for (int c = 0; c < 2; ++c) { sa[c] = sum16(sa[c]); yp[c] += dppf<0xB1>(yp[c]); yp[c] += dppf<0x4E>(yp[c]); }
; #pragma unroll
;                 for (int c = 0; c < 2; ++c) {
;                     S01[c] = S01[c] * w4.lo + (k4.lo * vv[c] - a4.lo * sa[c]);
;                     S23[c] = S23[c] * w4.hi + (k4.hi * vv[c] - a4.hi * sa[c]);
;                     py[(t * 32 + 4 * c) * 4] = yp[c] + 0.25f * (vv[c] * sc.x - sa[c] * sc.y);
;                 }
;                 kk4 = nkk; wr4 = nwr; w4 = nw; k4 = nk; a4 = na; vv[0] = nv0; vv[1] = nv1; sc = nsc;
	v_pk_mul_f32 v[64:65], v[2:3], v[40:41] op_sel_hi:[1,0]
	v_pk_mul_f32 v[66:67], v[2:3], v[44:45] op_sel_hi:[1,0]
	v_pk_fma_f32 v[64:65], v[4:5], v[40:41], v[64:65] op_sel:[0,1,0] op_sel_hi:[1,1,1]
	v_pk_fma_f32 v[66:67], v[4:5], v[44:45], v[66:67] op_sel:[0,1,0] op_sel_hi:[1,1,1]
	v_pk_fma_f32 v[64:65], v[6:7], v[42:43], v[64:65] op_sel_hi:[1,0,1]
	v_pk_fma_f32 v[66:67], v[6:7], v[46:47], v[66:67] op_sel_hi:[1,0,1]
	v_pk_fma_f32 v[64:65], v[8:9], v[42:43], v[64:65] op_sel:[0,1,0] op_sel_hi:[1,1,1]
	v_pk_fma_f32 v[66:67], v[8:9], v[46:47], v[66:67] op_sel:[0,1,0] op_sel_hi:[1,1,1]
	ds_read_b128 v[16:19], v10 offset:6144
	v_add_f32_dpp v78, v65, v64 quad_perm:[1,0,3,2] row_mask:0xf bank_mask:0xf bound_ctrl:1
	ds_read_b128 v[20:23], v10 offset:14336
	ds_read_b128 v[24:27], v10 offset:22528
	v_add_f32_dpp v79, v78, v78 quad_perm:[3,2,1,0] row_mask:0xf bank_mask:0xf bound_ctrl:1
	ds_read_b128 v[28:31], v10 offset:30720
	ds_read_b128 v[32:35], v10 offset:38912
	v_add_f32_dpp v80, v79, v79 row_half_mirror row_mask:0xf bank_mask:0xf bound_ctrl:1
	ds_read_b32 v36, v11 offset:44032
	ds_read_b32 v37, v12 offset:44032
	v_add_f32_dpp v76, v80, v80 row_mirror row_mask:0xf bank_mask:0xf bound_ctrl:1
	ds_read_b64 v[38:39], v13 offset:45248
	v_pk_mul_f32 v[68:69], v[60:61], v[52:53] op_sel_hi:[1,0]
	v_mov_b32_dpp v77, v76 quad_perm:[1,0,3,2] row_mask:0xf bank_mask:0xf bound_ctrl:1
	v_pk_mul_f32 v[70:71], v[60:61], v[52:53] op_sel:[0,1] op_sel_hi:[1,1]
	v_pk_mul_f32 v[72:73], v[60:61], v[54:55] op_sel_hi:[1,0]
	v_pk_mul_f32 v[74:75], v[60:61], v[54:55] op_sel:[0,1] op_sel_hi:[1,1]
	v_pk_fma_f32 v[68:69], v[2:3], v[48:49], v[68:69] op_sel_hi:[1,0,1]
	v_pk_fma_f32 v[70:71], v[4:5], v[48:49], v[70:71] op_sel:[0,1,0] op_sel_hi:[1,1,1]
	v_pk_fma_f32 v[72:73], v[6:7], v[50:51], v[72:73] op_sel_hi:[1,0,1]
	v_pk_fma_f32 v[74:75], v[8:9], v[50:51], v[74:75] op_sel:[0,1,0] op_sel_hi:[1,1,1]
	v_pk_fma_f32 v[2:3], v[56:57], v[76:77], v[68:69] op_sel_hi:[0,1,1] neg_lo:[1,0,0] neg_hi:[1,0,0]
	v_pk_fma_f32 v[4:5], v[56:57], v[76:77], v[70:71] op_sel:[1,0,0] op_sel_hi:[1,1,1] neg_lo:[1,0,0] neg_hi:[1,0,0]
	v_mul_f32_e32 v83, v60, v62
	v_add_f32_dpp v81, v67, v66 quad_perm:[1,0,3,2] row_mask:0xf bank_mask:0xf bound_ctrl:1
	v_pk_fma_f32 v[6:7], v[58:59], v[76:77], v[72:73] op_sel_hi:[0,1,1] neg_lo:[1,0,0] neg_hi:[1,0,0]
	v_pk_fma_f32 v[8:9], v[58:59], v[76:77], v[74:75] op_sel:[1,0,0] op_sel_hi:[1,1,1] neg_lo:[1,0,0] neg_hi:[1,0,0]
	v_add_f32_dpp v82, v81, v81 quad_perm:[3,2,1,0] row_mask:0xf bank_mask:0xf bound_ctrl:1
	v_fma_f32 v83, -v76, v63, v83
	v_fmac_f32_e32 v82, 0x3e800000, v83
	ds_write_b32 v14, v82 offset:11776
	s_waitcnt lgkmcnt(1)
	v_pk_mul_f32 v[64:65], v[2:3], v[16:17] op_sel_hi:[1,0]
	v_pk_mul_f32 v[66:67], v[2:3], v[20:21] op_sel_hi:[1,0]
	v_pk_fma_f32 v[64:65], v[4:5], v[16:17], v[64:65] op_sel:[0,1,0] op_sel_hi:[1,1,1]
	v_pk_fma_f32 v[66:67], v[4:5], v[20:21], v[66:67] op_sel:[0,1,0] op_sel_hi:[1,1,1]
	v_pk_fma_f32 v[64:65], v[6:7], v[18:19], v[64:65] op_sel_hi:[1,0,1]
	v_pk_fma_f32 v[66:67], v[6:7], v[22:23], v[66:67] op_sel_hi:[1,0,1]
	v_pk_fma_f32 v[64:65], v[8:9], v[18:19], v[64:65] op_sel:[0,1,0] op_sel_hi:[1,1,1]
	v_pk_fma_f32 v[66:67], v[8:9], v[22:23], v[66:67] op_sel:[0,1,0] op_sel_hi:[1,1,1]
	ds_read_b128 v[40:43], v10 offset:6400
	v_add_f32_dpp v78, v65, v64 quad_perm:[1,0,3,2] row_mask:0xf bank_mask:0xf bound_ctrl:1
	ds_read_b128 v[44:47], v10 offset:14592
	ds_read_b128 v[48:51], v10 offset:22784
	v_add_f32_dpp v79, v78, v78 quad_perm:[3,2,1,0] row_mask:0xf bank_mask:0xf bound_ctrl:1
	ds_read_b128 v[52:55], v10 offset:30976
	ds_read_b128 v[56:59], v10 offset:39168
	v_add_f32_dpp v80, v79, v79 row_half_mirror row_mask:0xf bank_mask:0xf bound_ctrl:1
	ds_read_b32 v60, v11 offset:44160
	ds_read_b32 v61, v12 offset:44160
	v_add_f32_dpp v76, v80, v80 row_mirror row_mask:0xf bank_mask:0xf bound_ctrl:1
	ds_read_b64 v[62:63], v13 offset:45256
	v_pk_mul_f32 v[68:69], v[36:37], v[28:29] op_sel_hi:[1,0]
	v_mov_b32_dpp v77, v76 quad_perm:[1,0,3,2] row_mask:0xf bank_mask:0xf bound_ctrl:1
	v_pk_mul_f32 v[70:71], v[36:37], v[28:29] op_sel:[0,1] op_sel_hi:[1,1]
	v_pk_mul_f32 v[72:73], v[36:37], v[30:31] op_sel_hi:[1,0]
	v_pk_mul_f32 v[74:75], v[36:37], v[30:31] op_sel:[0,1] op_sel_hi:[1,1]
	v_pk_fma_f32 v[68:69], v[2:3], v[24:25], v[68:69] op_sel_hi:[1,0,1]
	v_pk_fma_f32 v[70:71], v[4:5], v[24:25], v[70:71] op_sel:[0,1,0] op_sel_hi:[1,1,1]
	v_pk_fma_f32 v[72:73], v[6:7], v[26:27], v[72:73] op_sel_hi:[1,0,1]
	v_pk_fma_f32 v[74:75], v[8:9], v[26:27], v[74:75] op_sel:[0,1,0] op_sel_hi:[1,1,1]
	v_pk_fma_f32 v[2:3], v[32:33], v[76:77], v[68:69] op_sel_hi:[0,1,1] neg_lo:[1,0,0] neg_hi:[1,0,0]
	v_pk_fma_f32 v[4:5], v[32:33], v[76:77], v[70:71] op_sel:[1,0,0] op_sel_hi:[1,1,1] neg_lo:[1,0,0] neg_hi:[1,0,0]
	v_mul_f32_e32 v83, v36, v38
	v_add_f32_dpp v81, v67, v66 quad_perm:[1,0,3,2] row_mask:0xf bank_mask:0xf bound_ctrl:1
	v_pk_fma_f32 v[6:7], v[34:35], v[76:77], v[72:73] op_sel_hi:[0,1,1] neg_lo:[1,0,0] neg_hi:[1,0,0]
	v_pk_fma_f32 v[8:9], v[34:35], v[76:77], v[74:75] op_sel:[1,0,0] op_sel_hi:[1,1,1] neg_lo:[1,0,0] neg_hi:[1,0,0]
	v_add_f32_dpp v82, v81, v81 quad_perm:[3,2,1,0] row_mask:0xf bank_mask:0xf bound_ctrl:1
	v_fma_f32 v83, -v76, v39, v83
	v_fmac_f32_e32 v82, 0x3e800000, v83
	ds_write_b32 v14, v82 offset:12288
	s_waitcnt lgkmcnt(1)
; #define LAS __attribute__((address_space(3)))
; template <int CTRL> __device__ __forceinline__ float dppf(float x) { return __builtin_bit_cast(float, __builtin_amdgcn_mov_dpp(__builtin_bit_cast(int, x), CTRL, 0xf, 0xf, true)); }
; __device__ __forceinline__ float sum16(float x) { x = sum8(x); x += dppf<0x140>(x); return x; }
; __device__ __forceinline__ void rwkv_item(LAS unsigned char* lds, int l, const bf16_t* PROJ, const bf16_t* LO, bf16_t* YR, float* BON, int b, int h, int qv) {
;     ...
;             for (int t = 0; t < CH; ++t) {
;                 const int tn = (t + 1) & (CH - 1);
;                 const LAS float* pn = pk + tn * 64;
;                 const f32x4 nkk = *(const LAS f32x4*)(pn), nwr = *(const LAS f32x4*)(pn + 2048), nw = *(const LAS f32x4*)(pn + 4096), nk = *(const LAS f32x4*)(pn + 6144), na = *(const LAS f32x4*)(pn + 8192);
;                 const float nv0 = pv[tn * 32], nv1 = pv[tn * 32 + 4]; const f32x2 nsc = *(const LAS f32x2*)(ps + 2 * tn);
;                 float sa[2], yp[2];
; #pragma unroll
;                 for (int c = 0; c < 2; ++c) { const f32x2 pa = S23[c] * kk4.hi + S01[c] * kk4.lo, pb = S23[c] * wr4.hi + S01[c] * wr4.lo; sa[c] = pa.x + pa.y; yp[c] = pb.x + pb.y; }
; #pragma unroll
;                 for (int c = 0; c < 2; ++c) { sa[c] = sum16(sa[c]); yp[c] += dppf<0xB1>(yp[c]); yp[c] += dppf<0x4E>(yp[c]); }
; #pragma unroll
;                 for (int c = 0; c < 2; ++c) {
;                     S01[c] = S01[c] * w4.lo + (k4.lo * vv[c] - a4.lo * sa[c]);
;                     S23[c] = S23[c] * w4.hi + (k4.hi * vv[c] - a4.hi * sa[c]);
;                     py[(t * 32 + 4 * c) * 4] = yp[c] + 0.25f * (vv[c] * sc.x - sa[c] * sc.y);
;                 }
;                 kk4 = nkk; wr4 = nwr; w4 = nw; k4 = nk; a4 = na; vv[0] = nv0; vv[1] = nv1; sc = nsc;
	v_pk_mul_f32 v[64:65], v[2:3], v[40:41] op_sel_hi:[1,0]
	v_pk_mul_f32 v[66:67], v[2:3], v[44:45] op_sel_hi:[1,0]
	v_pk_fma_f32 v[64:65], v[4:5], v[40:41], v[64:65] op_sel:[0,1,0] op_sel_hi:[1,1,1]
	v_pk_fma_f32 v[66:67], v[4:5], v[44:45], v[66:67] op_sel:[0,1,0] op_sel_hi:[1,1,1]
	v_pk_fma_f32 v[64:65], v[6:7], v[42:43], v[64:65] op_sel_hi:[1,0,1]
	v_pk_fma_f32 v[66:67], v[6:7], v[46:47], v[66:67] op_sel_hi:[1,0,1]
	v_pk_fma_f32 v[64:65], v[8:9], v[42:43], v[64:65] op_sel:[0,1,0] op_sel_hi:[1,1,1]
	v_pk_fma_f32 v[66:67], v[8:9], v[46:47], v[66:67] op_sel:[0,1,0] op_sel_hi:[1,1,1]
	ds_read_b128 v[16:19], v10 offset:6656
	v_add_f32_dpp v78, v65, v64 quad_perm:[1,0,3,2] row_mask:0xf bank_mask:0xf bound_ctrl:1
	ds_read_b128 v[20:23], v10 offset:14848
	ds_read_b128 v[24:27], v10 offset:23040
	v_add_f32_dpp v79, v78, v78 quad_perm:[3,2,1,0] row_mask:0xf bank_mask:0xf bound_ctrl:1
	ds_read_b128 v[28:31], v10 offset:31232
	ds_read_b128 v[32:35], v10 offset:39424
	v_add_f32_dpp v80, v79, v79 row_half_mirror row_mask:0xf bank_mask:0xf bound_ctrl:1
	ds_read_b32 v36, v11 offset:44288
	ds_read_b32 v37, v12 offset:44288
	v_add_f32_dpp v76, v80, v80 row_mirror row_mask:0xf bank_mask:0xf bound_ctrl:1
	ds_read_b64 v[38:39], v13 offset:45264
	v_pk_mul_f32 v[68:69], v[60:61], v[52:53] op_sel_hi:[1,0]
	v_mov_b32_dpp v77, v76 quad_perm:[1,0,3,2] row_mask:0xf bank_mask:0xf bound_ctrl:1
	v_pk_mul_f32 v[70:71], v[60:61], v[52:53] op_sel:[0,1] op_sel_hi:[1,1]
	v_pk_mul_f32 v[72:73], v[60:61], v[54:55] op_sel_hi:[1,0]
	v_pk_mul_f32 v[74:75], v[60:61], v[54:55] op_sel:[0,1] op_sel_hi:[1,1]
	v_pk_fma_f32 v[68:69], v[2:3], v[48:49], v[68:69] op_sel_hi:[1,0,1]
	v_pk_fma_f32 v[70:71], v[4:5], v[48:49], v[70:71] op_sel:[0,1,0] op_sel_hi:[1,1,1]
	v_pk_fma_f32 v[72:73], v[6:7], v[50:51], v[72:73] op_sel_hi:[1,0,1]
	v_pk_fma_f32 v[74:75], v[8:9], v[50:51], v[74:75] op_sel:[0,1,0] op_sel_hi:[1,1,1]
	v_pk_fma_f32 v[2:3], v[56:57], v[76:77], v[68:69] op_sel_hi:[0,1,1] neg_lo:[1,0,0] neg_hi:[1,0,0]
	v_pk_fma_f32 v[4:5], v[56:57], v[76:77], v[70:71] op_sel:[1,0,0] op_sel_hi:[1,1,1] neg_lo:[1,0,0] neg_hi:[1,0,0]
	v_mul_f32_e32 v83, v60, v62
	v_add_f32_dpp v81, v67, v66 quad_perm:[1,0,3,2] row_mask:0xf bank_mask:0xf bound_ctrl:1
	v_pk_fma_f32 v[6:7], v[58:59], v[76:77], v[72:73] op_sel_hi:[0,1,1] neg_lo:[1,0,0] neg_hi:[1,0,0]
	v_pk_fma_f32 v[8:9], v[58:59], v[76:77], v[74:75] op_sel:[1,0,0] op_sel_hi:[1,1,1] neg_lo:[1,0,0] neg_hi:[1,0,0]
	v_add_f32_dpp v82, v81, v81 quad_perm:[3,2,1,0] row_mask:0xf bank_mask:0xf bound_ctrl:1
	v_fma_f32 v83, -v76, v63, v83
	v_fmac_f32_e32 v82, 0x3e800000, v83
	ds_write_b32 v14, v82 offset:12800
	s_waitcnt lgkmcnt(1)
	v_pk_mul_f32 v[64:65], v[2:3], v[16:17] op_sel_hi:[1,0]
	v_pk_mul_f32 v[66:67], v[2:3], v[20:21] op_sel_hi:[1,0]
	v_pk_fma_f32 v[64:65], v[4:5], v[16:17], v[64:65] op_sel:[0,1,0] op_sel_hi:[1,1,1]
	v_pk_fma_f32 v[66:67], v[4:5], v[20:21], v[66:67] op_sel:[0,1,0] op_sel_hi:[1,1,1]
	v_pk_fma_f32 v[64:65], v[6:7], v[18:19], v[64:65] op_sel_hi:[1,0,1]
	v_pk_fma_f32 v[66:67], v[6:7], v[22:23], v[66:67] op_sel_hi:[1,0,1]
	v_pk_fma_f32 v[64:65], v[8:9], v[18:19], v[64:65] op_sel:[0,1,0] op_sel_hi:[1,1,1]
	v_pk_fma_f32 v[66:67], v[8:9], v[22:23], v[66:67] op_sel:[0,1,0] op_sel_hi:[1,1,1]
	ds_read_b128 v[40:43], v10 offset:6912
	v_add_f32_dpp v78, v65, v64 quad_perm:[1,0,3,2] row_mask:0xf bank_mask:0xf bound_ctrl:1
	ds_read_b128 v[44:47], v10 offset:15104
	ds_read_b128 v[48:51], v10 offset:23296
	v_add_f32_dpp v79, v78, v78 quad_perm:[3,2,1,0] row_mask:0xf bank_mask:0xf bound_ctrl:1
	ds_read_b128 v[52:55], v10 offset:31488
	ds_read_b128 v[56:59], v10 offset:39680
	v_add_f32_dpp v80, v79, v79 row_half_mirror row_mask:0xf bank_mask:0xf bound_ctrl:1
	ds_read_b32 v60, v11 offset:44416
	ds_read_b32 v61, v12 offset:44416
	v_add_f32_dpp v76, v80, v80 row_mirror row_mask:0xf bank_mask:0xf bound_ctrl:1
	ds_read_b64 v[62:63], v13 offset:45272
	v_pk_mul_f32 v[68:69], v[36:37], v[28:29] op_sel_hi:[1,0]
	v_mov_b32_dpp v77, v76 quad_perm:[1,0,3,2] row_mask:0xf bank_mask:0xf bound_ctrl:1
	v_pk_mul_f32 v[70:71], v[36:37], v[28:29] op_sel:[0,1] op_sel_hi:[1,1]
	v_pk_mul_f32 v[72:73], v[36:37], v[30:31] op_sel_hi:[1,0]
	v_pk_mul_f32 v[74:75], v[36:37], v[30:31] op_sel:[0,1] op_sel_hi:[1,1]
	v_pk_fma_f32 v[68:69], v[2:3], v[24:25], v[68:69] op_sel_hi:[1,0,1]
	v_pk_fma_f32 v[70:71], v[4:5], v[24:25], v[70:71] op_sel:[0,1,0] op_sel_hi:[1,1,1]
	v_pk_fma_f32 v[72:73], v[6:7], v[26:27], v[72:73] op_sel_hi:[1,0,1]
	v_pk_fma_f32 v[74:75], v[8:9], v[26:27], v[74:75] op_sel:[0,1,0] op_sel_hi:[1,1,1]
	v_pk_fma_f32 v[2:3], v[32:33], v[76:77], v[68:69] op_sel_hi:[0,1,1] neg_lo:[1,0,0] neg_hi:[1,0,0]
	v_pk_fma_f32 v[4:5], v[32:33], v[76:77], v[70:71] op_sel:[1,0,0] op_sel_hi:[1,1,1] neg_lo:[1,0,0] neg_hi:[1,0,0]
	v_mul_f32_e32 v83, v36, v38
	v_add_f32_dpp v81, v67, v66 quad_perm:[1,0,3,2] row_mask:0xf bank_mask:0xf bound_ctrl:1
	v_pk_fma_f32 v[6:7], v[34:35], v[76:77], v[72:73] op_sel_hi:[0,1,1] neg_lo:[1,0,0] neg_hi:[1,0,0]
	v_pk_fma_f32 v[8:9], v[34:35], v[76:77], v[74:75] op_sel:[1,0,0] op_sel_hi:[1,1,1] neg_lo:[1,0,0] neg_hi:[1,0,0]
	v_add_f32_dpp v82, v81, v81 quad_perm:[3,2,1,0] row_mask:0xf bank_mask:0xf bound_ctrl:1
	v_fma_f32 v83, -v76, v39, v83
	v_fmac_f32_e32 v82, 0x3e800000, v83
	ds_write_b32 v14, v82 offset:13312
	s_waitcnt lgkmcnt(1)
; #define LAS __attribute__((address_space(3)))
; template <int CTRL> __device__ __forceinline__ float dppf(float x) { return __builtin_bit_cast(float, __builtin_amdgcn_mov_dpp(__builtin_bit_cast(int, x), CTRL, 0xf, 0xf, true)); }
; __device__ __forceinline__ float sum16(float x) { x = sum8(x); x += dppf<0x140>(x); return x; }
; __device__ __forceinline__ void rwkv_item(LAS unsigned char* lds, int l, const bf16_t* PROJ, const bf16_t* LO, bf16_t* YR, float* BON, int b, int h, int qv) {
;     ...
;             for (int t = 0; t < CH; ++t) {
;                 const int tn = (t + 1) & (CH - 1);
;                 const LAS float* pn = pk + tn * 64;
;                 const f32x4 nkk = *(const LAS f32x4*)(pn), nwr = *(const LAS f32x4*)(pn + 2048), nw = *(const LAS f32x4*)(pn + 4096), nk = *(const LAS f32x4*)(pn + 6144), na = *(const LAS f32x4*)(pn + 8192);
;                 const float nv0 = pv[tn * 32], nv1 = pv[tn * 32 + 4]; const f32x2 nsc = *(const LAS f32x2*)(ps + 2 * tn);
;                 float sa[2], yp[2];
; #pragma unroll
;                 for (int c = 0; c < 2; ++c) { const f32x2 pa = S23[c] * kk4.hi + S01[c] * kk4.lo, pb = S23[c] * wr4.hi + S01[c] * wr4.lo; sa[c] = pa.x + pa.y; yp[c] = pb.x + pb.y; }
; #pragma unroll
;                 for (int c = 0; c < 2; ++c) { sa[c] = sum16(sa[c]); yp[c] += dppf<0xB1>(yp[c]); yp[c] += dppf<0x4E>(yp[c]); }
; #pragma unroll
;                 for (int c = 0; c < 2; ++c) {
;                     S01[c] = S01[c] * w4.lo + (k4.lo * vv[c] - a4.lo * sa[c]);
;                     S23[c] = S23[c] * w4.hi + (k4.hi * vv[c] - a4.hi * sa[c]);
;                     py[(t * 32 + 4 * c) * 4] = yp[c] + 0.25f * (vv[c] * sc.x - sa[c] * sc.y);
;                 }
;                 kk4 = nkk; wr4 = nwr; w4 = nw; k4 = nk; a4 = na; vv[0] = nv0; vv[1] = nv1; sc = nsc;
	v_pk_mul_f32 v[64:65], v[2:3], v[40:41] op_sel_hi:[1,0]
	v_pk_mul_f32 v[66:67], v[2:3], v[44:45] op_sel_hi:[1,0]
	v_pk_fma_f32 v[64:65], v[4:5], v[40:41], v[64:65] op_sel:[0,1,0] op_sel_hi:[1,1,1]
	v_pk_fma_f32 v[66:67], v[4:5], v[44:45], v[66:67] op_sel:[0,1,0] op_sel_hi:[1,1,1]
	v_pk_fma_f32 v[64:65], v[6:7], v[42:43], v[64:65] op_sel_hi:[1,0,1]
	v_pk_fma_f32 v[66:67], v[6:7], v[46:47], v[66:67] op_sel_hi:[1,0,1]
	v_pk_fma_f32 v[64:65], v[8:9], v[42:43], v[64:65] op_sel:[0,1,0] op_sel_hi:[1,1,1]
	v_pk_fma_f32 v[66:67], v[8:9], v[46:47], v[66:67] op_sel:[0,1,0] op_sel_hi:[1,1,1]
	ds_read_b128 v[16:19], v10 offset:7168
	v_add_f32_dpp v78, v65, v64 quad_perm:[1,0,3,2] row_mask:0xf bank_mask:0xf bound_ctrl:1
	ds_read_b128 v[20:23], v10 offset:15360
	ds_read_b128 v[24:27], v10 offset:23552
	v_add_f32_dpp v79, v78, v78 quad_perm:[3,2,1,0] row_mask:0xf bank_mask:0xf bound_ctrl:1
	ds_read_b128 v[28:31], v10 offset:31744
	ds_read_b128 v[32:35], v10 offset:39936
	v_add_f32_dpp v80, v79, v79 row_half_mirror row_mask:0xf bank_mask:0xf bound_ctrl:1
	ds_read_b32 v36, v11 offset:44544
	ds_read_b32 v37, v12 offset:44544
	v_add_f32_dpp v76, v80, v80 row_mirror row_mask:0xf bank_mask:0xf bound_ctrl:1
	ds_read_b64 v[38:39], v13 offset:45280
	v_pk_mul_f32 v[68:69], v[60:61], v[52:53] op_sel_hi:[1,0]
	v_mov_b32_dpp v77, v76 quad_perm:[1,0,3,2] row_mask:0xf bank_mask:0xf bound_ctrl:1
	v_pk_mul_f32 v[70:71], v[60:61], v[52:53] op_sel:[0,1] op_sel_hi:[1,1]
	v_pk_mul_f32 v[72:73], v[60:61], v[54:55] op_sel_hi:[1,0]
	v_pk_mul_f32 v[74:75], v[60:61], v[54:55] op_sel:[0,1] op_sel_hi:[1,1]
	v_pk_fma_f32 v[68:69], v[2:3], v[48:49], v[68:69] op_sel_hi:[1,0,1]
	v_pk_fma_f32 v[70:71], v[4:5], v[48:49], v[70:71] op_sel:[0,1,0] op_sel_hi:[1,1,1]
	v_pk_fma_f32 v[72:73], v[6:7], v[50:51], v[72:73] op_sel_hi:[1,0,1]
	v_pk_fma_f32 v[74:75], v[8:9], v[50:51], v[74:75] op_sel:[0,1,0] op_sel_hi:[1,1,1]
	v_pk_fma_f32 v[2:3], v[56:57], v[76:77], v[68:69] op_sel_hi:[0,1,1] neg_lo:[1,0,0] neg_hi:[1,0,0]
	v_pk_fma_f32 v[4:5], v[56:57], v[76:77], v[70:71] op_sel:[1,0,0] op_sel_hi:[1,1,1] neg_lo:[1,0,0] neg_hi:[1,0,0]
	v_mul_f32_e32 v83, v60, v62
	v_add_f32_dpp v81, v67, v66 quad_perm:[1,0,3,2] row_mask:0xf bank_mask:0xf bound_ctrl:1
	v_pk_fma_f32 v[6:7], v[58:59], v[76:77], v[72:73] op_sel_hi:[0,1,1] neg_lo:[1,0,0] neg_hi:[1,0,0]
	v_pk_fma_f32 v[8:9], v[58:59], v[76:77], v[74:75] op_sel:[1,0,0] op_sel_hi:[1,1,1] neg_lo:[1,0,0] neg_hi:[1,0,0]
	v_add_f32_dpp v82, v81, v81 quad_perm:[3,2,1,0] row_mask:0xf bank_mask:0xf bound_ctrl:1
	v_fma_f32 v83, -v76, v63, v83
	v_fmac_f32_e32 v82, 0x3e800000, v83
	ds_write_b32 v14, v82 offset:13824
	s_waitcnt lgkmcnt(1)
	v_pk_mul_f32 v[64:65], v[2:3], v[16:17] op_sel_hi:[1,0]
	v_pk_mul_f32 v[66:67], v[2:3], v[20:21] op_sel_hi:[1,0]
	v_pk_fma_f32 v[64:65], v[4:5], v[16:17], v[64:65] op_sel:[0,1,0] op_sel_hi:[1,1,1]
	v_pk_fma_f32 v[66:67], v[4:5], v[20:21], v[66:67] op_sel:[0,1,0] op_sel_hi:[1,1,1]
	v_pk_fma_f32 v[64:65], v[6:7], v[18:19], v[64:65] op_sel_hi:[1,0,1]
	v_pk_fma_f32 v[66:67], v[6:7], v[22:23], v[66:67] op_sel_hi:[1,0,1]
	v_pk_fma_f32 v[64:65], v[8:9], v[18:19], v[64:65] op_sel:[0,1,0] op_sel_hi:[1,1,1]
	v_pk_fma_f32 v[66:67], v[8:9], v[22:23], v[66:67] op_sel:[0,1,0] op_sel_hi:[1,1,1]
	ds_read_b128 v[40:43], v10 offset:7424
	v_add_f32_dpp v78, v65, v64 quad_perm:[1,0,3,2] row_mask:0xf bank_mask:0xf bound_ctrl:1
	ds_read_b128 v[44:47], v10 offset:15616
	ds_read_b128 v[48:51], v10 offset:23808
	v_add_f32_dpp v79, v78, v78 quad_perm:[3,2,1,0] row_mask:0xf bank_mask:0xf bound_ctrl:1
	ds_read_b128 v[52:55], v10 offset:32000
	ds_read_b128 v[56:59], v10 offset:40192
	v_add_f32_dpp v80, v79, v79 row_half_mirror row_mask:0xf bank_mask:0xf bound_ctrl:1
	ds_read_b32 v60, v11 offset:44672
	ds_read_b32 v61, v12 offset:44672
	v_add_f32_dpp v76, v80, v80 row_mirror row_mask:0xf bank_mask:0xf bound_ctrl:1
	ds_read_b64 v[62:63], v13 offset:45288
	v_pk_mul_f32 v[68:69], v[36:37], v[28:29] op_sel_hi:[1,0]
	v_mov_b32_dpp v77, v76 quad_perm:[1,0,3,2] row_mask:0xf bank_mask:0xf bound_ctrl:1
	v_pk_mul_f32 v[70:71], v[36:37], v[28:29] op_sel:[0,1] op_sel_hi:[1,1]
	v_pk_mul_f32 v[72:73], v[36:37], v[30:31] op_sel_hi:[1,0]
	v_pk_mul_f32 v[74:75], v[36:37], v[30:31] op_sel:[0,1] op_sel_hi:[1,1]
	v_pk_fma_f32 v[68:69], v[2:3], v[24:25], v[68:69] op_sel_hi:[1,0,1]
	v_pk_fma_f32 v[70:71], v[4:5], v[24:25], v[70:71] op_sel:[0,1,0] op_sel_hi:[1,1,1]
	v_pk_fma_f32 v[72:73], v[6:7], v[26:27], v[72:73] op_sel_hi:[1,0,1]
	v_pk_fma_f32 v[74:75], v[8:9], v[26:27], v[74:75] op_sel:[0,1,0] op_sel_hi:[1,1,1]
	v_pk_fma_f32 v[2:3], v[32:33], v[76:77], v[68:69] op_sel_hi:[0,1,1] neg_lo:[1,0,0] neg_hi:[1,0,0]
	v_pk_fma_f32 v[4:5], v[32:33], v[76:77], v[70:71] op_sel:[1,0,0] op_sel_hi:[1,1,1] neg_lo:[1,0,0] neg_hi:[1,0,0]
	v_mul_f32_e32 v83, v36, v38
	v_add_f32_dpp v81, v67, v66 quad_perm:[1,0,3,2] row_mask:0xf bank_mask:0xf bound_ctrl:1
	v_pk_fma_f32 v[6:7], v[34:35], v[76:77], v[72:73] op_sel_hi:[0,1,1] neg_lo:[1,0,0] neg_hi:[1,0,0]
	v_pk_fma_f32 v[8:9], v[34:35], v[76:77], v[74:75] op_sel:[1,0,0] op_sel_hi:[1,1,1] neg_lo:[1,0,0] neg_hi:[1,0,0]
	v_add_f32_dpp v82, v81, v81 quad_perm:[3,2,1,0] row_mask:0xf bank_mask:0xf bound_ctrl:1
	v_fma_f32 v83, -v76, v39, v83
	v_fmac_f32_e32 v82, 0x3e800000, v83
	ds_write_b32 v14, v82 offset:14336
	s_waitcnt lgkmcnt(1)
; #define LAS __attribute__((address_space(3)))
; template <int CTRL> __device__ __forceinline__ float dppf(float x) { return __builtin_bit_cast(float, __builtin_amdgcn_mov_dpp(__builtin_bit_cast(int, x), CTRL, 0xf, 0xf, true)); }
; __device__ __forceinline__ float sum16(float x) { x = sum8(x); x += dppf<0x140>(x); return x; }
; __device__ __forceinline__ void rwkv_item(LAS unsigned char* lds, int l, const bf16_t* PROJ, const bf16_t* LO, bf16_t* YR, float* BON, int b, int h, int qv) {
;     ...
;             for (int t = 0; t < CH; ++t) {
;                 const int tn = (t + 1) & (CH - 1);
;                 const LAS float* pn = pk + tn * 64;
;                 const f32x4 nkk = *(const LAS f32x4*)(pn), nwr = *(const LAS f32x4*)(pn + 2048), nw = *(const LAS f32x4*)(pn + 4096), nk = *(const LAS f32x4*)(pn + 6144), na = *(const LAS f32x4*)(pn + 8192);
;                 const float nv0 = pv[tn * 32], nv1 = pv[tn * 32 + 4]; const f32x2 nsc = *(const LAS f32x2*)(ps + 2 * tn);
;                 float sa[2], yp[2];
; #pragma unroll
;                 for (int c = 0; c < 2; ++c) { const f32x2 pa = S23[c] * kk4.hi + S01[c] * kk4.lo, pb = S23[c] * wr4.hi + S01[c] * wr4.lo; sa[c] = pa.x + pa.y; yp[c] = pb.x + pb.y; }
; #pragma unroll
;                 for (int c = 0; c < 2; ++c) { sa[c] = sum16(sa[c]); yp[c] += dppf<0xB1>(yp[c]); yp[c] += dppf<0x4E>(yp[c]); }
; #pragma unroll
;                 for (int c = 0; c < 2; ++c) {
;                     S01[c] = S01[c] * w4.lo + (k4.lo * vv[c] - a4.lo * sa[c]);
;                     S23[c] = S23[c] * w4.hi + (k4.hi * vv[c] - a4.hi * sa[c]);
;                     py[(t * 32 + 4 * c) * 4] = yp[c] + 0.25f * (vv[c] * sc.x - sa[c] * sc.y);
;                 }
;                 kk4 = nkk; wr4 = nwr; w4 = nw; k4 = nk; a4 = na; vv[0] = nv0; vv[1] = nv1; sc = nsc;
	v_pk_mul_f32 v[64:65], v[2:3], v[40:41] op_sel_hi:[1,0]
	v_pk_mul_f32 v[66:67], v[2:3], v[44:45] op_sel_hi:[1,0]
	v_pk_fma_f32 v[64:65], v[4:5], v[40:41], v[64:65] op_sel:[0,1,0] op_sel_hi:[1,1,1]
	v_pk_fma_f32 v[66:67], v[4:5], v[44:45], v[66:67] op_sel:[0,1,0] op_sel_hi:[1,1,1]
	v_pk_fma_f32 v[64:65], v[6:7], v[42:43], v[64:65] op_sel_hi:[1,0,1]
	v_pk_fma_f32 v[66:67], v[6:7], v[46:47], v[66:67] op_sel_hi:[1,0,1]
	v_pk_fma_f32 v[64:65], v[8:9], v[42:43], v[64:65] op_sel:[0,1,0] op_sel_hi:[1,1,1]
	v_pk_fma_f32 v[66:67], v[8:9], v[46:47], v[66:67] op_sel:[0,1,0] op_sel_hi:[1,1,1]
	ds_read_b128 v[16:19], v10 offset:7680
	v_add_f32_dpp v78, v65, v64 quad_perm:[1,0,3,2] row_mask:0xf bank_mask:0xf bound_ctrl:1
	ds_read_b128 v[20:23], v10 offset:15872
	ds_read_b128 v[24:27], v10 offset:24064
	v_add_f32_dpp v79, v78, v78 quad_perm:[3,2,1,0] row_mask:0xf bank_mask:0xf bound_ctrl:1
	ds_read_b128 v[28:31], v10 offset:32256
	ds_read_b128 v[32:35], v10 offset:40448
	v_add_f32_dpp v80, v79, v79 row_half_mirror row_mask:0xf bank_mask:0xf bound_ctrl:1
	ds_read_b32 v36, v11 offset:44800
	ds_read_b32 v37, v12 offset:44800
	v_add_f32_dpp v76, v80, v80 row_mirror row_mask:0xf bank_mask:0xf bound_ctrl:1
	ds_read_b64 v[38:39], v13 offset:45296
	v_pk_mul_f32 v[68:69], v[60:61], v[52:53] op_sel_hi:[1,0]
	v_mov_b32_dpp v77, v76 quad_perm:[1,0,3,2] row_mask:0xf bank_mask:0xf bound_ctrl:1
	v_pk_mul_f32 v[70:71], v[60:61], v[52:53] op_sel:[0,1] op_sel_hi:[1,1]
	v_pk_mul_f32 v[72:73], v[60:61], v[54:55] op_sel_hi:[1,0]
	v_pk_mul_f32 v[74:75], v[60:61], v[54:55] op_sel:[0,1] op_sel_hi:[1,1]
	v_pk_fma_f32 v[68:69], v[2:3], v[48:49], v[68:69] op_sel_hi:[1,0,1]
	v_pk_fma_f32 v[70:71], v[4:5], v[48:49], v[70:71] op_sel:[0,1,0] op_sel_hi:[1,1,1]
	v_pk_fma_f32 v[72:73], v[6:7], v[50:51], v[72:73] op_sel_hi:[1,0,1]
	v_pk_fma_f32 v[74:75], v[8:9], v[50:51], v[74:75] op_sel:[0,1,0] op_sel_hi:[1,1,1]
	v_pk_fma_f32 v[2:3], v[56:57], v[76:77], v[68:69] op_sel_hi:[0,1,1] neg_lo:[1,0,0] neg_hi:[1,0,0]
	v_pk_fma_f32 v[4:5], v[56:57], v[76:77], v[70:71] op_sel:[1,0,0] op_sel_hi:[1,1,1] neg_lo:[1,0,0] neg_hi:[1,0,0]
	v_mul_f32_e32 v83, v60, v62
	v_add_f32_dpp v81, v67, v66 quad_perm:[1,0,3,2] row_mask:0xf bank_mask:0xf bound_ctrl:1
	v_pk_fma_f32 v[6:7], v[58:59], v[76:77], v[72:73] op_sel_hi:[0,1,1] neg_lo:[1,0,0] neg_hi:[1,0,0]
	v_pk_fma_f32 v[8:9], v[58:59], v[76:77], v[74:75] op_sel:[1,0,0] op_sel_hi:[1,1,1] neg_lo:[1,0,0] neg_hi:[1,0,0]
	v_add_f32_dpp v82, v81, v81 quad_perm:[3,2,1,0] row_mask:0xf bank_mask:0xf bound_ctrl:1
	v_fma_f32 v83, -v76, v63, v83
	v_fmac_f32_e32 v82, 0x3e800000, v83
	ds_write_b32 v14, v82 offset:14848
	s_waitcnt lgkmcnt(1)
; #define LAS __attribute__((address_space(3)))
; template <int CTRL> __device__ __forceinline__ float dppf(float x) { return __builtin_bit_cast(float, __builtin_amdgcn_mov_dpp(__builtin_bit_cast(int, x), CTRL, 0xf, 0xf, true)); }
; __device__ __forceinline__ float sum16(float x) { x = sum8(x); x += dppf<0x140>(x); return x; }
; __device__ __forceinline__ void rwkv_item(LAS unsigned char* lds, int l, const bf16_t* PROJ, const bf16_t* LO, bf16_t* YR, float* BON, int b, int h, int qv) {
;     ...
;             for (int t = 0; t < CH; ++t) {
;                 const int tn = (t + 1) & (CH - 1);
;                 const LAS float* pn = pk + tn * 64;
;                 const f32x4 nkk = *(const LAS f32x4*)(pn), nwr = *(const LAS f32x4*)(pn + 2048), nw = *(const LAS f32x4*)(pn + 4096), nk = *(const LAS f32x4*)(pn + 6144), na = *(const LAS f32x4*)(pn + 8192);
;                 const float nv0 = pv[tn * 32], nv1 = pv[tn * 32 + 4]; const f32x2 nsc = *(const LAS f32x2*)(ps + 2 * tn);
;                 float sa[2], yp[2];
; #pragma unroll
;                 for (int c = 0; c < 2; ++c) { const f32x2 pa = S23[c] * kk4.hi + S01[c] * kk4.lo, pb = S23[c] * wr4.hi + S01[c] * wr4.lo; sa[c] = pa.x + pa.y; yp[c] = pb.x + pb.y; }
; #pragma unroll
;                 for (int c = 0; c < 2; ++c) { sa[c] = sum16(sa[c]); yp[c] += dppf<0xB1>(yp[c]); yp[c] += dppf<0x4E>(yp[c]); }
; #pragma unroll
;                 for (int c = 0; c < 2; ++c) {
;                     S01[c] = S01[c] * w4.lo + (k4.lo * vv[c] - a4.lo * sa[c]);
;                     S23[c] = S23[c] * w4.hi + (k4.hi * vv[c] - a4.hi * sa[c]);
;                     py[(t * 32 + 4 * c) * 4] = yp[c] + 0.25f * (vv[c] * sc.x - sa[c] * sc.y);
;                 }
;                 kk4 = nkk; wr4 = nwr; w4 = nw; k4 = nk; a4 = na; vv[0] = nv0; vv[1] = nv1; sc = nsc;
;             }
;             __syncthreads();
;         }
	v_pk_mul_f32 v[64:65], v[2:3], v[16:17] op_sel_hi:[1,0]
	v_pk_mul_f32 v[66:67], v[2:3], v[20:21] op_sel_hi:[1,0]
	v_pk_fma_f32 v[64:65], v[4:5], v[16:17], v[64:65] op_sel:[0,1,0] op_sel_hi:[1,1,1]
	v_pk_fma_f32 v[66:67], v[4:5], v[20:21], v[66:67] op_sel:[0,1,0] op_sel_hi:[1,1,1]
	v_pk_fma_f32 v[64:65], v[6:7], v[18:19], v[64:65] op_sel_hi:[1,0,1]
	v_pk_fma_f32 v[66:67], v[6:7], v[22:23], v[66:67] op_sel_hi:[1,0,1]
	v_pk_fma_f32 v[64:65], v[8:9], v[18:19], v[64:65] op_sel:[0,1,0] op_sel_hi:[1,1,1]
	v_pk_fma_f32 v[66:67], v[8:9], v[22:23], v[66:67] op_sel:[0,1,0] op_sel_hi:[1,1,1]
	ds_read_b128 v[40:43], v10 offset:7936
	v_add_f32_dpp v78, v65, v64 quad_perm:[1,0,3,2] row_mask:0xf bank_mask:0xf bound_ctrl:1
	ds_read_b128 v[44:47], v10 offset:16128
	ds_read_b128 v[48:51], v10 offset:24320
	v_add_f32_dpp v79, v78, v78 quad_perm:[3,2,1,0] row_mask:0xf bank_mask:0xf bound_ctrl:1
	ds_read_b128 v[52:55], v10 offset:32512
	ds_read_b128 v[56:59], v10 offset:40704
	v_add_f32_dpp v80, v79, v79 row_half_mirror row_mask:0xf bank_mask:0xf bound_ctrl:1
	ds_read_b32 v60, v11 offset:44928
	ds_read_b32 v61, v12 offset:44928
	v_add_f32_dpp v76, v80, v80 row_mirror row_mask:0xf bank_mask:0xf bound_ctrl:1
	ds_read_b64 v[62:63], v13 offset:45304
	v_pk_mul_f32 v[68:69], v[36:37], v[28:29] op_sel_hi:[1,0]
	v_mov_b32_dpp v77, v76 quad_perm:[1,0,3,2] row_mask:0xf bank_mask:0xf bound_ctrl:1
	v_pk_mul_f32 v[70:71], v[36:37], v[28:29] op_sel:[0,1] op_sel_hi:[1,1]
	v_pk_mul_f32 v[72:73], v[36:37], v[30:31] op_sel_hi:[1,0]
	v_pk_mul_f32 v[74:75], v[36:37], v[30:31] op_sel:[0,1] op_sel_hi:[1,1]
	v_pk_fma_f32 v[68:69], v[2:3], v[24:25], v[68:69] op_sel_hi:[1,0,1]
	v_pk_fma_f32 v[70:71], v[4:5], v[24:25], v[70:71] op_sel:[0,1,0] op_sel_hi:[1,1,1]
	v_pk_fma_f32 v[72:73], v[6:7], v[26:27], v[72:73] op_sel_hi:[1,0,1]
	v_pk_fma_f32 v[74:75], v[8:9], v[26:27], v[74:75] op_sel:[0,1,0] op_sel_hi:[1,1,1]
	v_pk_fma_f32 v[2:3], v[32:33], v[76:77], v[68:69] op_sel_hi:[0,1,1] neg_lo:[1,0,0] neg_hi:[1,0,0]
	v_pk_fma_f32 v[4:5], v[32:33], v[76:77], v[70:71] op_sel:[1,0,0] op_sel_hi:[1,1,1] neg_lo:[1,0,0] neg_hi:[1,0,0]
	v_mul_f32_e32 v83, v36, v38
	v_add_f32_dpp v81, v67, v66 quad_perm:[1,0,3,2] row_mask:0xf bank_mask:0xf bound_ctrl:1
	v_pk_fma_f32 v[6:7], v[34:35], v[76:77], v[72:73] op_sel_hi:[0,1,1] neg_lo:[1,0,0] neg_hi:[1,0,0]
	v_pk_fma_f32 v[8:9], v[34:35], v[76:77], v[74:75] op_sel:[1,0,0] op_sel_hi:[1,1,1] neg_lo:[1,0,0] neg_hi:[1,0,0]
	v_add_f32_dpp v82, v81, v81 quad_perm:[3,2,1,0] row_mask:0xf bank_mask:0xf bound_ctrl:1
	v_fma_f32 v83, -v76, v39, v83
	v_fmac_f32_e32 v82, 0x3e800000, v83
	ds_write_b32 v14, v82 offset:15360
	s_waitcnt lgkmcnt(1)
	v_pk_mul_f32 v[64:65], v[2:3], v[40:41] op_sel_hi:[1,0]
	v_pk_mul_f32 v[66:67], v[2:3], v[44:45] op_sel_hi:[1,0]
	v_pk_fma_f32 v[64:65], v[4:5], v[40:41], v[64:65] op_sel:[0,1,0] op_sel_hi:[1,1,1]
	v_pk_fma_f32 v[66:67], v[4:5], v[44:45], v[66:67] op_sel:[0,1,0] op_sel_hi:[1,1,1]
	v_pk_fma_f32 v[64:65], v[6:7], v[42:43], v[64:65] op_sel_hi:[1,0,1]
	v_pk_fma_f32 v[66:67], v[6:7], v[46:47], v[66:67] op_sel_hi:[1,0,1]
	v_pk_fma_f32 v[64:65], v[8:9], v[42:43], v[64:65] op_sel:[0,1,0] op_sel_hi:[1,1,1]
	v_pk_fma_f32 v[66:67], v[8:9], v[46:47], v[66:67] op_sel:[0,1,0] op_sel_hi:[1,1,1]
	s_nop 0
	v_add_f32_dpp v78, v65, v64 quad_perm:[1,0,3,2] row_mask:0xf bank_mask:0xf bound_ctrl:1
	s_nop 0
	s_nop 0
	v_add_f32_dpp v79, v78, v78 quad_perm:[3,2,1,0] row_mask:0xf bank_mask:0xf bound_ctrl:1
	s_nop 0
	s_nop 0
	v_add_f32_dpp v80, v79, v79 row_half_mirror row_mask:0xf bank_mask:0xf bound_ctrl:1
	s_nop 0
	s_nop 0
	v_add_f32_dpp v76, v80, v80 row_mirror row_mask:0xf bank_mask:0xf bound_ctrl:1
	s_nop 0
	v_pk_mul_f32 v[68:69], v[60:61], v[52:53] op_sel_hi:[1,0]
	v_mov_b32_dpp v77, v76 quad_perm:[1,0,3,2] row_mask:0xf bank_mask:0xf bound_ctrl:1
	v_pk_mul_f32 v[70:71], v[60:61], v[52:53] op_sel:[0,1] op_sel_hi:[1,1]
	v_pk_mul_f32 v[72:73], v[60:61], v[54:55] op_sel_hi:[1,0]
	v_pk_mul_f32 v[74:75], v[60:61], v[54:55] op_sel:[0,1] op_sel_hi:[1,1]
	v_pk_fma_f32 v[68:69], v[2:3], v[48:49], v[68:69] op_sel_hi:[1,0,1]
	v_pk_fma_f32 v[70:71], v[4:5], v[48:49], v[70:71] op_sel:[0,1,0] op_sel_hi:[1,1,1]
	v_pk_fma_f32 v[72:73], v[6:7], v[50:51], v[72:73] op_sel_hi:[1,0,1]
	v_pk_fma_f32 v[74:75], v[8:9], v[50:51], v[74:75] op_sel:[0,1,0] op_sel_hi:[1,1,1]
	v_pk_fma_f32 v[2:3], v[56:57], v[76:77], v[68:69] op_sel_hi:[0,1,1] neg_lo:[1,0,0] neg_hi:[1,0,0]
	v_pk_fma_f32 v[4:5], v[56:57], v[76:77], v[70:71] op_sel:[1,0,0] op_sel_hi:[1,1,1] neg_lo:[1,0,0] neg_hi:[1,0,0]
	v_mul_f32_e32 v83, v60, v62
	v_add_f32_dpp v81, v67, v66 quad_perm:[1,0,3,2] row_mask:0xf bank_mask:0xf bound_ctrl:1
	v_pk_fma_f32 v[6:7], v[58:59], v[76:77], v[72:73] op_sel_hi:[0,1,1] neg_lo:[1,0,0] neg_hi:[1,0,0]
	v_pk_fma_f32 v[8:9], v[58:59], v[76:77], v[74:75] op_sel:[1,0,0] op_sel_hi:[1,1,1] neg_lo:[1,0,0] neg_hi:[1,0,0]
	v_add_f32_dpp v82, v81, v81 quad_perm:[3,2,1,0] row_mask:0xf bank_mask:0xf bound_ctrl:1
	v_fma_f32 v83, -v76, v63, v83
	v_fmac_f32_e32 v82, 0x3e800000, v83
	ds_write_b32 v14, v82 offset:15872
	s_add_i32 s30, s30, 1
	s_cmpk_eq_i32 s30, 0x80
	s_waitcnt lgkmcnt(0)
	s_barrier
	s_cbranch_scc0 .Lscan_chunk
	s_setprio 0
	s_mov_b64 s[30:31], 0
